# o55: o54 + post-barrier SALU runs (DMA pointer / m0 setup) at the 3 mid-trip segment boundaries hoisted into the previous MFMA block, 8 GEMM loops
# baseline (speedup 1.0000x reference)
;     __device__ float mid(int row) const { return rg(row) / ra(row); }
; #define PG8_WAIT_V(n) asm volatile("s_waitcnt vmcnt(" #n ")" ::: "memory")
; #define PG8_WAIT_L(n) asm volatile("s_waitcnt lgkmcnt(" #n ")" ::: "memory")
; #define PG8_BAR __builtin_amdgcn_s_barrier()
; template <class Epi, class Sched, bool ALIGN_EPI = false, bool SP2 = false>
; __device__ __forceinline__ void gemm_phase(PG8_LAS unsigned char* lds, const Gemm g, const Sched& S, const Epi& E, int wid0) {
;     ...
;         const char* nA = has_next ? (const char*)g.A + (size_t)nxt.pm * tstepA : cA; const char* nB = has_next ? (const char*)g.Bt + (size_t)nxt.pn * tstep : cB;
; #pragma nounroll
;         for (int t = 0; t < nt; t += 2) {
;             const bool last = (t == nt - 2);
;             const char* a1 = cA + (size_t)(t + 1) * kstep;
;             const char* a2 = last ? nA : cA + (size_t)(t + 2) * kstep; const char* b2 = last ? nB : cB + (size_t)(t + 2) * kstep;
;             const char* a3 = a2 + kstep; const char* b3 = b2 + kstep;
;             if (last && has_next) S.a_ready(nxt);
;             if constexpr (Epi::HAS_MID) { if (t == Epi::MID_T) E.mid(acc, cur, wr, fr); }
;             unsigned vA_[2] = {voffA[0], voffA[1]}, vB_[2] = {voffB[0], voffB[1]};
;             asm volatile("" : "+v"(vA_[0]), "+v"(vA_[1]), "+v"(vB_[0]), "+v"(vB_[1]));
;             if constexpr (SP2) {
;             PG8_LDB(B0, 0, 0); PG8_LDB(B1, 0, 1); PG8_SCHED; PG8_LDA(At, 0, 0); PG8_STAGE(PG8_SA(1, 1), a1 + hstepA, vA_);
;             PG8_WAIT_V(8); PG8_WAIT_L(0); PG8_BAR; PG8_MMA(0, 0, At, B0); PG8_MMA(0, 1, At, B1); PG8_BAR; PG8_SCHED;
;             PG8_LDA(At, 0, 1); PG8_STAGE(PG8_SB(0, 0), b2, vB_); PG8_STAGE(PG8_SB(0, 1), b2 + hstep, vB_); PG8_STAGE(PG8_SA(0, 0), a2, vA_);
;             PG8_WAIT_V(8); PG8_WAIT_L(0); PG8_BAR; PG8_MMA(1, 0, At, B0); PG8_MMA(1, 1, At, B1); PG8_BAR; PG8_SCHED;
;             PG8_LDB(B0, 1, 0); PG8_LDB(B1, 1, 1); PG8_SCHED; PG8_LDA(At, 1, 0); PG8_STAGE(PG8_SA(0, 1), a2 + hstepA, vA_);
;             PG8_WAIT_V(8); PG8_WAIT_L(0); PG8_BAR; PG8_MMA(0, 0, At, B0); PG8_MMA(0, 1, At, B1); PG8_BAR; PG8_SCHED;
;             PG8_LDA(At, 1, 1); PG8_STAGE(PG8_SB(1, 0), b3, vB_); PG8_STAGE(PG8_SB(1, 1), b3 + hstep, vB_); PG8_STAGE(PG8_SA(1, 0), a3, vA_);
;             PG8_WAIT_V(8); PG8_WAIT_L(0); PG8_BAR; PG8_MMA(1, 0, At, B0); PG8_MMA(1, 1, At, B1); PG8_BAR; PG8_SCHED;
.LBB13_358:
	v_mov_b32_e32 v8, v174
	v_mov_b32_e32 v220, v200
	v_mov_b32_e32 v221, v176
	v_mov_b32_e32 v222, v178
	ds_read_b128 v[82:85], v201
	ds_read_b128 v[90:93], v201 offset:1024
	ds_read_b128 v[94:97], v201 offset:2048
	ds_read_b128 v[102:105], v201 offset:3072
	ds_read_b128 v[158:161], v202
	ds_read_b128 v[162:165], v202 offset:1024
	ds_read_b128 v[166:169], v202 offset:2048
	ds_read_b128 v[170:173], v202 offset:3072
	s_add_u32 s8, s2, 0x100
	s_addc_u32 s9, s3, 0
	s_cmp_eq_u32 s82, 12
	s_cselect_b32 s58, s78, s8
	s_cselect_b32 s59, s47, s9
	s_cselect_b32 s12, s79, s80
	s_cselect_b32 s13, s49, s81
	s_add_u32 s10, s58, 0x80
	s_addc_u32 s11, s59, 0
	s_add_u32 s2, s2, 0x40080
	s_addc_u32 s3, s3, 0
	s_add_i32 m0, s57, 0xc000
	ds_read_b128 v[180:183], v203
	ds_read_b128 v[184:187], v203 offset:1024
	ds_read_b128 v[188:191], v203 offset:2048
	ds_read_b128 v[192:195], v203 offset:3072
	ds_read_b128 v[204:207], v203 offset:4096
	ds_read_b128 v[208:211], v203 offset:5120
	ds_read_b128 v[212:215], v203 offset:6144
	ds_read_b128 v[216:219], v203 offset:7168
	s_nop 0
	global_load_lds_dwordx4 v8, s[2:3]
	s_add_i32 m0, s57, 0xe000
	s_nop 0
	global_load_lds_dwordx4 v221, s[2:3]
	s_waitcnt vmcnt(8)
	s_waitcnt lgkmcnt(0)
	s_barrier
	s_setprio 1
	s_waitcnt lgkmcnt(0)
	v_mfma_f32_16x16x32_bf16 v[154:157], v[82:85], v[180:183], v[154:157]
	v_mfma_f32_16x16x32_bf16 v[150:153], v[94:97], v[180:183], v[150:153]
	v_mfma_f32_16x16x32_bf16 v[138:141], v[82:85], v[188:191], v[138:141]
	v_mfma_f32_16x16x32_bf16 v[134:137], v[94:97], v[188:191], v[134:137]
	v_mfma_f32_16x16x32_bf16 v[122:125], v[82:85], v[204:207], v[122:125]
	v_mfma_f32_16x16x32_bf16 v[118:121], v[94:97], v[204:207], v[118:121]
	v_mfma_f32_16x16x32_bf16 v[106:109], v[82:85], v[212:215], v[106:109]
	v_mfma_f32_16x16x32_bf16 v[98:101], v[94:97], v[212:215], v[98:101]
	v_mfma_f32_16x16x32_bf16 v[154:157], v[90:93], v[184:187], v[154:157]
	v_mfma_f32_16x16x32_bf16 v[150:153], v[102:105], v[184:187], v[150:153]
	v_mfma_f32_16x16x32_bf16 v[138:141], v[90:93], v[192:195], v[138:141]
	v_mfma_f32_16x16x32_bf16 v[134:137], v[102:105], v[192:195], v[134:137]
	v_mfma_f32_16x16x32_bf16 v[122:125], v[90:93], v[208:211], v[122:125]
	v_mfma_f32_16x16x32_bf16 v[118:121], v[102:105], v[208:211], v[118:121]
	v_mfma_f32_16x16x32_bf16 v[106:109], v[90:93], v[216:219], v[106:109]
	v_mfma_f32_16x16x32_bf16 v[98:101], v[102:105], v[216:219], v[98:101]
	s_setprio 0
	s_setprio 1
	v_mfma_f32_16x16x32_bf16 v[146:149], v[158:161], v[180:183], v[146:149]
	v_mfma_f32_16x16x32_bf16 v[142:145], v[166:169], v[180:183], v[142:145]
	v_mfma_f32_16x16x32_bf16 v[130:133], v[158:161], v[188:191], v[130:133]
	v_mfma_f32_16x16x32_bf16 v[126:129], v[166:169], v[188:191], v[126:129]
	v_mfma_f32_16x16x32_bf16 v[114:117], v[158:161], v[204:207], v[114:117]
	v_mfma_f32_16x16x32_bf16 v[110:113], v[166:169], v[204:207], v[110:113]
	v_mfma_f32_16x16x32_bf16 v[86:89], v[158:161], v[212:215], v[86:89]
	v_mfma_f32_16x16x32_bf16 v[78:81], v[166:169], v[212:215], v[78:81]
	v_mfma_f32_16x16x32_bf16 v[146:149], v[162:165], v[184:187], v[146:149]
	v_mfma_f32_16x16x32_bf16 v[142:145], v[170:173], v[184:187], v[142:145]
	v_mfma_f32_16x16x32_bf16 v[130:133], v[162:165], v[192:195], v[130:133]
	v_mfma_f32_16x16x32_bf16 v[126:129], v[170:173], v[192:195], v[126:129]
	s_add_i32 s83, s74, s55
	s_mov_b64 s[2:3], s[12:13]
	s_mov_b32 m0, s83
	v_mfma_f32_16x16x32_bf16 v[114:117], v[162:165], v[208:211], v[114:117]
	v_mfma_f32_16x16x32_bf16 v[110:113], v[170:173], v[208:211], v[110:113]
	v_mfma_f32_16x16x32_bf16 v[86:89], v[162:165], v[216:219], v[86:89]
	v_mfma_f32_16x16x32_bf16 v[78:81], v[170:173], v[216:219], v[78:81]
	s_setprio 0
	s_barrier
	ds_read_b128 v[180:183], v203 offset:16384
	ds_read_b128 v[184:187], v203 offset:17408
	ds_read_b128 v[188:191], v203 offset:18432
	ds_read_b128 v[192:195], v203 offset:19456
	ds_read_b128 v[204:207], v203 offset:20480
	ds_read_b128 v[208:211], v203 offset:21504
	ds_read_b128 v[212:215], v203 offset:22528
	ds_read_b128 v[216:219], v203 offset:23552
	s_nop 0
	global_load_lds_dwordx4 v220, s[2:3]
	s_add_i32 m0, s83, 0x2000
	s_nop 0
	global_load_lds_dwordx4 v222, s[2:3]
	s_add_u32 s2, s12, 0x40000
	s_addc_u32 s3, s13, 0
	s_add_i32 s83, s75, s55
	s_mov_b32 m0, s83
	s_nop 0
	global_load_lds_dwordx4 v220, s[2:3]
	s_add_i32 m0, s83, 0x2000
	s_nop 0
	global_load_lds_dwordx4 v222, s[2:3]
	s_mov_b64 s[2:3], s[58:59]
	s_mov_b32 m0, s57
	s_nop 0
	global_load_lds_dwordx4 v8, s[2:3]
	s_mov_b32 m0, s63
	s_nop 0
	global_load_lds_dwordx4 v221, s[2:3]
	s_waitcnt vmcnt(8)
	s_waitcnt lgkmcnt(0)
	s_barrier
; #define PG8_STAGE(bufoff, gbase, voff) do { const char* gb_ = (const char*)(gbase); asm volatile("" : "+s"(gb_));     \
;         _Pragma("unroll") for (int _i = 0; _i < 2; ++_i) \
;         __builtin_amdgcn_global_load_lds((const unsigned*)(gb_ + (voff)[_i]), (PG8_LAS unsigned*)(lds + (bufoff) + ldsw + _i * 8192), 16, 0, 0); } while (0)
; #define PG8_LDA(dst, b, h) do { _Pragma("unroll") for (int m = 0; m < 4; ++m) _Pragma("unroll") for (int k = 0; k < 2; ++k) dst[m][k] = *(const PG8_LAS bf16x8*)(lds + PG8_SA(b, h) + aoff + m * 2048 + k * 1024); } while (0)
; #define PG8_LDB(dst, b, h) do { _Pragma("unroll") for (int n = 0; n < 2; ++n) _Pragma("unroll") for (int k = 0; k < 2; ++k) dst[n][k] = *(const PG8_LAS bf16x8*)(lds + PG8_SB(b, h) + boff + n * 2048 + k * 1024); } while (0)
; #define PG8_MMA(ai, bj, At, Bt) do { __builtin_amdgcn_s_setprio(1); _Pragma("unroll") for (int m = 0; m < 4; ++m) _Pragma("unroll") for (int n = 0; n < 2; ++n) _Pragma("unroll") for (int k = 0; k < 2; ++k) \
;         acc[ai][bj][m][n] = __builtin_amdgcn_mfma_f32_16x16x32_bf16(Bt[n][k], At[m][k], acc[ai][bj][m][n], 0, 0, 0); __builtin_amdgcn_s_setprio(0); } while (0)
; template <class Epi, class Sched, bool ALIGN_EPI = false, bool SP2 = false>
; __device__ __forceinline__ void gemm_phase(PG8_LAS unsigned char* lds, const Gemm g, const Sched& S, const Epi& E, int wid0) {
;     ...
;             PG8_LDB(B0, 0, 0); PG8_LDB(B1, 0, 1); PG8_SCHED; PG8_LDA(At, 0, 0); PG8_STAGE(PG8_SA(1, 1), a1 + hstepA, vA_);
;             PG8_WAIT_V(8); PG8_WAIT_L(0); PG8_BAR; PG8_MMA(0, 0, At, B0); PG8_MMA(0, 1, At, B1); PG8_BAR; PG8_SCHED;
;             PG8_LDA(At, 0, 1); PG8_STAGE(PG8_SB(0, 0), b2, vB_); PG8_STAGE(PG8_SB(0, 1), b2 + hstep, vB_); PG8_STAGE(PG8_SA(0, 0), a2, vA_);
;             PG8_WAIT_V(8); PG8_WAIT_L(0); PG8_BAR; PG8_MMA(1, 0, At, B0); PG8_MMA(1, 1, At, B1); PG8_BAR; PG8_SCHED;
;             PG8_LDB(B0, 1, 0); PG8_LDB(B1, 1, 1); PG8_SCHED; PG8_LDA(At, 1, 0); PG8_STAGE(PG8_SA(0, 1), a2 + hstepA, vA_);
;             PG8_WAIT_V(8); PG8_WAIT_L(0); PG8_BAR; PG8_MMA(0, 0, At, B0); PG8_MMA(0, 1, At, B1); PG8_BAR; PG8_SCHED;
;             PG8_LDA(At, 1, 1); PG8_STAGE(PG8_SB(1, 0), b3, vB_); PG8_STAGE(PG8_SB(1, 1), b3 + hstep, vB_); PG8_STAGE(PG8_SA(1, 0), a3, vA_);
;             PG8_WAIT_V(8); PG8_WAIT_L(0); PG8_BAR; PG8_MMA(1, 0, At, B0); PG8_MMA(1, 1, At, B1); PG8_BAR; PG8_SCHED;
	s_setprio 1
	s_waitcnt lgkmcnt(0)
	v_mfma_f32_16x16x32_bf16 v[74:77], v[82:85], v[180:183], v[74:77]
	v_mfma_f32_16x16x32_bf16 v[70:73], v[94:97], v[180:183], v[70:73]
	v_mfma_f32_16x16x32_bf16 v[58:61], v[82:85], v[188:191], v[58:61]
	v_mfma_f32_16x16x32_bf16 v[54:57], v[94:97], v[188:191], v[54:57]
	v_mfma_f32_16x16x32_bf16 v[42:45], v[82:85], v[204:207], v[42:45]
	v_mfma_f32_16x16x32_bf16 v[38:41], v[94:97], v[204:207], v[38:41]
	v_mfma_f32_16x16x32_bf16 v[26:29], v[82:85], v[212:215], v[26:29]
	v_mfma_f32_16x16x32_bf16 v[22:25], v[94:97], v[212:215], v[22:25]
	v_mfma_f32_16x16x32_bf16 v[74:77], v[90:93], v[184:187], v[74:77]
	v_mfma_f32_16x16x32_bf16 v[70:73], v[102:105], v[184:187], v[70:73]
	v_mfma_f32_16x16x32_bf16 v[58:61], v[90:93], v[192:195], v[58:61]
	v_mfma_f32_16x16x32_bf16 v[54:57], v[102:105], v[192:195], v[54:57]
	v_mfma_f32_16x16x32_bf16 v[42:45], v[90:93], v[208:211], v[42:45]
	v_mfma_f32_16x16x32_bf16 v[38:41], v[102:105], v[208:211], v[38:41]
	v_mfma_f32_16x16x32_bf16 v[26:29], v[90:93], v[216:219], v[26:29]
	v_mfma_f32_16x16x32_bf16 v[22:25], v[102:105], v[216:219], v[22:25]
	s_setprio 0
	s_setprio 1
	v_mfma_f32_16x16x32_bf16 v[66:69], v[158:161], v[180:183], v[66:69]
	v_mfma_f32_16x16x32_bf16 v[62:65], v[166:169], v[180:183], v[62:65]
	v_mfma_f32_16x16x32_bf16 v[50:53], v[158:161], v[188:191], v[50:53]
	v_mfma_f32_16x16x32_bf16 v[46:49], v[166:169], v[188:191], v[46:49]
	v_mfma_f32_16x16x32_bf16 v[34:37], v[158:161], v[204:207], v[34:37]
	v_mfma_f32_16x16x32_bf16 v[30:33], v[166:169], v[204:207], v[30:33]
	v_mfma_f32_16x16x32_bf16 v[18:21], v[158:161], v[212:215], v[18:21]
	v_mfma_f32_16x16x32_bf16 v[14:17], v[166:169], v[212:215], v[14:17]
	v_mfma_f32_16x16x32_bf16 v[66:69], v[162:165], v[184:187], v[66:69]
	v_mfma_f32_16x16x32_bf16 v[62:65], v[170:173], v[184:187], v[62:65]
	v_mfma_f32_16x16x32_bf16 v[50:53], v[162:165], v[192:195], v[50:53]
	v_mfma_f32_16x16x32_bf16 v[46:49], v[170:173], v[192:195], v[46:49]
	s_add_i32 s83, 0, 0x18000
	s_add_i32 s84, 0, 0x1c000
	v_mfma_f32_16x16x32_bf16 v[34:37], v[162:165], v[208:211], v[34:37]
	v_mfma_f32_16x16x32_bf16 v[30:33], v[170:173], v[208:211], v[30:33]
	v_mfma_f32_16x16x32_bf16 v[18:21], v[162:165], v[216:219], v[18:21]
	v_mfma_f32_16x16x32_bf16 v[14:17], v[170:173], v[216:219], v[14:17]
	s_setprio 0
	s_barrier
	v_add_u32_e32 v102, s83, v175
	v_add_u32_e32 v170, s84, v175
	ds_read_b128 v[82:85], v102
	ds_read_b128 v[90:93], v102 offset:1024
	ds_read_b128 v[94:97], v102 offset:2048
	ds_read_b128 v[102:105], v102 offset:3072
	ds_read_b128 v[158:161], v170
	ds_read_b128 v[162:165], v170 offset:1024
	ds_read_b128 v[166:169], v170 offset:2048
	ds_read_b128 v[170:173], v170 offset:3072
	s_add_u32 s2, s58, 0x40000
	s_addc_u32 s3, s59, 0
	s_mov_b32 m0, s64
	ds_read_b128 v[180:183], v203 offset:32768
	ds_read_b128 v[184:187], v203 offset:33792
	ds_read_b128 v[188:191], v203 offset:34816
	ds_read_b128 v[192:195], v203 offset:35840
	ds_read_b128 v[204:207], v203 offset:36864
	ds_read_b128 v[208:211], v203 offset:37888
	ds_read_b128 v[212:215], v203 offset:38912
	ds_read_b128 v[216:219], v203 offset:39936
	s_nop 0
	global_load_lds_dwordx4 v8, s[2:3]
	s_mov_b32 m0, s65
	s_nop 0
	global_load_lds_dwordx4 v221, s[2:3]
	s_waitcnt vmcnt(8)
	s_waitcnt lgkmcnt(0)
	s_barrier
	s_setprio 1
	s_waitcnt lgkmcnt(0)
	v_mfma_f32_16x16x32_bf16 v[154:157], v[82:85], v[180:183], v[154:157]
	v_mfma_f32_16x16x32_bf16 v[150:153], v[94:97], v[180:183], v[150:153]
	v_mfma_f32_16x16x32_bf16 v[138:141], v[82:85], v[188:191], v[138:141]
	v_mfma_f32_16x16x32_bf16 v[134:137], v[94:97], v[188:191], v[134:137]
	v_mfma_f32_16x16x32_bf16 v[122:125], v[82:85], v[204:207], v[122:125]
	v_mfma_f32_16x16x32_bf16 v[118:121], v[94:97], v[204:207], v[118:121]
	v_mfma_f32_16x16x32_bf16 v[106:109], v[82:85], v[212:215], v[106:109]
	v_mfma_f32_16x16x32_bf16 v[98:101], v[94:97], v[212:215], v[98:101]
	v_mfma_f32_16x16x32_bf16 v[154:157], v[90:93], v[184:187], v[154:157]
	v_mfma_f32_16x16x32_bf16 v[150:153], v[102:105], v[184:187], v[150:153]
	v_mfma_f32_16x16x32_bf16 v[138:141], v[90:93], v[192:195], v[138:141]
	v_mfma_f32_16x16x32_bf16 v[134:137], v[102:105], v[192:195], v[134:137]
	v_mfma_f32_16x16x32_bf16 v[122:125], v[90:93], v[208:211], v[122:125]
	v_mfma_f32_16x16x32_bf16 v[118:121], v[102:105], v[208:211], v[118:121]
	v_mfma_f32_16x16x32_bf16 v[106:109], v[90:93], v[216:219], v[106:109]
	v_mfma_f32_16x16x32_bf16 v[98:101], v[102:105], v[216:219], v[98:101]
	s_setprio 0
	s_setprio 1
	v_mfma_f32_16x16x32_bf16 v[146:149], v[158:161], v[180:183], v[146:149]
	v_mfma_f32_16x16x32_bf16 v[142:145], v[166:169], v[180:183], v[142:145]
	v_mfma_f32_16x16x32_bf16 v[130:133], v[158:161], v[188:191], v[130:133]
	v_mfma_f32_16x16x32_bf16 v[126:129], v[166:169], v[188:191], v[126:129]
	v_mfma_f32_16x16x32_bf16 v[114:117], v[158:161], v[204:207], v[114:117]
	v_mfma_f32_16x16x32_bf16 v[110:113], v[166:169], v[204:207], v[110:113]
	v_mfma_f32_16x16x32_bf16 v[86:89], v[158:161], v[212:215], v[86:89]
	v_mfma_f32_16x16x32_bf16 v[78:81], v[166:169], v[212:215], v[78:81]
	v_mfma_f32_16x16x32_bf16 v[146:149], v[162:165], v[184:187], v[146:149]
	v_mfma_f32_16x16x32_bf16 v[142:145], v[170:173], v[184:187], v[142:145]
	v_mfma_f32_16x16x32_bf16 v[130:133], v[162:165], v[192:195], v[130:133]
	v_mfma_f32_16x16x32_bf16 v[126:129], v[170:173], v[192:195], v[126:129]
	s_add_u32 s2, s12, 0x80
	s_addc_u32 s3, s13, 0
	s_add_i32 s58, s83, s55
	s_mov_b32 m0, s58
	v_mfma_f32_16x16x32_bf16 v[114:117], v[162:165], v[208:211], v[114:117]
	v_mfma_f32_16x16x32_bf16 v[110:113], v[170:173], v[208:211], v[110:113]
	v_mfma_f32_16x16x32_bf16 v[86:89], v[162:165], v[216:219], v[86:89]
	v_mfma_f32_16x16x32_bf16 v[78:81], v[170:173], v[216:219], v[78:81]
	s_setprio 0
	s_barrier
; #define PG8_STAGE(bufoff, gbase, voff) do { const char* gb_ = (const char*)(gbase); asm volatile("" : "+s"(gb_));     \
;         _Pragma("unroll") for (int _i = 0; _i < 2; ++_i) \
;         __builtin_amdgcn_global_load_lds((const unsigned*)(gb_ + (voff)[_i]), (PG8_LAS unsigned*)(lds + (bufoff) + ldsw + _i * 8192), 16, 0, 0); } while (0)
; #define PG8_LDA(dst, b, h) do { _Pragma("unroll") for (int m = 0; m < 4; ++m) _Pragma("unroll") for (int k = 0; k < 2; ++k) dst[m][k] = *(const PG8_LAS bf16x8*)(lds + PG8_SA(b, h) + aoff + m * 2048 + k * 1024); } while (0)
; #define PG8_LDB(dst, b, h) do { _Pragma("unroll") for (int n = 0; n < 2; ++n) _Pragma("unroll") for (int k = 0; k < 2; ++k) dst[n][k] = *(const PG8_LAS bf16x8*)(lds + PG8_SB(b, h) + boff + n * 2048 + k * 1024); } while (0)
; #define PG8_WAIT_V(n) asm volatile("s_waitcnt vmcnt(" #n ")" ::: "memory")
; #define PG8_WAIT_L(n) asm volatile("s_waitcnt lgkmcnt(" #n ")" ::: "memory")
; #define PG8_BAR __builtin_amdgcn_s_barrier()
; #define PG8_SCHED __builtin_amdgcn_sched_barrier(0)
; template <class Epi, class Sched, bool ALIGN_EPI = false, bool SP2 = false>
; __device__ __forceinline__ void gemm_phase(PG8_LAS unsigned char* lds, const Gemm g, const Sched& S, const Epi& E, int wid0) {
;     ...
;             PG8_LDB(B0, 0, 0); PG8_LDB(B1, 0, 1); PG8_SCHED; PG8_LDA(At, 0, 0); PG8_STAGE(PG8_SA(1, 1), a1 + hstepA, vA_);
;             PG8_WAIT_V(8); PG8_WAIT_L(0); PG8_BAR; PG8_MMA(0, 0, At, B0); PG8_MMA(0, 1, At, B1); PG8_BAR; PG8_SCHED;
;             PG8_LDA(At, 0, 1); PG8_STAGE(PG8_SB(0, 0), b2, vB_); PG8_STAGE(PG8_SB(0, 1), b2 + hstep, vB_); PG8_STAGE(PG8_SA(0, 0), a2, vA_);
;             PG8_WAIT_V(8); PG8_WAIT_L(0); PG8_BAR; PG8_MMA(1, 0, At, B0); PG8_MMA(1, 1, At, B1); PG8_BAR; PG8_SCHED;
;             PG8_LDB(B0, 1, 0); PG8_LDB(B1, 1, 1); PG8_SCHED; PG8_LDA(At, 1, 0); PG8_STAGE(PG8_SA(0, 1), a2 + hstepA, vA_);
;             PG8_WAIT_V(8); PG8_WAIT_L(0); PG8_BAR; PG8_MMA(0, 0, At, B0); PG8_MMA(0, 1, At, B1); PG8_BAR; PG8_SCHED;
;             PG8_LDA(At, 1, 1); PG8_STAGE(PG8_SB(1, 0), b3, vB_); PG8_STAGE(PG8_SB(1, 1), b3 + hstep, vB_); PG8_STAGE(PG8_SA(1, 0), a3, vA_);
;             PG8_WAIT_V(8); PG8_WAIT_L(0); PG8_BAR; PG8_MMA(1, 0, At, B0); PG8_MMA(1, 1, At, B1); PG8_BAR; PG8_SCHED;
;     ...
;         if constexpr (ALIGN_EPI) { if (wr == 0) PG8_BAR; }
	ds_read_b128 v[180:183], v203 offset:49152
	ds_read_b128 v[184:187], v203 offset:50176
	ds_read_b128 v[188:191], v203 offset:51200
	ds_read_b128 v[192:195], v203 offset:52224
	ds_read_b128 v[204:207], v203 offset:53248
	ds_read_b128 v[208:211], v203 offset:54272
	ds_read_b128 v[212:215], v203 offset:55296
	ds_read_b128 v[216:219], v203 offset:56320
	s_nop 0
	global_load_lds_dwordx4 v220, s[2:3]
	s_add_i32 m0, s58, 0x2000
	s_nop 0
	global_load_lds_dwordx4 v222, s[2:3]
	s_add_u32 s2, s12, 0x40080
	s_addc_u32 s3, s13, 0
	s_add_i32 s12, s84, s55
	s_mov_b32 m0, s12
	s_nop 0
	global_load_lds_dwordx4 v220, s[2:3]
	s_add_i32 m0, s12, 0x2000
	s_nop 0
	global_load_lds_dwordx4 v222, s[2:3]
	s_mov_b32 m0, s68
	s_nop 0
	global_load_lds_dwordx4 v8, s[10:11]
	s_mov_b32 m0, s69
	s_nop 0
	global_load_lds_dwordx4 v221, s[10:11]
	s_waitcnt vmcnt(8)
	s_waitcnt lgkmcnt(0)
	s_barrier
	s_setprio 1
	s_waitcnt lgkmcnt(0)
	v_mfma_f32_16x16x32_bf16 v[74:77], v[82:85], v[180:183], v[74:77]
	v_mfma_f32_16x16x32_bf16 v[70:73], v[94:97], v[180:183], v[70:73]
	v_mfma_f32_16x16x32_bf16 v[58:61], v[82:85], v[188:191], v[58:61]
	v_mfma_f32_16x16x32_bf16 v[54:57], v[94:97], v[188:191], v[54:57]
	v_mfma_f32_16x16x32_bf16 v[42:45], v[82:85], v[204:207], v[42:45]
	v_mfma_f32_16x16x32_bf16 v[38:41], v[94:97], v[204:207], v[38:41]
	v_mfma_f32_16x16x32_bf16 v[26:29], v[82:85], v[212:215], v[26:29]
	v_mfma_f32_16x16x32_bf16 v[22:25], v[94:97], v[212:215], v[22:25]
	v_mfma_f32_16x16x32_bf16 v[74:77], v[90:93], v[184:187], v[74:77]
	v_mfma_f32_16x16x32_bf16 v[70:73], v[102:105], v[184:187], v[70:73]
	v_mfma_f32_16x16x32_bf16 v[58:61], v[90:93], v[192:195], v[58:61]
	v_mfma_f32_16x16x32_bf16 v[54:57], v[102:105], v[192:195], v[54:57]
	v_mfma_f32_16x16x32_bf16 v[42:45], v[90:93], v[208:211], v[42:45]
	v_mfma_f32_16x16x32_bf16 v[38:41], v[102:105], v[208:211], v[38:41]
	v_mfma_f32_16x16x32_bf16 v[26:29], v[90:93], v[216:219], v[26:29]
	v_mfma_f32_16x16x32_bf16 v[22:25], v[102:105], v[216:219], v[22:25]
	s_setprio 0
	s_setprio 1
	v_mfma_f32_16x16x32_bf16 v[66:69], v[158:161], v[180:183], v[66:69]
	v_mfma_f32_16x16x32_bf16 v[62:65], v[166:169], v[180:183], v[62:65]
	v_mfma_f32_16x16x32_bf16 v[50:53], v[158:161], v[188:191], v[50:53]
	v_mfma_f32_16x16x32_bf16 v[46:49], v[166:169], v[188:191], v[46:49]
	v_mfma_f32_16x16x32_bf16 v[34:37], v[158:161], v[204:207], v[34:37]
	v_mfma_f32_16x16x32_bf16 v[30:33], v[166:169], v[204:207], v[30:33]
	v_mfma_f32_16x16x32_bf16 v[18:21], v[158:161], v[212:215], v[18:21]
	v_mfma_f32_16x16x32_bf16 v[14:17], v[166:169], v[212:215], v[14:17]
	v_mfma_f32_16x16x32_bf16 v[66:69], v[162:165], v[184:187], v[66:69]
	v_mfma_f32_16x16x32_bf16 v[62:65], v[170:173], v[184:187], v[62:65]
	v_mfma_f32_16x16x32_bf16 v[50:53], v[162:165], v[192:195], v[50:53]
	v_mfma_f32_16x16x32_bf16 v[46:49], v[170:173], v[192:195], v[46:49]
	s_add_i32 s82, s82, 2
	s_add_u32 s80, s80, 0x100
	s_addc_u32 s81, s81, 0
	s_cmp_gt_u32 s82, 13
	s_mov_b64 s[2:3], s[8:9]
	v_mfma_f32_16x16x32_bf16 v[34:37], v[162:165], v[208:211], v[34:37]
	v_mfma_f32_16x16x32_bf16 v[30:33], v[170:173], v[208:211], v[30:33]
	v_mfma_f32_16x16x32_bf16 v[18:21], v[162:165], v[216:219], v[18:21]
	v_mfma_f32_16x16x32_bf16 v[14:17], v[170:173], v[216:219], v[14:17]
	s_setprio 0
	s_barrier
	s_cbranch_scc0 .LBB13_358
	s_and_b64 vcc, exec, s[42:43]
	s_cbranch_vccz .LBB13_361
	s_barrier

;     __device__ float mid(int row) const { return rg(row) / ra(row); }
; #define PG8_WAIT_V(n) asm volatile("s_waitcnt vmcnt(" #n ")" ::: "memory")
; #define PG8_WAIT_L(n) asm volatile("s_waitcnt lgkmcnt(" #n ")" ::: "memory")
; #define PG8_BAR __builtin_amdgcn_s_barrier()
; template <class Epi, class Sched, bool ALIGN_EPI = false, bool SP2 = false>
; __device__ __forceinline__ void gemm_phase(PG8_LAS unsigned char* lds, const Gemm g, const Sched& S, const Epi& E, int wid0) {
;     ...
;         const char* nA = has_next ? (const char*)g.A + (size_t)nxt.pm * tstepA : cA; const char* nB = has_next ? (const char*)g.Bt + (size_t)nxt.pn * tstep : cB;
; #pragma nounroll
;         for (int t = 0; t < nt; t += 2) {
;             const bool last = (t == nt - 2);
;             const char* a1 = cA + (size_t)(t + 1) * kstep;
;             const char* a2 = last ? nA : cA + (size_t)(t + 2) * kstep; const char* b2 = last ? nB : cB + (size_t)(t + 2) * kstep;
;             const char* a3 = a2 + kstep; const char* b3 = b2 + kstep;
;             if (last && has_next) S.a_ready(nxt);
;             if constexpr (Epi::HAS_MID) { if (t == Epi::MID_T) E.mid(acc, cur, wr, fr); }
;             unsigned vA_[2] = {voffA[0], voffA[1]}, vB_[2] = {voffB[0], voffB[1]};
;             asm volatile("" : "+v"(vA_[0]), "+v"(vA_[1]), "+v"(vB_[0]), "+v"(vB_[1]));
;             if constexpr (SP2) {
;             PG8_LDB(B0, 0, 0); PG8_LDB(B1, 0, 1); PG8_SCHED; PG8_LDA(At, 0, 0); PG8_STAGE(PG8_SA(1, 1), a1 + hstepA, vA_);
;             PG8_WAIT_V(8); PG8_WAIT_L(0); PG8_BAR; PG8_MMA(0, 0, At, B0); PG8_MMA(0, 1, At, B1); PG8_BAR; PG8_SCHED;
;             PG8_LDA(At, 0, 1); PG8_STAGE(PG8_SB(0, 0), b2, vB_); PG8_STAGE(PG8_SB(0, 1), b2 + hstep, vB_); PG8_STAGE(PG8_SA(0, 0), a2, vA_);
;             PG8_WAIT_V(8); PG8_WAIT_L(0); PG8_BAR; PG8_MMA(1, 0, At, B0); PG8_MMA(1, 1, At, B1); PG8_BAR; PG8_SCHED;
;             PG8_LDB(B0, 1, 0); PG8_LDB(B1, 1, 1); PG8_SCHED; PG8_LDA(At, 1, 0); PG8_STAGE(PG8_SA(0, 1), a2 + hstepA, vA_);
;             PG8_WAIT_V(8); PG8_WAIT_L(0); PG8_BAR; PG8_MMA(0, 0, At, B0); PG8_MMA(0, 1, At, B1); PG8_BAR; PG8_SCHED;
;             PG8_LDA(At, 1, 1); PG8_STAGE(PG8_SB(1, 0), b3, vB_); PG8_STAGE(PG8_SB(1, 1), b3 + hstep, vB_); PG8_STAGE(PG8_SA(1, 0), a3, vA_);
;             PG8_WAIT_V(8); PG8_WAIT_L(0); PG8_BAR; PG8_MMA(1, 0, At, B0); PG8_MMA(1, 1, At, B1); PG8_BAR; PG8_SCHED;
.LBB13_942:
	v_mov_b32_e32 v9, v160
	v_mov_b32_e32 v154, v162
	v_mov_b32_e32 v155, v156
	v_mov_b32_e32 v166, v158
	v_add_u32_e32 v10, s64, v157
	ds_read_b128 v[142:145], v10
	ds_read_b128 v[146:149], v10 offset:1024
	ds_read_b128 v[150:153], v10 offset:2048
	ds_read_b128 v[168:171], v10 offset:3072
	v_add_u32_e32 v10, s65, v157
	s_add_u32 s6, s42, 0x100
	ds_read_b128 v[172:175], v10
	ds_read_b128 v[176:179], v10 offset:1024
	ds_read_b128 v[180:183], v10 offset:2048
	ds_read_b128 v[184:187], v10 offset:3072
	s_addc_u32 s7, s43, 0
	s_cmp_eq_u32 s70, 12
	s_cselect_b32 s50, s35, s6
	s_cselect_b32 s51, s29, s7
	s_cselect_b32 s45, s31, s69
	s_cselect_b32 s44, s67, s68
	s_add_u32 s46, s50, 0x80
	s_addc_u32 s47, s51, 0
	s_add_u32 s48, s44, 0x80
	s_addc_u32 s49, s45, 0
	s_add_u32 s42, s42, 0x80080
	s_addc_u32 s43, s43, 0
	s_add_i32 m0, s13, 0xc000
	ds_read_b128 v[188:191], v167
	ds_read_b128 v[192:195], v167 offset:1024
	ds_read_b128 v[196:199], v167 offset:2048
	ds_read_b128 v[200:203], v167 offset:3072
	ds_read_b128 v[204:207], v167 offset:4096
	ds_read_b128 v[208:211], v167 offset:5120
	ds_read_b128 v[212:215], v167 offset:6144
	ds_read_b128 v[216:219], v167 offset:7168
	s_nop 0
	global_load_lds_dwordx4 v155, s[42:43]
	s_add_i32 m0, s13, 0xe000
	s_nop 0
	global_load_lds_dwordx4 v9, s[42:43]
	s_waitcnt vmcnt(8)
	s_waitcnt lgkmcnt(0)
	s_barrier
	s_setprio 1
	s_waitcnt lgkmcnt(0)
	v_mfma_f32_16x16x32_bf16 v[136:139], v[142:145], v[188:191], v[136:139]
	v_mfma_f32_16x16x32_bf16 v[132:135], v[150:153], v[188:191], v[132:135]
	v_mfma_f32_16x16x32_bf16 v[128:131], v[142:145], v[196:199], v[128:131]
	v_mfma_f32_16x16x32_bf16 v[124:127], v[150:153], v[196:199], v[124:127]
	v_mfma_f32_16x16x32_bf16 v[120:123], v[142:145], v[204:207], v[120:123]
	v_mfma_f32_16x16x32_bf16 v[116:119], v[150:153], v[204:207], v[116:119]
	v_mfma_f32_16x16x32_bf16 v[112:115], v[142:145], v[212:215], v[112:115]
	v_mfma_f32_16x16x32_bf16 v[108:111], v[150:153], v[212:215], v[108:111]
	v_mfma_f32_16x16x32_bf16 v[136:139], v[146:149], v[192:195], v[136:139]
	v_mfma_f32_16x16x32_bf16 v[132:135], v[168:171], v[192:195], v[132:135]
	v_mfma_f32_16x16x32_bf16 v[128:131], v[146:149], v[200:203], v[128:131]
	v_mfma_f32_16x16x32_bf16 v[124:127], v[168:171], v[200:203], v[124:127]
	v_mfma_f32_16x16x32_bf16 v[120:123], v[146:149], v[208:211], v[120:123]
	v_mfma_f32_16x16x32_bf16 v[116:119], v[168:171], v[208:211], v[116:119]
	v_mfma_f32_16x16x32_bf16 v[112:115], v[146:149], v[216:219], v[112:115]
	v_mfma_f32_16x16x32_bf16 v[108:111], v[168:171], v[216:219], v[108:111]
	s_setprio 0
	s_setprio 1
	v_mfma_f32_16x16x32_bf16 v[72:75], v[172:175], v[188:191], v[72:75]
	v_mfma_f32_16x16x32_bf16 v[68:71], v[180:183], v[188:191], v[68:71]
	v_mfma_f32_16x16x32_bf16 v[64:67], v[172:175], v[196:199], v[64:67]
	v_mfma_f32_16x16x32_bf16 v[60:63], v[180:183], v[196:199], v[60:63]
	v_mfma_f32_16x16x32_bf16 v[56:59], v[172:175], v[204:207], v[56:59]
	v_mfma_f32_16x16x32_bf16 v[52:55], v[180:183], v[204:207], v[52:55]
	v_mfma_f32_16x16x32_bf16 v[48:51], v[172:175], v[212:215], v[48:51]
	v_mfma_f32_16x16x32_bf16 v[44:47], v[180:183], v[212:215], v[44:47]
	v_mfma_f32_16x16x32_bf16 v[72:75], v[176:179], v[192:195], v[72:75]
	v_mfma_f32_16x16x32_bf16 v[68:71], v[184:187], v[192:195], v[68:71]
	v_mfma_f32_16x16x32_bf16 v[64:67], v[176:179], v[200:203], v[64:67]
	v_mfma_f32_16x16x32_bf16 v[60:63], v[184:187], v[200:203], v[60:63]
	s_add_i32 s71, s64, s27
	s_mov_b64 s[42:43], s[44:45]
	s_mov_b32 m0, s71
	v_mfma_f32_16x16x32_bf16 v[56:59], v[176:179], v[208:211], v[56:59]
	v_mfma_f32_16x16x32_bf16 v[52:55], v[184:187], v[208:211], v[52:55]
	v_mfma_f32_16x16x32_bf16 v[48:51], v[176:179], v[216:219], v[48:51]
	v_mfma_f32_16x16x32_bf16 v[44:47], v[184:187], v[216:219], v[44:47]
	s_setprio 0
	s_barrier
	ds_read_b128 v[188:191], v167 offset:16384
	ds_read_b128 v[192:195], v167 offset:17408
	ds_read_b128 v[196:199], v167 offset:18432
	ds_read_b128 v[200:203], v167 offset:19456
	ds_read_b128 v[204:207], v167 offset:20480
	ds_read_b128 v[208:211], v167 offset:21504
	ds_read_b128 v[212:215], v167 offset:22528
	ds_read_b128 v[216:219], v167 offset:23552
	s_nop 0
	global_load_lds_dwordx4 v166, s[42:43]
	s_add_i32 m0, s71, 0x2000
	s_nop 0
	global_load_lds_dwordx4 v154, s[42:43]
	s_add_u32 s42, s44, 0x40000
	s_addc_u32 s43, s45, 0
	s_add_i32 s71, s65, s27
	s_mov_b32 m0, s71
	s_nop 0
	global_load_lds_dwordx4 v166, s[42:43]
	s_add_i32 m0, s71, 0x2000
	s_nop 0
	global_load_lds_dwordx4 v154, s[42:43]
	s_mov_b64 s[42:43], s[50:51]
	s_mov_b32 m0, s13
	s_nop 0
	global_load_lds_dwordx4 v155, s[42:43]
	s_mov_b32 m0, s53
	s_nop 0
	global_load_lds_dwordx4 v9, s[42:43]
	s_waitcnt vmcnt(8)
	s_waitcnt lgkmcnt(0)
	s_barrier
; #define PG8_STAGE(bufoff, gbase, voff) do { const char* gb_ = (const char*)(gbase); asm volatile("" : "+s"(gb_));     \
;         _Pragma("unroll") for (int _i = 0; _i < 2; ++_i) \
;         __builtin_amdgcn_global_load_lds((const unsigned*)(gb_ + (voff)[_i]), (PG8_LAS unsigned*)(lds + (bufoff) + ldsw + _i * 8192), 16, 0, 0); } while (0)
; #define PG8_LDA(dst, b, h) do { _Pragma("unroll") for (int m = 0; m < 4; ++m) _Pragma("unroll") for (int k = 0; k < 2; ++k) dst[m][k] = *(const PG8_LAS bf16x8*)(lds + PG8_SA(b, h) + aoff + m * 2048 + k * 1024); } while (0)
; #define PG8_LDB(dst, b, h) do { _Pragma("unroll") for (int n = 0; n < 2; ++n) _Pragma("unroll") for (int k = 0; k < 2; ++k) dst[n][k] = *(const PG8_LAS bf16x8*)(lds + PG8_SB(b, h) + boff + n * 2048 + k * 1024); } while (0)
; #define PG8_MMA(ai, bj, At, Bt) do { __builtin_amdgcn_s_setprio(1); _Pragma("unroll") for (int m = 0; m < 4; ++m) _Pragma("unroll") for (int n = 0; n < 2; ++n) _Pragma("unroll") for (int k = 0; k < 2; ++k) \
;         acc[ai][bj][m][n] = __builtin_amdgcn_mfma_f32_16x16x32_bf16(Bt[n][k], At[m][k], acc[ai][bj][m][n], 0, 0, 0); __builtin_amdgcn_s_setprio(0); } while (0)
; template <class Epi, class Sched, bool ALIGN_EPI = false, bool SP2 = false>
; __device__ __forceinline__ void gemm_phase(PG8_LAS unsigned char* lds, const Gemm g, const Sched& S, const Epi& E, int wid0) {
;     ...
;             PG8_LDB(B0, 0, 0); PG8_LDB(B1, 0, 1); PG8_SCHED; PG8_LDA(At, 0, 0); PG8_STAGE(PG8_SA(1, 1), a1 + hstepA, vA_);
;             PG8_WAIT_V(8); PG8_WAIT_L(0); PG8_BAR; PG8_MMA(0, 0, At, B0); PG8_MMA(0, 1, At, B1); PG8_BAR; PG8_SCHED;
;             PG8_LDA(At, 0, 1); PG8_STAGE(PG8_SB(0, 0), b2, vB_); PG8_STAGE(PG8_SB(0, 1), b2 + hstep, vB_); PG8_STAGE(PG8_SA(0, 0), a2, vA_);
;             PG8_WAIT_V(8); PG8_WAIT_L(0); PG8_BAR; PG8_MMA(1, 0, At, B0); PG8_MMA(1, 1, At, B1); PG8_BAR; PG8_SCHED;
;             PG8_LDB(B0, 1, 0); PG8_LDB(B1, 1, 1); PG8_SCHED; PG8_LDA(At, 1, 0); PG8_STAGE(PG8_SA(0, 1), a2 + hstepA, vA_);
;             PG8_WAIT_V(8); PG8_WAIT_L(0); PG8_BAR; PG8_MMA(0, 0, At, B0); PG8_MMA(0, 1, At, B1); PG8_BAR; PG8_SCHED;
;             PG8_LDA(At, 1, 1); PG8_STAGE(PG8_SB(1, 0), b3, vB_); PG8_STAGE(PG8_SB(1, 1), b3 + hstep, vB_); PG8_STAGE(PG8_SA(1, 0), a3, vA_);
;             PG8_WAIT_V(8); PG8_WAIT_L(0); PG8_BAR; PG8_MMA(1, 0, At, B0); PG8_MMA(1, 1, At, B1); PG8_BAR; PG8_SCHED;
	s_setprio 1
	s_waitcnt lgkmcnt(0)
	v_mfma_f32_16x16x32_bf16 v[104:107], v[142:145], v[188:191], v[104:107]
	v_mfma_f32_16x16x32_bf16 v[100:103], v[150:153], v[188:191], v[100:103]
	v_mfma_f32_16x16x32_bf16 v[96:99], v[142:145], v[196:199], v[96:99]
	v_mfma_f32_16x16x32_bf16 v[92:95], v[150:153], v[196:199], v[92:95]
	v_mfma_f32_16x16x32_bf16 v[88:91], v[142:145], v[204:207], v[88:91]
	v_mfma_f32_16x16x32_bf16 v[84:87], v[150:153], v[204:207], v[84:87]
	v_mfma_f32_16x16x32_bf16 v[80:83], v[142:145], v[212:215], v[80:83]
	v_mfma_f32_16x16x32_bf16 v[76:79], v[150:153], v[212:215], v[76:79]
	v_mfma_f32_16x16x32_bf16 v[104:107], v[146:149], v[192:195], v[104:107]
	v_mfma_f32_16x16x32_bf16 v[100:103], v[168:171], v[192:195], v[100:103]
	v_mfma_f32_16x16x32_bf16 v[96:99], v[146:149], v[200:203], v[96:99]
	v_mfma_f32_16x16x32_bf16 v[92:95], v[168:171], v[200:203], v[92:95]
	v_mfma_f32_16x16x32_bf16 v[88:91], v[146:149], v[208:211], v[88:91]
	v_mfma_f32_16x16x32_bf16 v[84:87], v[168:171], v[208:211], v[84:87]
	v_mfma_f32_16x16x32_bf16 v[80:83], v[146:149], v[216:219], v[80:83]
	v_mfma_f32_16x16x32_bf16 v[76:79], v[168:171], v[216:219], v[76:79]
	s_setprio 0
	s_setprio 1
	v_mfma_f32_16x16x32_bf16 v[40:43], v[172:175], v[188:191], v[40:43]
	v_mfma_f32_16x16x32_bf16 v[36:39], v[180:183], v[188:191], v[36:39]
	v_mfma_f32_16x16x32_bf16 v[32:35], v[172:175], v[196:199], v[32:35]
	v_mfma_f32_16x16x32_bf16 v[28:31], v[180:183], v[196:199], v[28:31]
	v_mfma_f32_16x16x32_bf16 v[24:27], v[172:175], v[204:207], v[24:27]
	v_mfma_f32_16x16x32_bf16 v[20:23], v[180:183], v[204:207], v[20:23]
	v_mfma_f32_16x16x32_bf16 v[16:19], v[172:175], v[212:215], v[16:19]
	v_mfma_f32_16x16x32_bf16 v[10:13], v[180:183], v[212:215], v[12:15]
	v_mfma_f32_16x16x32_bf16 v[40:43], v[176:179], v[192:195], v[40:43]
	v_mfma_f32_16x16x32_bf16 v[36:39], v[184:187], v[192:195], v[36:39]
	v_mfma_f32_16x16x32_bf16 v[32:35], v[176:179], v[200:203], v[32:35]
	v_mfma_f32_16x16x32_bf16 v[28:31], v[184:187], v[200:203], v[28:31]
	s_add_i32 s71, 0, 0x18000
	v_mfma_f32_16x16x32_bf16 v[24:27], v[176:179], v[208:211], v[24:27]
	v_mfma_f32_16x16x32_bf16 v[20:23], v[184:187], v[208:211], v[20:23]
	v_mfma_f32_16x16x32_bf16 v[16:19], v[176:179], v[216:219], v[16:19]
	v_mfma_f32_16x16x32_bf16 v[10:13], v[184:187], v[216:219], v[10:13]
	s_setprio 0
	s_barrier
	v_add_u32_e32 v14, s71, v157
	s_add_i32 s72, 0, 0x1c000
	ds_read_b128 v[142:145], v14
	ds_read_b128 v[146:149], v14 offset:1024
	ds_read_b128 v[150:153], v14 offset:2048
	ds_read_b128 v[168:171], v14 offset:3072
	v_add_u32_e32 v14, s72, v157
	ds_read_b128 v[172:175], v14
	ds_read_b128 v[176:179], v14 offset:1024
	ds_read_b128 v[180:183], v14 offset:2048
	ds_read_b128 v[184:187], v14 offset:3072
	s_add_u32 s42, s50, 0x80000
	s_addc_u32 s43, s51, 0
	s_mov_b32 m0, s54
	ds_read_b128 v[188:191], v167 offset:32768
	ds_read_b128 v[192:195], v167 offset:33792
	ds_read_b128 v[196:199], v167 offset:34816
	ds_read_b128 v[200:203], v167 offset:35840
	ds_read_b128 v[204:207], v167 offset:36864
	ds_read_b128 v[208:211], v167 offset:37888
	ds_read_b128 v[212:215], v167 offset:38912
	ds_read_b128 v[216:219], v167 offset:39936
	s_nop 0
	global_load_lds_dwordx4 v155, s[42:43]
	s_mov_b32 m0, s55
	s_nop 0
	global_load_lds_dwordx4 v9, s[42:43]
	s_waitcnt vmcnt(8)
	s_waitcnt lgkmcnt(0)
	s_barrier
	s_setprio 1
	s_waitcnt lgkmcnt(0)
	v_mfma_f32_16x16x32_bf16 v[136:139], v[142:145], v[188:191], v[136:139]
	v_mfma_f32_16x16x32_bf16 v[132:135], v[150:153], v[188:191], v[132:135]
	v_mfma_f32_16x16x32_bf16 v[128:131], v[142:145], v[196:199], v[128:131]
	v_mfma_f32_16x16x32_bf16 v[124:127], v[150:153], v[196:199], v[124:127]
	v_mfma_f32_16x16x32_bf16 v[120:123], v[142:145], v[204:207], v[120:123]
	v_mfma_f32_16x16x32_bf16 v[116:119], v[150:153], v[204:207], v[116:119]
	v_mfma_f32_16x16x32_bf16 v[112:115], v[142:145], v[212:215], v[112:115]
	v_mfma_f32_16x16x32_bf16 v[108:111], v[150:153], v[212:215], v[108:111]
	v_mfma_f32_16x16x32_bf16 v[136:139], v[146:149], v[192:195], v[136:139]
	v_mfma_f32_16x16x32_bf16 v[132:135], v[168:171], v[192:195], v[132:135]
	v_mfma_f32_16x16x32_bf16 v[128:131], v[146:149], v[200:203], v[128:131]
	v_mfma_f32_16x16x32_bf16 v[124:127], v[168:171], v[200:203], v[124:127]
	v_mfma_f32_16x16x32_bf16 v[120:123], v[146:149], v[208:211], v[120:123]
	v_mfma_f32_16x16x32_bf16 v[116:119], v[168:171], v[208:211], v[116:119]
	v_mfma_f32_16x16x32_bf16 v[112:115], v[146:149], v[216:219], v[112:115]
	v_mfma_f32_16x16x32_bf16 v[108:111], v[168:171], v[216:219], v[108:111]
	s_setprio 0
	s_setprio 1
	v_mfma_f32_16x16x32_bf16 v[72:75], v[172:175], v[188:191], v[72:75]
	v_mfma_f32_16x16x32_bf16 v[68:71], v[180:183], v[188:191], v[68:71]
	v_mfma_f32_16x16x32_bf16 v[64:67], v[172:175], v[196:199], v[64:67]
	v_mfma_f32_16x16x32_bf16 v[60:63], v[180:183], v[196:199], v[60:63]
	v_mfma_f32_16x16x32_bf16 v[56:59], v[172:175], v[204:207], v[56:59]
	v_mfma_f32_16x16x32_bf16 v[52:55], v[180:183], v[204:207], v[52:55]
	v_mfma_f32_16x16x32_bf16 v[48:51], v[172:175], v[212:215], v[48:51]
	v_mfma_f32_16x16x32_bf16 v[44:47], v[180:183], v[212:215], v[44:47]
	v_mfma_f32_16x16x32_bf16 v[72:75], v[176:179], v[192:195], v[72:75]
	v_mfma_f32_16x16x32_bf16 v[68:71], v[184:187], v[192:195], v[68:71]
	v_mfma_f32_16x16x32_bf16 v[64:67], v[176:179], v[200:203], v[64:67]
	v_mfma_f32_16x16x32_bf16 v[60:63], v[184:187], v[200:203], v[60:63]
	s_add_i32 s42, s71, s27
	s_mov_b32 m0, s42
	v_mfma_f32_16x16x32_bf16 v[56:59], v[176:179], v[208:211], v[56:59]
	v_mfma_f32_16x16x32_bf16 v[52:55], v[184:187], v[208:211], v[52:55]
	v_mfma_f32_16x16x32_bf16 v[48:51], v[176:179], v[216:219], v[48:51]
	v_mfma_f32_16x16x32_bf16 v[44:47], v[184:187], v[216:219], v[44:47]
	s_setprio 0
	s_barrier
;     __device__ float mid(int row) const { return rg(row) / ra(row); }
; #define PG8_STAGE(bufoff, gbase, voff) do { const char* gb_ = (const char*)(gbase); asm volatile("" : "+s"(gb_));     \
;         _Pragma("unroll") for (int _i = 0; _i < 2; ++_i) \
;         __builtin_amdgcn_global_load_lds((const unsigned*)(gb_ + (voff)[_i]), (PG8_LAS unsigned*)(lds + (bufoff) + ldsw + _i * 8192), 16, 0, 0); } while (0)
; #define PG8_LDA(dst, b, h) do { _Pragma("unroll") for (int m = 0; m < 4; ++m) _Pragma("unroll") for (int k = 0; k < 2; ++k) dst[m][k] = *(const PG8_LAS bf16x8*)(lds + PG8_SA(b, h) + aoff + m * 2048 + k * 1024); } while (0)
; #define PG8_WAIT_V(n) asm volatile("s_waitcnt vmcnt(" #n ")" ::: "memory")
; #define PG8_WAIT_L(n) asm volatile("s_waitcnt lgkmcnt(" #n ")" ::: "memory")
; template <class Epi, class Sched, bool ALIGN_EPI = false, bool SP2 = false>
; __device__ __forceinline__ void gemm_phase(PG8_LAS unsigned char* lds, const Gemm g, const Sched& S, const Epi& E, int wid0) {
;     ...
;             if constexpr (Epi::HAS_MID) { if (t == Epi::MID_T) E.mid(acc, cur, wr, fr); }
;             unsigned vA_[2] = {voffA[0], voffA[1]}, vB_[2] = {voffB[0], voffB[1]};
;             asm volatile("" : "+v"(vA_[0]), "+v"(vA_[1]), "+v"(vB_[0]), "+v"(vB_[1]));
;             if constexpr (SP2) {
;             PG8_LDB(B0, 0, 0); PG8_LDB(B1, 0, 1); PG8_SCHED; PG8_LDA(At, 0, 0); PG8_STAGE(PG8_SA(1, 1), a1 + hstepA, vA_);
;             PG8_WAIT_V(8); PG8_WAIT_L(0); PG8_BAR; PG8_MMA(0, 0, At, B0); PG8_MMA(0, 1, At, B1); PG8_BAR; PG8_SCHED;
;             PG8_LDA(At, 0, 1); PG8_STAGE(PG8_SB(0, 0), b2, vB_); PG8_STAGE(PG8_SB(0, 1), b2 + hstep, vB_); PG8_STAGE(PG8_SA(0, 0), a2, vA_);
;             PG8_WAIT_V(8); PG8_WAIT_L(0); PG8_BAR; PG8_MMA(1, 0, At, B0); PG8_MMA(1, 1, At, B1); PG8_BAR; PG8_SCHED;
;             PG8_LDB(B0, 1, 0); PG8_LDB(B1, 1, 1); PG8_SCHED; PG8_LDA(At, 1, 0); PG8_STAGE(PG8_SA(0, 1), a2 + hstepA, vA_);
;             PG8_WAIT_V(8); PG8_WAIT_L(0); PG8_BAR; PG8_MMA(0, 0, At, B0); PG8_MMA(0, 1, At, B1); PG8_BAR; PG8_SCHED;
;             PG8_LDA(At, 1, 1); PG8_STAGE(PG8_SB(1, 0), b3, vB_); PG8_STAGE(PG8_SB(1, 1), b3 + hstep, vB_); PG8_STAGE(PG8_SA(1, 0), a3, vA_);
;             PG8_WAIT_V(8); PG8_WAIT_L(0); PG8_BAR; PG8_MMA(1, 0, At, B0); PG8_MMA(1, 1, At, B1); PG8_BAR; PG8_SCHED;
;     ...
;         if constexpr (ALIGN_EPI) { if (wr == 0) PG8_BAR; }
	ds_read_b128 v[188:191], v167 offset:49152
	ds_read_b128 v[192:195], v167 offset:50176
	ds_read_b128 v[196:199], v167 offset:51200
	ds_read_b128 v[200:203], v167 offset:52224
	ds_read_b128 v[204:207], v167 offset:53248
	ds_read_b128 v[208:211], v167 offset:54272
	ds_read_b128 v[212:215], v167 offset:55296
	ds_read_b128 v[216:219], v167 offset:56320
	s_nop 0
	global_load_lds_dwordx4 v166, s[48:49]
	s_add_i32 m0, s42, 0x2000
	s_add_u32 s42, s44, 0x40080
	s_addc_u32 s43, s45, 0
	s_add_i32 s44, s72, s27
	global_load_lds_dwordx4 v154, s[48:49]
	s_mov_b32 m0, s44
	s_nop 0
	global_load_lds_dwordx4 v166, s[42:43]
	s_add_i32 m0, s44, 0x2000
	s_nop 0
	global_load_lds_dwordx4 v154, s[42:43]
	s_mov_b32 m0, s59
	s_nop 0
	global_load_lds_dwordx4 v155, s[46:47]
	s_mov_b32 m0, s60
	s_nop 0
	global_load_lds_dwordx4 v9, s[46:47]
	s_waitcnt vmcnt(8)
	s_waitcnt lgkmcnt(0)
	s_barrier
	s_setprio 1
	s_waitcnt lgkmcnt(0)
	v_mfma_f32_16x16x32_bf16 v[104:107], v[142:145], v[188:191], v[104:107]
	v_mfma_f32_16x16x32_bf16 v[100:103], v[150:153], v[188:191], v[100:103]
	v_mfma_f32_16x16x32_bf16 v[96:99], v[142:145], v[196:199], v[96:99]
	v_mfma_f32_16x16x32_bf16 v[92:95], v[150:153], v[196:199], v[92:95]
	v_mfma_f32_16x16x32_bf16 v[88:91], v[142:145], v[204:207], v[88:91]
	v_mfma_f32_16x16x32_bf16 v[84:87], v[150:153], v[204:207], v[84:87]
	v_mfma_f32_16x16x32_bf16 v[80:83], v[142:145], v[212:215], v[80:83]
	v_mfma_f32_16x16x32_bf16 v[76:79], v[150:153], v[212:215], v[76:79]
	v_mfma_f32_16x16x32_bf16 v[104:107], v[146:149], v[192:195], v[104:107]
	v_mfma_f32_16x16x32_bf16 v[100:103], v[168:171], v[192:195], v[100:103]
	v_mfma_f32_16x16x32_bf16 v[96:99], v[146:149], v[200:203], v[96:99]
	v_mfma_f32_16x16x32_bf16 v[92:95], v[168:171], v[200:203], v[92:95]
	v_mfma_f32_16x16x32_bf16 v[88:91], v[146:149], v[208:211], v[88:91]
	v_mfma_f32_16x16x32_bf16 v[84:87], v[168:171], v[208:211], v[84:87]
	v_mfma_f32_16x16x32_bf16 v[80:83], v[146:149], v[216:219], v[80:83]
	v_mfma_f32_16x16x32_bf16 v[76:79], v[168:171], v[216:219], v[76:79]
	s_setprio 0
	s_setprio 1
	v_mfma_f32_16x16x32_bf16 v[40:43], v[172:175], v[188:191], v[40:43]
	v_mfma_f32_16x16x32_bf16 v[36:39], v[180:183], v[188:191], v[36:39]
	v_mfma_f32_16x16x32_bf16 v[32:35], v[172:175], v[196:199], v[32:35]
	v_mfma_f32_16x16x32_bf16 v[28:31], v[180:183], v[196:199], v[28:31]
	v_mfma_f32_16x16x32_bf16 v[24:27], v[172:175], v[204:207], v[24:27]
	v_mfma_f32_16x16x32_bf16 v[20:23], v[180:183], v[204:207], v[20:23]
	v_mfma_f32_16x16x32_bf16 v[14:17], v[172:175], v[212:215], v[16:19]
	v_mfma_f32_16x16x32_bf16 v[10:13], v[180:183], v[212:215], v[10:13]
	v_mfma_f32_16x16x32_bf16 v[40:43], v[176:179], v[192:195], v[40:43]
	v_mfma_f32_16x16x32_bf16 v[36:39], v[184:187], v[192:195], v[36:39]
	v_mfma_f32_16x16x32_bf16 v[32:35], v[176:179], v[200:203], v[32:35]
	v_mfma_f32_16x16x32_bf16 v[28:31], v[184:187], v[200:203], v[28:31]
	s_add_i32 s70, s70, 2
	s_add_u32 s68, s68, 0x100
	s_addc_u32 s69, s69, 0
	s_cmp_gt_u32 s70, 13
	v_mfma_f32_16x16x32_bf16 v[24:27], v[176:179], v[208:211], v[24:27]
	v_mfma_f32_16x16x32_bf16 v[20:23], v[184:187], v[208:211], v[20:23]
	v_mfma_f32_16x16x32_bf16 v[16:19], v[176:179], v[216:219], v[14:17]
	v_mfma_f32_16x16x32_bf16 v[12:15], v[184:187], v[216:219], v[10:13]
	s_setprio 0
	s_barrier
	s_cbranch_scc1 .LBB13_944
	s_mov_b64 s[42:43], s[6:7]
	s_cmp_lg_u32 s70, 6
	s_cbranch_scc0 .LBB13_941
	s_branch .LBB13_942

; #define PG8_STAGE(bufoff, gbase, voff) do { const char* gb_ = (const char*)(gbase); asm volatile("" : "+s"(gb_));     \
;         _Pragma("unroll") for (int _i = 0; _i < 2; ++_i) \
;         __builtin_amdgcn_global_load_lds((const unsigned*)(gb_ + (voff)[_i]), (PG8_LAS unsigned*)(lds + (bufoff) + ldsw + _i * 8192), 16, 0, 0); } while (0)
; #define PG8_LDA(dst, b, h) do { _Pragma("unroll") for (int m = 0; m < 4; ++m) _Pragma("unroll") for (int k = 0; k < 2; ++k) dst[m][k] = *(const PG8_LAS bf16x8*)(lds + PG8_SA(b, h) + aoff + m * 2048 + k * 1024); } while (0)
; #define PG8_LDB(dst, b, h) do { _Pragma("unroll") for (int n = 0; n < 2; ++n) _Pragma("unroll") for (int k = 0; k < 2; ++k) dst[n][k] = *(const PG8_LAS bf16x8*)(lds + PG8_SB(b, h) + boff + n * 2048 + k * 1024); } while (0)
; #define PG8_MMA(ai, bj, At, Bt) do { __builtin_amdgcn_s_setprio(1); _Pragma("unroll") for (int m = 0; m < 4; ++m) _Pragma("unroll") for (int n = 0; n < 2; ++n) _Pragma("unroll") for (int k = 0; k < 2; ++k) \
;         acc[ai][bj][m][n] = __builtin_amdgcn_mfma_f32_16x16x32_bf16(Bt[n][k], At[m][k], acc[ai][bj][m][n], 0, 0, 0); __builtin_amdgcn_s_setprio(0); } while (0)
; template <class Epi, class Sched, bool ALIGN_EPI = false, bool SP2 = false>
; __device__ __forceinline__ void gemm_phase(PG8_LAS unsigned char* lds, const Gemm g, const Sched& S, const Epi& E, int wid0) {
;     ...
;             PG8_LDB(B0, 0, 0); PG8_LDB(B1, 0, 1); PG8_SCHED; PG8_LDA(At, 0, 0); PG8_STAGE(PG8_SA(1, 1), a1 + hstepA, vA_);
;             PG8_WAIT_V(8); PG8_WAIT_L(0); PG8_BAR; PG8_MMA(0, 0, At, B0); PG8_MMA(0, 1, At, B1); PG8_BAR; PG8_SCHED;
;             PG8_LDA(At, 0, 1); PG8_STAGE(PG8_SB(0, 0), b2, vB_); PG8_STAGE(PG8_SB(0, 1), b2 + hstep, vB_); PG8_STAGE(PG8_SA(0, 0), a2, vA_);
;             PG8_WAIT_V(8); PG8_WAIT_L(0); PG8_BAR; PG8_MMA(1, 0, At, B0); PG8_MMA(1, 1, At, B1); PG8_BAR; PG8_SCHED;
;             PG8_LDB(B0, 1, 0); PG8_LDB(B1, 1, 1); PG8_SCHED; PG8_LDA(At, 1, 0); PG8_STAGE(PG8_SA(0, 1), a2 + hstepA, vA_);
;             PG8_WAIT_V(8); PG8_WAIT_L(0); PG8_BAR; PG8_MMA(0, 0, At, B0); PG8_MMA(0, 1, At, B1); PG8_BAR; PG8_SCHED;
;             PG8_LDA(At, 1, 1); PG8_STAGE(PG8_SB(1, 0), b3, vB_); PG8_STAGE(PG8_SB(1, 1), b3 + hstep, vB_); PG8_STAGE(PG8_SA(1, 0), a3, vA_);
;             PG8_WAIT_V(8); PG8_WAIT_L(0); PG8_BAR; PG8_MMA(1, 0, At, B0); PG8_MMA(1, 1, At, B1); PG8_BAR; PG8_SCHED;
.Lff1a_wd_0:
	s_waitcnt lgkmcnt(0)
	s_barrier
	s_setprio 1
	s_waitcnt lgkmcnt(0)
	v_mfma_f32_16x16x32_bf16 v[138:141], v[142:145], v[186:189], v[138:141]
	v_mfma_f32_16x16x32_bf16 v[134:137], v[150:153], v[186:189], v[134:137]
	v_mfma_f32_16x16x32_bf16 v[122:125], v[142:145], v[194:197], v[122:125]
	v_mfma_f32_16x16x32_bf16 v[118:121], v[150:153], v[194:197], v[118:121]
	v_mfma_f32_16x16x32_bf16 v[106:109], v[142:145], v[202:205], v[106:109]
	v_mfma_f32_16x16x32_bf16 v[102:105], v[150:153], v[202:205], v[102:105]
	v_mfma_f32_16x16x32_bf16 v[90:93], v[142:145], v[210:213], v[90:93]
	v_mfma_f32_16x16x32_bf16 v[86:89], v[150:153], v[210:213], v[86:89]
	v_mfma_f32_16x16x32_bf16 v[138:141], v[146:149], v[190:193], v[138:141]
	v_mfma_f32_16x16x32_bf16 v[134:137], v[154:157], v[190:193], v[134:137]
	v_mfma_f32_16x16x32_bf16 v[122:125], v[146:149], v[198:201], v[122:125]
	v_mfma_f32_16x16x32_bf16 v[118:121], v[154:157], v[198:201], v[118:121]
	v_mfma_f32_16x16x32_bf16 v[106:109], v[146:149], v[206:209], v[106:109]
	v_mfma_f32_16x16x32_bf16 v[102:105], v[154:157], v[206:209], v[102:105]
	v_mfma_f32_16x16x32_bf16 v[90:93], v[146:149], v[214:217], v[90:93]
	v_mfma_f32_16x16x32_bf16 v[86:89], v[154:157], v[214:217], v[86:89]
	s_setprio 0
	s_setprio 1
	v_mfma_f32_16x16x32_bf16 v[130:133], v[164:167], v[186:189], v[130:133]
	v_mfma_f32_16x16x32_bf16 v[126:129], v[178:181], v[186:189], v[126:129]
	v_mfma_f32_16x16x32_bf16 v[114:117], v[164:167], v[194:197], v[114:117]
	v_mfma_f32_16x16x32_bf16 v[110:113], v[178:181], v[194:197], v[110:113]
	v_mfma_f32_16x16x32_bf16 v[98:101], v[164:167], v[202:205], v[98:101]
	v_mfma_f32_16x16x32_bf16 v[94:97], v[178:181], v[202:205], v[94:97]
	v_mfma_f32_16x16x32_bf16 v[82:85], v[164:167], v[210:213], v[82:85]
	v_mfma_f32_16x16x32_bf16 v[78:81], v[178:181], v[210:213], v[78:81]
	v_mfma_f32_16x16x32_bf16 v[130:133], v[174:177], v[190:193], v[130:133]
	v_mfma_f32_16x16x32_bf16 v[126:129], v[182:185], v[190:193], v[126:129]
	v_mfma_f32_16x16x32_bf16 v[114:117], v[174:177], v[198:201], v[114:117]
	v_mfma_f32_16x16x32_bf16 v[110:113], v[182:185], v[198:201], v[110:113]
	s_add_i32 s62, s53, s27
	s_mov_b64 s[8:9], s[38:39]
	s_mov_b32 m0, s62
	v_mfma_f32_16x16x32_bf16 v[98:101], v[174:177], v[206:209], v[98:101]
	v_mfma_f32_16x16x32_bf16 v[94:97], v[182:185], v[206:209], v[94:97]
	v_mfma_f32_16x16x32_bf16 v[82:85], v[174:177], v[214:217], v[82:85]
	v_mfma_f32_16x16x32_bf16 v[78:81], v[182:185], v[214:217], v[78:81]
	s_setprio 0
	s_barrier
	ds_read_b128 v[186:189], v173 offset:16384
	ds_read_b128 v[190:193], v173 offset:17408
	ds_read_b128 v[194:197], v173 offset:18432
	ds_read_b128 v[198:201], v173 offset:19456
	ds_read_b128 v[202:205], v173 offset:20480
	ds_read_b128 v[206:209], v173 offset:21504
	ds_read_b128 v[210:213], v173 offset:22528
	ds_read_b128 v[214:217], v173 offset:23552
	s_nop 0
	global_load_lds_dwordx4 v219, s[8:9]
	s_add_i32 m0, s62, 0x2000
	s_nop 0
	global_load_lds_dwordx4 v221, s[8:9]
	s_add_u32 s8, s38, 0x10000
	s_addc_u32 s9, s39, 0
	s_add_i32 s62, s54, s27
	s_mov_b32 m0, s62
	s_nop 0
	global_load_lds_dwordx4 v219, s[8:9]
	s_add_i32 m0, s62, 0x2000
	s_nop 0
	global_load_lds_dwordx4 v221, s[8:9]
	s_mov_b64 s[8:9], s[40:41]
	s_mov_b32 m0, s29
	s_nop 0
	global_load_lds_dwordx4 v218, s[8:9]
	s_mov_b32 m0, s45
	s_nop 0
	global_load_lds_dwordx4 v220, s[8:9]
	s_cmp_lg_u32 s61, -2
	s_cbranch_scc1 .Lff1a_w8_1
	s_cmp_eq_u32 s56, 0
	s_cbranch_scc1 .Lff1a_w8_1
	s_waitcnt vmcnt(24)
	s_branch .Lff1a_wd_1

; #define PG8_STAGE(bufoff, gbase, voff) do { const char* gb_ = (const char*)(gbase); asm volatile("" : "+s"(gb_));     \
;         _Pragma("unroll") for (int _i = 0; _i < 2; ++_i) \
;         __builtin_amdgcn_global_load_lds((const unsigned*)(gb_ + (voff)[_i]), (PG8_LAS unsigned*)(lds + (bufoff) + ldsw + _i * 8192), 16, 0, 0); } while (0)
; #define PG8_LDA(dst, b, h) do { _Pragma("unroll") for (int m = 0; m < 4; ++m) _Pragma("unroll") for (int k = 0; k < 2; ++k) dst[m][k] = *(const PG8_LAS bf16x8*)(lds + PG8_SA(b, h) + aoff + m * 2048 + k * 1024); } while (0)
; #define PG8_LDB(dst, b, h) do { _Pragma("unroll") for (int n = 0; n < 2; ++n) _Pragma("unroll") for (int k = 0; k < 2; ++k) dst[n][k] = *(const PG8_LAS bf16x8*)(lds + PG8_SB(b, h) + boff + n * 2048 + k * 1024); } while (0)
; #define PG8_MMA(ai, bj, At, Bt) do { __builtin_amdgcn_s_setprio(1); _Pragma("unroll") for (int m = 0; m < 4; ++m) _Pragma("unroll") for (int n = 0; n < 2; ++n) _Pragma("unroll") for (int k = 0; k < 2; ++k) \
;         acc[ai][bj][m][n] = __builtin_amdgcn_mfma_f32_16x16x32_bf16(Bt[n][k], At[m][k], acc[ai][bj][m][n], 0, 0, 0); __builtin_amdgcn_s_setprio(0); } while (0)
; template <class Epi, class Sched, bool ALIGN_EPI = false, bool SP2 = false>
; __device__ __forceinline__ void gemm_phase(PG8_LAS unsigned char* lds, const Gemm g, const Sched& S, const Epi& E, int wid0) {
;     ...
;             PG8_LDB(B0, 0, 0); PG8_LDB(B1, 0, 1); PG8_SCHED; PG8_LDA(At, 0, 0); PG8_STAGE(PG8_SA(1, 1), a1 + hstepA, vA_);
;             PG8_WAIT_V(8); PG8_WAIT_L(0); PG8_BAR; PG8_MMA(0, 0, At, B0); PG8_MMA(0, 1, At, B1); PG8_BAR; PG8_SCHED;
;             PG8_LDA(At, 0, 1); PG8_STAGE(PG8_SB(0, 0), b2, vB_); PG8_STAGE(PG8_SB(0, 1), b2 + hstep, vB_); PG8_STAGE(PG8_SA(0, 0), a2, vA_);
;             PG8_WAIT_V(8); PG8_WAIT_L(0); PG8_BAR; PG8_MMA(1, 0, At, B0); PG8_MMA(1, 1, At, B1); PG8_BAR; PG8_SCHED;
;             PG8_LDB(B0, 1, 0); PG8_LDB(B1, 1, 1); PG8_SCHED; PG8_LDA(At, 1, 0); PG8_STAGE(PG8_SA(0, 1), a2 + hstepA, vA_);
;             PG8_WAIT_V(8); PG8_WAIT_L(0); PG8_BAR; PG8_MMA(0, 0, At, B0); PG8_MMA(0, 1, At, B1); PG8_BAR; PG8_SCHED;
;             PG8_LDA(At, 1, 1); PG8_STAGE(PG8_SB(1, 0), b3, vB_); PG8_STAGE(PG8_SB(1, 1), b3 + hstep, vB_); PG8_STAGE(PG8_SA(1, 0), a3, vA_);
;             PG8_WAIT_V(8); PG8_WAIT_L(0); PG8_BAR; PG8_MMA(1, 0, At, B0); PG8_MMA(1, 1, At, B1); PG8_BAR; PG8_SCHED;
.Lff1a_wd_1:
	s_waitcnt lgkmcnt(0)
	s_barrier
	s_setprio 1
	s_waitcnt lgkmcnt(0)
	v_mfma_f32_16x16x32_bf16 v[74:77], v[142:145], v[186:189], v[74:77]
	v_mfma_f32_16x16x32_bf16 v[70:73], v[150:153], v[186:189], v[70:73]
	v_mfma_f32_16x16x32_bf16 v[58:61], v[142:145], v[194:197], v[58:61]
	v_mfma_f32_16x16x32_bf16 v[54:57], v[150:153], v[194:197], v[54:57]
	v_mfma_f32_16x16x32_bf16 v[42:45], v[142:145], v[202:205], v[42:45]
	v_mfma_f32_16x16x32_bf16 v[38:41], v[150:153], v[202:205], v[38:41]
	v_mfma_f32_16x16x32_bf16 v[26:29], v[142:145], v[210:213], v[26:29]
	v_mfma_f32_16x16x32_bf16 v[22:25], v[150:153], v[210:213], v[22:25]
	v_mfma_f32_16x16x32_bf16 v[74:77], v[146:149], v[190:193], v[74:77]
	v_mfma_f32_16x16x32_bf16 v[70:73], v[154:157], v[190:193], v[70:73]
	v_mfma_f32_16x16x32_bf16 v[58:61], v[146:149], v[198:201], v[58:61]
	v_mfma_f32_16x16x32_bf16 v[54:57], v[154:157], v[198:201], v[54:57]
	v_mfma_f32_16x16x32_bf16 v[42:45], v[146:149], v[206:209], v[42:45]
	v_mfma_f32_16x16x32_bf16 v[38:41], v[154:157], v[206:209], v[38:41]
	v_mfma_f32_16x16x32_bf16 v[26:29], v[146:149], v[214:217], v[26:29]
	v_mfma_f32_16x16x32_bf16 v[22:25], v[154:157], v[214:217], v[22:25]
	s_setprio 0
	s_setprio 1
	v_mfma_f32_16x16x32_bf16 v[66:69], v[164:167], v[186:189], v[66:69]
	v_mfma_f32_16x16x32_bf16 v[62:65], v[178:181], v[186:189], v[62:65]
	v_mfma_f32_16x16x32_bf16 v[50:53], v[164:167], v[194:197], v[50:53]
	v_mfma_f32_16x16x32_bf16 v[46:49], v[178:181], v[194:197], v[46:49]
	v_mfma_f32_16x16x32_bf16 v[34:37], v[164:167], v[202:205], v[34:37]
	v_mfma_f32_16x16x32_bf16 v[30:33], v[178:181], v[202:205], v[30:33]
	v_mfma_f32_16x16x32_bf16 v[18:21], v[164:167], v[210:213], v[18:21]
	v_mfma_f32_16x16x32_bf16 v[14:17], v[178:181], v[210:213], v[14:17]
	v_mfma_f32_16x16x32_bf16 v[66:69], v[174:177], v[190:193], v[66:69]
	v_mfma_f32_16x16x32_bf16 v[62:65], v[182:185], v[190:193], v[62:65]
	v_mfma_f32_16x16x32_bf16 v[50:53], v[174:177], v[198:201], v[50:53]
	v_mfma_f32_16x16x32_bf16 v[46:49], v[182:185], v[198:201], v[46:49]
	s_add_i32 s62, 0, 0x18000
	s_add_i32 s63, 0, 0x1c000
	v_mfma_f32_16x16x32_bf16 v[34:37], v[174:177], v[206:209], v[34:37]
	v_mfma_f32_16x16x32_bf16 v[30:33], v[182:185], v[206:209], v[30:33]
	v_mfma_f32_16x16x32_bf16 v[18:21], v[174:177], v[214:217], v[18:21]
	v_mfma_f32_16x16x32_bf16 v[14:17], v[182:185], v[214:217], v[14:17]
	s_setprio 0
	s_barrier
	v_add_u32_e32 v154, s62, v9
	v_add_u32_e32 v182, s63, v9
	ds_read_b128 v[142:145], v154
	ds_read_b128 v[146:149], v154 offset:1024
	ds_read_b128 v[150:153], v154 offset:2048
	ds_read_b128 v[154:157], v154 offset:3072
	ds_read_b128 v[164:167], v182
	ds_read_b128 v[174:177], v182 offset:1024
	ds_read_b128 v[178:181], v182 offset:2048
	ds_read_b128 v[182:185], v182 offset:3072
	s_add_u32 s8, s40, 0x40000
	s_addc_u32 s9, s41, 0
	s_mov_b32 m0, s46
	ds_read_b128 v[186:189], v173 offset:32768
	ds_read_b128 v[190:193], v173 offset:33792
	ds_read_b128 v[194:197], v173 offset:34816
	ds_read_b128 v[198:201], v173 offset:35840
	ds_read_b128 v[202:205], v173 offset:36864
	ds_read_b128 v[206:209], v173 offset:37888
	ds_read_b128 v[210:213], v173 offset:38912
	ds_read_b128 v[214:217], v173 offset:39936
	s_nop 0
	global_load_lds_dwordx4 v218, s[8:9]
	s_mov_b32 m0, s47
	s_nop 0
	global_load_lds_dwordx4 v220, s[8:9]
	s_waitcnt vmcnt(8)
	s_waitcnt lgkmcnt(0)
	s_barrier
	s_setprio 1
	s_waitcnt lgkmcnt(0)
	v_mfma_f32_16x16x32_bf16 v[138:141], v[142:145], v[186:189], v[138:141]
	v_mfma_f32_16x16x32_bf16 v[134:137], v[150:153], v[186:189], v[134:137]
	v_mfma_f32_16x16x32_bf16 v[122:125], v[142:145], v[194:197], v[122:125]
	v_mfma_f32_16x16x32_bf16 v[118:121], v[150:153], v[194:197], v[118:121]
	v_mfma_f32_16x16x32_bf16 v[106:109], v[142:145], v[202:205], v[106:109]
	v_mfma_f32_16x16x32_bf16 v[102:105], v[150:153], v[202:205], v[102:105]
	v_mfma_f32_16x16x32_bf16 v[90:93], v[142:145], v[210:213], v[90:93]
	v_mfma_f32_16x16x32_bf16 v[86:89], v[150:153], v[210:213], v[86:89]
	v_mfma_f32_16x16x32_bf16 v[138:141], v[146:149], v[190:193], v[138:141]
	v_mfma_f32_16x16x32_bf16 v[134:137], v[154:157], v[190:193], v[134:137]
	v_mfma_f32_16x16x32_bf16 v[122:125], v[146:149], v[198:201], v[122:125]
	v_mfma_f32_16x16x32_bf16 v[118:121], v[154:157], v[198:201], v[118:121]
	v_mfma_f32_16x16x32_bf16 v[106:109], v[146:149], v[206:209], v[106:109]
	v_mfma_f32_16x16x32_bf16 v[102:105], v[154:157], v[206:209], v[102:105]
	v_mfma_f32_16x16x32_bf16 v[90:93], v[146:149], v[214:217], v[90:93]
	v_mfma_f32_16x16x32_bf16 v[86:89], v[154:157], v[214:217], v[86:89]
	s_setprio 0
	s_setprio 1
	v_mfma_f32_16x16x32_bf16 v[130:133], v[164:167], v[186:189], v[130:133]
	v_mfma_f32_16x16x32_bf16 v[126:129], v[178:181], v[186:189], v[126:129]
	v_mfma_f32_16x16x32_bf16 v[114:117], v[164:167], v[194:197], v[114:117]
	v_mfma_f32_16x16x32_bf16 v[110:113], v[178:181], v[194:197], v[110:113]
	v_mfma_f32_16x16x32_bf16 v[98:101], v[164:167], v[202:205], v[98:101]
	v_mfma_f32_16x16x32_bf16 v[94:97], v[178:181], v[202:205], v[94:97]
	v_mfma_f32_16x16x32_bf16 v[82:85], v[164:167], v[210:213], v[82:85]
	v_mfma_f32_16x16x32_bf16 v[78:81], v[178:181], v[210:213], v[78:81]
	v_mfma_f32_16x16x32_bf16 v[130:133], v[174:177], v[190:193], v[130:133]
	v_mfma_f32_16x16x32_bf16 v[126:129], v[182:185], v[190:193], v[126:129]
	v_mfma_f32_16x16x32_bf16 v[114:117], v[174:177], v[198:201], v[114:117]
	v_mfma_f32_16x16x32_bf16 v[110:113], v[182:185], v[198:201], v[110:113]
	s_add_u32 s8, s38, 0x80
	s_addc_u32 s9, s39, 0
	s_add_i32 s40, s62, s27
	s_mov_b32 m0, s40
	v_mfma_f32_16x16x32_bf16 v[98:101], v[174:177], v[206:209], v[98:101]
	v_mfma_f32_16x16x32_bf16 v[94:97], v[182:185], v[206:209], v[94:97]
	v_mfma_f32_16x16x32_bf16 v[82:85], v[174:177], v[214:217], v[82:85]
	v_mfma_f32_16x16x32_bf16 v[78:81], v[182:185], v[214:217], v[78:81]
	s_setprio 0
	s_barrier
; #define PG8_STAGE(bufoff, gbase, voff) do { const char* gb_ = (const char*)(gbase); asm volatile("" : "+s"(gb_));     \
;         _Pragma("unroll") for (int _i = 0; _i < 2; ++_i) \
;         __builtin_amdgcn_global_load_lds((const unsigned*)(gb_ + (voff)[_i]), (PG8_LAS unsigned*)(lds + (bufoff) + ldsw + _i * 8192), 16, 0, 0); } while (0)
; #define PG8_LDA(dst, b, h) do { _Pragma("unroll") for (int m = 0; m < 4; ++m) _Pragma("unroll") for (int k = 0; k < 2; ++k) dst[m][k] = *(const PG8_LAS bf16x8*)(lds + PG8_SA(b, h) + aoff + m * 2048 + k * 1024); } while (0)
; #define PG8_LDB(dst, b, h) do { _Pragma("unroll") for (int n = 0; n < 2; ++n) _Pragma("unroll") for (int k = 0; k < 2; ++k) dst[n][k] = *(const PG8_LAS bf16x8*)(lds + PG8_SB(b, h) + boff + n * 2048 + k * 1024); } while (0)
; #define PG8_WAIT_V(n) asm volatile("s_waitcnt vmcnt(" #n ")" ::: "memory")
; #define PG8_WAIT_L(n) asm volatile("s_waitcnt lgkmcnt(" #n ")" ::: "memory")
; #define PG8_BAR __builtin_amdgcn_s_barrier()
; #define PG8_SCHED __builtin_amdgcn_sched_barrier(0)
; template <class Epi, class Sched, bool ALIGN_EPI = false, bool SP2 = false>
; __device__ __forceinline__ void gemm_phase(PG8_LAS unsigned char* lds, const Gemm g, const Sched& S, const Epi& E, int wid0) {
;     ...
;             PG8_LDB(B0, 0, 0); PG8_LDB(B1, 0, 1); PG8_SCHED; PG8_LDA(At, 0, 0); PG8_STAGE(PG8_SA(1, 1), a1 + hstepA, vA_);
;             PG8_WAIT_V(8); PG8_WAIT_L(0); PG8_BAR; PG8_MMA(0, 0, At, B0); PG8_MMA(0, 1, At, B1); PG8_BAR; PG8_SCHED;
;             PG8_LDA(At, 0, 1); PG8_STAGE(PG8_SB(0, 0), b2, vB_); PG8_STAGE(PG8_SB(0, 1), b2 + hstep, vB_); PG8_STAGE(PG8_SA(0, 0), a2, vA_);
;             PG8_WAIT_V(8); PG8_WAIT_L(0); PG8_BAR; PG8_MMA(1, 0, At, B0); PG8_MMA(1, 1, At, B1); PG8_BAR; PG8_SCHED;
;             PG8_LDB(B0, 1, 0); PG8_LDB(B1, 1, 1); PG8_SCHED; PG8_LDA(At, 1, 0); PG8_STAGE(PG8_SA(0, 1), a2 + hstepA, vA_);
;             PG8_WAIT_V(8); PG8_WAIT_L(0); PG8_BAR; PG8_MMA(0, 0, At, B0); PG8_MMA(0, 1, At, B1); PG8_BAR; PG8_SCHED;
;             PG8_LDA(At, 1, 1); PG8_STAGE(PG8_SB(1, 0), b3, vB_); PG8_STAGE(PG8_SB(1, 1), b3 + hstep, vB_); PG8_STAGE(PG8_SA(1, 0), a3, vA_);
;             PG8_WAIT_V(8); PG8_WAIT_L(0); PG8_BAR; PG8_MMA(1, 0, At, B0); PG8_MMA(1, 1, At, B1); PG8_BAR; PG8_SCHED;
;     ...
;         if constexpr (ALIGN_EPI) { if (wr == 0) PG8_BAR; }
	ds_read_b128 v[186:189], v173 offset:49152
	ds_read_b128 v[190:193], v173 offset:50176
	ds_read_b128 v[194:197], v173 offset:51200
	ds_read_b128 v[198:201], v173 offset:52224
	ds_read_b128 v[202:205], v173 offset:53248
	ds_read_b128 v[206:209], v173 offset:54272
	ds_read_b128 v[210:213], v173 offset:55296
	ds_read_b128 v[214:217], v173 offset:56320
	s_nop 0
	global_load_lds_dwordx4 v219, s[8:9]
	s_add_i32 m0, s40, 0x2000
	s_nop 0
	global_load_lds_dwordx4 v221, s[8:9]
	s_add_u32 s8, s38, 0x10080
	s_addc_u32 s9, s39, 0
	s_add_i32 s38, s63, s27
	s_mov_b32 m0, s38
	s_nop 0
	global_load_lds_dwordx4 v219, s[8:9]
	s_add_i32 m0, s38, 0x2000
	s_nop 0
	global_load_lds_dwordx4 v221, s[8:9]
	s_mov_b32 m0, s50
	s_nop 0
	global_load_lds_dwordx4 v218, s[36:37]
	s_mov_b32 m0, s51
	s_nop 0
	global_load_lds_dwordx4 v220, s[36:37]
	s_waitcnt vmcnt(8)
	s_waitcnt lgkmcnt(0)
	s_barrier
	s_setprio 1
	s_waitcnt lgkmcnt(0)
	v_mfma_f32_16x16x32_bf16 v[74:77], v[142:145], v[186:189], v[74:77]
	v_mfma_f32_16x16x32_bf16 v[70:73], v[150:153], v[186:189], v[70:73]
	v_mfma_f32_16x16x32_bf16 v[58:61], v[142:145], v[194:197], v[58:61]
	v_mfma_f32_16x16x32_bf16 v[54:57], v[150:153], v[194:197], v[54:57]
	v_mfma_f32_16x16x32_bf16 v[42:45], v[142:145], v[202:205], v[42:45]
	v_mfma_f32_16x16x32_bf16 v[38:41], v[150:153], v[202:205], v[38:41]
	v_mfma_f32_16x16x32_bf16 v[26:29], v[142:145], v[210:213], v[26:29]
	v_mfma_f32_16x16x32_bf16 v[22:25], v[150:153], v[210:213], v[22:25]
	v_mfma_f32_16x16x32_bf16 v[74:77], v[146:149], v[190:193], v[74:77]
	v_mfma_f32_16x16x32_bf16 v[70:73], v[154:157], v[190:193], v[70:73]
	v_mfma_f32_16x16x32_bf16 v[58:61], v[146:149], v[198:201], v[58:61]
	v_mfma_f32_16x16x32_bf16 v[54:57], v[154:157], v[198:201], v[54:57]
	v_mfma_f32_16x16x32_bf16 v[42:45], v[146:149], v[206:209], v[42:45]
	v_mfma_f32_16x16x32_bf16 v[38:41], v[154:157], v[206:209], v[38:41]
	v_mfma_f32_16x16x32_bf16 v[26:29], v[146:149], v[214:217], v[26:29]
	v_mfma_f32_16x16x32_bf16 v[22:25], v[154:157], v[214:217], v[22:25]
	s_setprio 0
	s_setprio 1
	v_mfma_f32_16x16x32_bf16 v[66:69], v[164:167], v[186:189], v[66:69]
	v_mfma_f32_16x16x32_bf16 v[62:65], v[178:181], v[186:189], v[62:65]
	v_mfma_f32_16x16x32_bf16 v[50:53], v[164:167], v[194:197], v[50:53]
	v_mfma_f32_16x16x32_bf16 v[46:49], v[178:181], v[194:197], v[46:49]
	v_mfma_f32_16x16x32_bf16 v[34:37], v[164:167], v[202:205], v[34:37]
	v_mfma_f32_16x16x32_bf16 v[30:33], v[178:181], v[202:205], v[30:33]
	v_mfma_f32_16x16x32_bf16 v[18:21], v[164:167], v[210:213], v[18:21]
	v_mfma_f32_16x16x32_bf16 v[14:17], v[178:181], v[210:213], v[14:17]
	v_mfma_f32_16x16x32_bf16 v[66:69], v[174:177], v[190:193], v[66:69]
	v_mfma_f32_16x16x32_bf16 v[62:65], v[182:185], v[190:193], v[62:65]
	v_mfma_f32_16x16x32_bf16 v[50:53], v[174:177], v[198:201], v[50:53]
	v_mfma_f32_16x16x32_bf16 v[46:49], v[182:185], v[198:201], v[46:49]
	s_add_i32 s61, s61, 2
	s_add_u32 s59, s59, 0x100
	s_addc_u32 s60, s60, 0
	s_cmp_gt_u32 s61, 13
	s_mov_b64 s[8:9], s[34:35]
	v_mfma_f32_16x16x32_bf16 v[34:37], v[174:177], v[206:209], v[34:37]
	v_mfma_f32_16x16x32_bf16 v[30:33], v[182:185], v[206:209], v[30:33]
	v_mfma_f32_16x16x32_bf16 v[18:21], v[174:177], v[214:217], v[18:21]
	v_mfma_f32_16x16x32_bf16 v[14:17], v[182:185], v[214:217], v[14:17]
	s_setprio 0
	s_barrier
	s_cbranch_scc0 .LBB13_1074
	s_and_b64 vcc, exec, s[16:17]
	s_cbranch_vccz .LBB13_1077
	s_barrier

;     __device__ float mid(int row) const { return rg(row) / ra(row); }
; #define PG8_WAIT_V(n) asm volatile("s_waitcnt vmcnt(" #n ")" ::: "memory")
; #define PG8_WAIT_L(n) asm volatile("s_waitcnt lgkmcnt(" #n ")" ::: "memory")
; #define PG8_BAR __builtin_amdgcn_s_barrier()
; template <class Epi, class Sched, bool ALIGN_EPI = false, bool SP2 = false>
; __device__ __forceinline__ void gemm_phase(PG8_LAS unsigned char* lds, const Gemm g, const Sched& S, const Epi& E, int wid0) {
;     ...
;         const char* nA = has_next ? (const char*)g.A + (size_t)nxt.pm * tstepA : cA; const char* nB = has_next ? (const char*)g.Bt + (size_t)nxt.pn * tstep : cB;
; #pragma nounroll
;         for (int t = 0; t < nt; t += 2) {
;             const bool last = (t == nt - 2);
;             const char* a1 = cA + (size_t)(t + 1) * kstep;
;             const char* a2 = last ? nA : cA + (size_t)(t + 2) * kstep; const char* b2 = last ? nB : cB + (size_t)(t + 2) * kstep;
;             const char* a3 = a2 + kstep; const char* b3 = b2 + kstep;
;             if (last && has_next) S.a_ready(nxt);
;             if constexpr (Epi::HAS_MID) { if (t == Epi::MID_T) E.mid(acc, cur, wr, fr); }
;             unsigned vA_[2] = {voffA[0], voffA[1]}, vB_[2] = {voffB[0], voffB[1]};
;             asm volatile("" : "+v"(vA_[0]), "+v"(vA_[1]), "+v"(vB_[0]), "+v"(vB_[1]));
;             if constexpr (SP2) {
;             PG8_LDB(B0, 0, 0); PG8_LDB(B1, 0, 1); PG8_SCHED; PG8_LDA(At, 0, 0); PG8_STAGE(PG8_SA(1, 1), a1 + hstepA, vA_);
;             PG8_WAIT_V(8); PG8_WAIT_L(0); PG8_BAR; PG8_MMA(0, 0, At, B0); PG8_MMA(0, 1, At, B1); PG8_BAR; PG8_SCHED;
;             PG8_LDA(At, 0, 1); PG8_STAGE(PG8_SB(0, 0), b2, vB_); PG8_STAGE(PG8_SB(0, 1), b2 + hstep, vB_); PG8_STAGE(PG8_SA(0, 0), a2, vA_);
;             PG8_WAIT_V(8); PG8_WAIT_L(0); PG8_BAR; PG8_MMA(1, 0, At, B0); PG8_MMA(1, 1, At, B1); PG8_BAR; PG8_SCHED;
;             PG8_LDB(B0, 1, 0); PG8_LDB(B1, 1, 1); PG8_SCHED; PG8_LDA(At, 1, 0); PG8_STAGE(PG8_SA(0, 1), a2 + hstepA, vA_);
;             PG8_WAIT_V(8); PG8_WAIT_L(0); PG8_BAR; PG8_MMA(0, 0, At, B0); PG8_MMA(0, 1, At, B1); PG8_BAR; PG8_SCHED;
;             PG8_LDA(At, 1, 1); PG8_STAGE(PG8_SB(1, 0), b3, vB_); PG8_STAGE(PG8_SB(1, 1), b3 + hstep, vB_); PG8_STAGE(PG8_SA(1, 0), a3, vA_);
;             PG8_WAIT_V(8); PG8_WAIT_L(0); PG8_BAR; PG8_MMA(1, 0, At, B0); PG8_MMA(1, 1, At, B1); PG8_BAR; PG8_SCHED;
.LBB13_1187:
	v_mov_b32_e32 v181, v162
	v_mov_b32_e32 v202, v156
	v_mov_b32_e32 v203, v158
	v_mov_b32_e32 v204, v160
	ds_read_b128 v[128:131], v161
	ds_read_b128 v[132:135], v161 offset:1024
	ds_read_b128 v[136:139], v161 offset:2048
	ds_read_b128 v[140:143], v161 offset:3072
	ds_read_b128 v[144:147], v163
	ds_read_b128 v[148:151], v163 offset:1024
	ds_read_b128 v[152:155], v163 offset:2048
	ds_read_b128 v[164:167], v163 offset:3072
	s_add_u32 s34, s30, 0x100
	s_addc_u32 s35, s31, 0
	s_cmp_eq_u32 s60, 60
	s_cselect_b32 s40, s27, s34
	s_cselect_b32 s41, s17, s35
	s_cselect_b32 s38, s57, s58
	s_cselect_b32 s39, s19, s59
	s_add_u32 s36, s40, 0x80
	s_addc_u32 s37, s41, 0
	s_add_u32 s30, s30, 0x100080
	s_addc_u32 s31, s31, 0
	s_add_i32 m0, s29, 0xc000
	ds_read_b128 v[168:171], v180
	ds_read_b128 v[172:175], v180 offset:1024
	ds_read_b128 v[176:179], v180 offset:2048
	ds_read_b128 v[182:185], v180 offset:3072
	ds_read_b128 v[186:189], v180 offset:4096
	ds_read_b128 v[190:193], v180 offset:5120
	ds_read_b128 v[194:197], v180 offset:6144
	ds_read_b128 v[198:201], v180 offset:7168
	s_nop 0
	global_load_lds_dwordx4 v202, s[30:31]
	s_add_i32 m0, s29, 0xe000
	s_nop 0
	global_load_lds_dwordx4 v204, s[30:31]
	s_waitcnt vmcnt(8)
	s_waitcnt lgkmcnt(0)
	s_barrier
	s_setprio 1
	s_waitcnt lgkmcnt(0)
	v_mfma_f32_16x16x32_bf16 v[124:127], v[128:131], v[168:171], v[124:127]
	v_mfma_f32_16x16x32_bf16 v[120:123], v[136:139], v[168:171], v[120:123]
	v_mfma_f32_16x16x32_bf16 v[116:119], v[128:131], v[176:179], v[116:119]
	v_mfma_f32_16x16x32_bf16 v[112:115], v[136:139], v[176:179], v[112:115]
	v_mfma_f32_16x16x32_bf16 v[108:111], v[128:131], v[186:189], v[108:111]
	v_mfma_f32_16x16x32_bf16 v[104:107], v[136:139], v[186:189], v[104:107]
	v_mfma_f32_16x16x32_bf16 v[100:103], v[128:131], v[194:197], v[100:103]
	v_mfma_f32_16x16x32_bf16 v[96:99], v[136:139], v[194:197], v[96:99]
	v_mfma_f32_16x16x32_bf16 v[124:127], v[132:135], v[172:175], v[124:127]
	v_mfma_f32_16x16x32_bf16 v[120:123], v[140:143], v[172:175], v[120:123]
	v_mfma_f32_16x16x32_bf16 v[116:119], v[132:135], v[182:185], v[116:119]
	v_mfma_f32_16x16x32_bf16 v[112:115], v[140:143], v[182:185], v[112:115]
	v_mfma_f32_16x16x32_bf16 v[108:111], v[132:135], v[190:193], v[108:111]
	v_mfma_f32_16x16x32_bf16 v[104:107], v[140:143], v[190:193], v[104:107]
	v_mfma_f32_16x16x32_bf16 v[100:103], v[132:135], v[198:201], v[100:103]
	v_mfma_f32_16x16x32_bf16 v[96:99], v[140:143], v[198:201], v[96:99]
	s_setprio 0
	s_setprio 1
	v_mfma_f32_16x16x32_bf16 v[60:63], v[144:147], v[168:171], v[60:63]
	v_mfma_f32_16x16x32_bf16 v[56:59], v[152:155], v[168:171], v[56:59]
	v_mfma_f32_16x16x32_bf16 v[52:55], v[144:147], v[176:179], v[52:55]
	v_mfma_f32_16x16x32_bf16 v[48:51], v[152:155], v[176:179], v[48:51]
	v_mfma_f32_16x16x32_bf16 v[44:47], v[144:147], v[186:189], v[44:47]
	v_mfma_f32_16x16x32_bf16 v[40:43], v[152:155], v[186:189], v[40:43]
	v_mfma_f32_16x16x32_bf16 v[36:39], v[144:147], v[194:197], v[36:39]
	v_mfma_f32_16x16x32_bf16 v[32:35], v[152:155], v[194:197], v[32:35]
	v_mfma_f32_16x16x32_bf16 v[60:63], v[148:151], v[172:175], v[60:63]
	v_mfma_f32_16x16x32_bf16 v[56:59], v[164:167], v[172:175], v[56:59]
	v_mfma_f32_16x16x32_bf16 v[52:55], v[148:151], v[182:185], v[52:55]
	v_mfma_f32_16x16x32_bf16 v[48:51], v[164:167], v[182:185], v[48:51]
	s_add_i32 s61, s55, s33
	s_mov_b64 s[30:31], s[38:39]
	s_mov_b32 m0, s61
	v_mfma_f32_16x16x32_bf16 v[44:47], v[148:151], v[190:193], v[44:47]
	v_mfma_f32_16x16x32_bf16 v[40:43], v[164:167], v[190:193], v[40:43]
	v_mfma_f32_16x16x32_bf16 v[36:39], v[148:151], v[198:201], v[36:39]
	v_mfma_f32_16x16x32_bf16 v[32:35], v[164:167], v[198:201], v[32:35]
	s_setprio 0
	s_barrier
	ds_read_b128 v[168:171], v180 offset:16384
	ds_read_b128 v[172:175], v180 offset:17408
	ds_read_b128 v[176:179], v180 offset:18432
	ds_read_b128 v[182:185], v180 offset:19456
	ds_read_b128 v[186:189], v180 offset:20480
	ds_read_b128 v[190:193], v180 offset:21504
	ds_read_b128 v[194:197], v180 offset:22528
	ds_read_b128 v[198:201], v180 offset:23552
	s_nop 0
	global_load_lds_dwordx4 v203, s[30:31]
	s_add_i32 m0, s61, 0x2000
	s_nop 0
	global_load_lds_dwordx4 v181, s[30:31]
	s_add_u32 s30, s38, 0x100000
	s_addc_u32 s31, s39, 0
	s_add_i32 s61, s56, s33
	s_mov_b32 m0, s61
	s_nop 0
	global_load_lds_dwordx4 v203, s[30:31]
	s_add_i32 m0, s61, 0x2000
	s_nop 0
	global_load_lds_dwordx4 v181, s[30:31]
	s_mov_b64 s[30:31], s[40:41]
	s_mov_b32 m0, s29
	s_nop 0
	global_load_lds_dwordx4 v202, s[30:31]
	s_mov_b32 m0, s46
	s_nop 0
	global_load_lds_dwordx4 v204, s[30:31]
	s_waitcnt vmcnt(8)
	s_waitcnt lgkmcnt(0)
	s_barrier
; #define PG8_STAGE(bufoff, gbase, voff) do { const char* gb_ = (const char*)(gbase); asm volatile("" : "+s"(gb_));     \
;         _Pragma("unroll") for (int _i = 0; _i < 2; ++_i) \
;         __builtin_amdgcn_global_load_lds((const unsigned*)(gb_ + (voff)[_i]), (PG8_LAS unsigned*)(lds + (bufoff) + ldsw + _i * 8192), 16, 0, 0); } while (0)
; #define PG8_LDA(dst, b, h) do { _Pragma("unroll") for (int m = 0; m < 4; ++m) _Pragma("unroll") for (int k = 0; k < 2; ++k) dst[m][k] = *(const PG8_LAS bf16x8*)(lds + PG8_SA(b, h) + aoff + m * 2048 + k * 1024); } while (0)
; #define PG8_LDB(dst, b, h) do { _Pragma("unroll") for (int n = 0; n < 2; ++n) _Pragma("unroll") for (int k = 0; k < 2; ++k) dst[n][k] = *(const PG8_LAS bf16x8*)(lds + PG8_SB(b, h) + boff + n * 2048 + k * 1024); } while (0)
; #define PG8_MMA(ai, bj, At, Bt) do { __builtin_amdgcn_s_setprio(1); _Pragma("unroll") for (int m = 0; m < 4; ++m) _Pragma("unroll") for (int n = 0; n < 2; ++n) _Pragma("unroll") for (int k = 0; k < 2; ++k) \
;         acc[ai][bj][m][n] = __builtin_amdgcn_mfma_f32_16x16x32_bf16(Bt[n][k], At[m][k], acc[ai][bj][m][n], 0, 0, 0); __builtin_amdgcn_s_setprio(0); } while (0)
; template <class Epi, class Sched, bool ALIGN_EPI = false, bool SP2 = false>
; __device__ __forceinline__ void gemm_phase(PG8_LAS unsigned char* lds, const Gemm g, const Sched& S, const Epi& E, int wid0) {
;     ...
;             PG8_LDB(B0, 0, 0); PG8_LDB(B1, 0, 1); PG8_SCHED; PG8_LDA(At, 0, 0); PG8_STAGE(PG8_SA(1, 1), a1 + hstepA, vA_);
;             PG8_WAIT_V(8); PG8_WAIT_L(0); PG8_BAR; PG8_MMA(0, 0, At, B0); PG8_MMA(0, 1, At, B1); PG8_BAR; PG8_SCHED;
;             PG8_LDA(At, 0, 1); PG8_STAGE(PG8_SB(0, 0), b2, vB_); PG8_STAGE(PG8_SB(0, 1), b2 + hstep, vB_); PG8_STAGE(PG8_SA(0, 0), a2, vA_);
;             PG8_WAIT_V(8); PG8_WAIT_L(0); PG8_BAR; PG8_MMA(1, 0, At, B0); PG8_MMA(1, 1, At, B1); PG8_BAR; PG8_SCHED;
;             PG8_LDB(B0, 1, 0); PG8_LDB(B1, 1, 1); PG8_SCHED; PG8_LDA(At, 1, 0); PG8_STAGE(PG8_SA(0, 1), a2 + hstepA, vA_);
;             PG8_WAIT_V(8); PG8_WAIT_L(0); PG8_BAR; PG8_MMA(0, 0, At, B0); PG8_MMA(0, 1, At, B1); PG8_BAR; PG8_SCHED;
;             PG8_LDA(At, 1, 1); PG8_STAGE(PG8_SB(1, 0), b3, vB_); PG8_STAGE(PG8_SB(1, 1), b3 + hstep, vB_); PG8_STAGE(PG8_SA(1, 0), a3, vA_);
;             PG8_WAIT_V(8); PG8_WAIT_L(0); PG8_BAR; PG8_MMA(1, 0, At, B0); PG8_MMA(1, 1, At, B1); PG8_BAR; PG8_SCHED;
	s_setprio 1
	s_waitcnt lgkmcnt(0)
	v_mfma_f32_16x16x32_bf16 v[92:95], v[128:131], v[168:171], v[92:95]
	v_mfma_f32_16x16x32_bf16 v[88:91], v[136:139], v[168:171], v[88:91]
	v_mfma_f32_16x16x32_bf16 v[84:87], v[128:131], v[176:179], v[84:87]
	v_mfma_f32_16x16x32_bf16 v[80:83], v[136:139], v[176:179], v[80:83]
	v_mfma_f32_16x16x32_bf16 v[76:79], v[128:131], v[186:189], v[76:79]
	v_mfma_f32_16x16x32_bf16 v[72:75], v[136:139], v[186:189], v[72:75]
	v_mfma_f32_16x16x32_bf16 v[68:71], v[128:131], v[194:197], v[68:71]
	v_mfma_f32_16x16x32_bf16 v[64:67], v[136:139], v[194:197], v[64:67]
	v_mfma_f32_16x16x32_bf16 v[92:95], v[132:135], v[172:175], v[92:95]
	v_mfma_f32_16x16x32_bf16 v[88:91], v[140:143], v[172:175], v[88:91]
	v_mfma_f32_16x16x32_bf16 v[84:87], v[132:135], v[182:185], v[84:87]
	v_mfma_f32_16x16x32_bf16 v[80:83], v[140:143], v[182:185], v[80:83]
	v_mfma_f32_16x16x32_bf16 v[76:79], v[132:135], v[190:193], v[76:79]
	v_mfma_f32_16x16x32_bf16 v[72:75], v[140:143], v[190:193], v[72:75]
	v_mfma_f32_16x16x32_bf16 v[68:71], v[132:135], v[198:201], v[68:71]
	v_mfma_f32_16x16x32_bf16 v[64:67], v[140:143], v[198:201], v[64:67]
	s_setprio 0
	s_setprio 1
	v_mfma_f32_16x16x32_bf16 v[28:31], v[144:147], v[168:171], v[28:31]
	v_mfma_f32_16x16x32_bf16 v[24:27], v[152:155], v[168:171], v[24:27]
	v_mfma_f32_16x16x32_bf16 v[20:23], v[144:147], v[176:179], v[20:23]
	v_mfma_f32_16x16x32_bf16 v[16:19], v[152:155], v[176:179], v[16:19]
	v_mfma_f32_16x16x32_bf16 v[12:15], v[144:147], v[186:189], v[12:15]
	v_mfma_f32_16x16x32_bf16 v[8:11], v[152:155], v[186:189], v[8:11]
	v_mfma_f32_16x16x32_bf16 v[4:7], v[144:147], v[194:197], v[4:7]
	v_mfma_f32_16x16x32_bf16 v[0:3], v[152:155], v[194:197], v[0:3]
	v_mfma_f32_16x16x32_bf16 v[28:31], v[148:151], v[172:175], v[28:31]
	v_mfma_f32_16x16x32_bf16 v[24:27], v[164:167], v[172:175], v[24:27]
	v_mfma_f32_16x16x32_bf16 v[20:23], v[148:151], v[182:185], v[20:23]
	v_mfma_f32_16x16x32_bf16 v[16:19], v[164:167], v[182:185], v[16:19]
	s_add_i32 s61, 0, 0x18000
	s_add_i32 s62, 0, 0x1c000
	v_mfma_f32_16x16x32_bf16 v[12:15], v[148:151], v[190:193], v[12:15]
	v_mfma_f32_16x16x32_bf16 v[8:11], v[164:167], v[190:193], v[8:11]
	v_mfma_f32_16x16x32_bf16 v[4:7], v[148:151], v[198:201], v[4:7]
	v_mfma_f32_16x16x32_bf16 v[0:3], v[164:167], v[198:201], v[0:3]
	s_setprio 0
	s_barrier
	v_add_u32_e32 v140, s61, v157
	v_add_u32_e32 v164, s62, v157
	ds_read_b128 v[128:131], v140
	ds_read_b128 v[132:135], v140 offset:1024
	ds_read_b128 v[136:139], v140 offset:2048
	ds_read_b128 v[140:143], v140 offset:3072
	ds_read_b128 v[144:147], v164
	ds_read_b128 v[148:151], v164 offset:1024
	ds_read_b128 v[152:155], v164 offset:2048
	ds_read_b128 v[164:167], v164 offset:3072
	s_add_u32 s30, s40, 0x100000
	s_addc_u32 s31, s41, 0
	s_mov_b32 m0, s47
	ds_read_b128 v[168:171], v180 offset:32768
	ds_read_b128 v[172:175], v180 offset:33792
	ds_read_b128 v[176:179], v180 offset:34816
	ds_read_b128 v[182:185], v180 offset:35840
	ds_read_b128 v[186:189], v180 offset:36864
	ds_read_b128 v[190:193], v180 offset:37888
	ds_read_b128 v[194:197], v180 offset:38912
	ds_read_b128 v[198:201], v180 offset:39936
	s_nop 0
	global_load_lds_dwordx4 v202, s[30:31]
	s_mov_b32 m0, s48
	s_nop 0
	global_load_lds_dwordx4 v204, s[30:31]
	s_waitcnt vmcnt(8)
	s_waitcnt lgkmcnt(0)
	s_barrier
	s_setprio 1
	s_waitcnt lgkmcnt(0)
	v_mfma_f32_16x16x32_bf16 v[124:127], v[128:131], v[168:171], v[124:127]
	v_mfma_f32_16x16x32_bf16 v[120:123], v[136:139], v[168:171], v[120:123]
	v_mfma_f32_16x16x32_bf16 v[116:119], v[128:131], v[176:179], v[116:119]
	v_mfma_f32_16x16x32_bf16 v[112:115], v[136:139], v[176:179], v[112:115]
	v_mfma_f32_16x16x32_bf16 v[108:111], v[128:131], v[186:189], v[108:111]
	v_mfma_f32_16x16x32_bf16 v[104:107], v[136:139], v[186:189], v[104:107]
	v_mfma_f32_16x16x32_bf16 v[100:103], v[128:131], v[194:197], v[100:103]
	v_mfma_f32_16x16x32_bf16 v[96:99], v[136:139], v[194:197], v[96:99]
	v_mfma_f32_16x16x32_bf16 v[124:127], v[132:135], v[172:175], v[124:127]
	v_mfma_f32_16x16x32_bf16 v[120:123], v[140:143], v[172:175], v[120:123]
	v_mfma_f32_16x16x32_bf16 v[116:119], v[132:135], v[182:185], v[116:119]
	v_mfma_f32_16x16x32_bf16 v[112:115], v[140:143], v[182:185], v[112:115]
	v_mfma_f32_16x16x32_bf16 v[108:111], v[132:135], v[190:193], v[108:111]
	v_mfma_f32_16x16x32_bf16 v[104:107], v[140:143], v[190:193], v[104:107]
	v_mfma_f32_16x16x32_bf16 v[100:103], v[132:135], v[198:201], v[100:103]
	v_mfma_f32_16x16x32_bf16 v[96:99], v[140:143], v[198:201], v[96:99]
	s_setprio 0
	s_setprio 1
	v_mfma_f32_16x16x32_bf16 v[60:63], v[144:147], v[168:171], v[60:63]
	v_mfma_f32_16x16x32_bf16 v[56:59], v[152:155], v[168:171], v[56:59]
	v_mfma_f32_16x16x32_bf16 v[52:55], v[144:147], v[176:179], v[52:55]
	v_mfma_f32_16x16x32_bf16 v[48:51], v[152:155], v[176:179], v[48:51]
	v_mfma_f32_16x16x32_bf16 v[44:47], v[144:147], v[186:189], v[44:47]
	v_mfma_f32_16x16x32_bf16 v[40:43], v[152:155], v[186:189], v[40:43]
	v_mfma_f32_16x16x32_bf16 v[36:39], v[144:147], v[194:197], v[36:39]
	v_mfma_f32_16x16x32_bf16 v[32:35], v[152:155], v[194:197], v[32:35]
	v_mfma_f32_16x16x32_bf16 v[60:63], v[148:151], v[172:175], v[60:63]
	v_mfma_f32_16x16x32_bf16 v[56:59], v[164:167], v[172:175], v[56:59]
	v_mfma_f32_16x16x32_bf16 v[52:55], v[148:151], v[182:185], v[52:55]
	v_mfma_f32_16x16x32_bf16 v[48:51], v[164:167], v[182:185], v[48:51]
	s_add_u32 s30, s38, 0x80
	s_addc_u32 s31, s39, 0
	s_add_i32 s40, s61, s33
	s_mov_b32 m0, s40
	v_mfma_f32_16x16x32_bf16 v[44:47], v[148:151], v[190:193], v[44:47]
	v_mfma_f32_16x16x32_bf16 v[40:43], v[164:167], v[190:193], v[40:43]
	v_mfma_f32_16x16x32_bf16 v[36:39], v[148:151], v[198:201], v[36:39]
	v_mfma_f32_16x16x32_bf16 v[32:35], v[164:167], v[198:201], v[32:35]
	s_setprio 0
	s_barrier
; #define PG8_STAGE(bufoff, gbase, voff) do { const char* gb_ = (const char*)(gbase); asm volatile("" : "+s"(gb_));     \
;         _Pragma("unroll") for (int _i = 0; _i < 2; ++_i) \
;         __builtin_amdgcn_global_load_lds((const unsigned*)(gb_ + (voff)[_i]), (PG8_LAS unsigned*)(lds + (bufoff) + ldsw + _i * 8192), 16, 0, 0); } while (0)
; #define PG8_LDA(dst, b, h) do { _Pragma("unroll") for (int m = 0; m < 4; ++m) _Pragma("unroll") for (int k = 0; k < 2; ++k) dst[m][k] = *(const PG8_LAS bf16x8*)(lds + PG8_SA(b, h) + aoff + m * 2048 + k * 1024); } while (0)
; #define PG8_LDB(dst, b, h) do { _Pragma("unroll") for (int n = 0; n < 2; ++n) _Pragma("unroll") for (int k = 0; k < 2; ++k) dst[n][k] = *(const PG8_LAS bf16x8*)(lds + PG8_SB(b, h) + boff + n * 2048 + k * 1024); } while (0)
; #define PG8_WAIT_V(n) asm volatile("s_waitcnt vmcnt(" #n ")" ::: "memory")
; #define PG8_WAIT_L(n) asm volatile("s_waitcnt lgkmcnt(" #n ")" ::: "memory")
; #define PG8_BAR __builtin_amdgcn_s_barrier()
; #define PG8_SCHED __builtin_amdgcn_sched_barrier(0)
; template <class Epi, class Sched, bool ALIGN_EPI = false, bool SP2 = false>
; __device__ __forceinline__ void gemm_phase(PG8_LAS unsigned char* lds, const Gemm g, const Sched& S, const Epi& E, int wid0) {
;     ...
;             PG8_LDB(B0, 0, 0); PG8_LDB(B1, 0, 1); PG8_SCHED; PG8_LDA(At, 0, 0); PG8_STAGE(PG8_SA(1, 1), a1 + hstepA, vA_);
;             PG8_WAIT_V(8); PG8_WAIT_L(0); PG8_BAR; PG8_MMA(0, 0, At, B0); PG8_MMA(0, 1, At, B1); PG8_BAR; PG8_SCHED;
;             PG8_LDA(At, 0, 1); PG8_STAGE(PG8_SB(0, 0), b2, vB_); PG8_STAGE(PG8_SB(0, 1), b2 + hstep, vB_); PG8_STAGE(PG8_SA(0, 0), a2, vA_);
;             PG8_WAIT_V(8); PG8_WAIT_L(0); PG8_BAR; PG8_MMA(1, 0, At, B0); PG8_MMA(1, 1, At, B1); PG8_BAR; PG8_SCHED;
;             PG8_LDB(B0, 1, 0); PG8_LDB(B1, 1, 1); PG8_SCHED; PG8_LDA(At, 1, 0); PG8_STAGE(PG8_SA(0, 1), a2 + hstepA, vA_);
;             PG8_WAIT_V(8); PG8_WAIT_L(0); PG8_BAR; PG8_MMA(0, 0, At, B0); PG8_MMA(0, 1, At, B1); PG8_BAR; PG8_SCHED;
;             PG8_LDA(At, 1, 1); PG8_STAGE(PG8_SB(1, 0), b3, vB_); PG8_STAGE(PG8_SB(1, 1), b3 + hstep, vB_); PG8_STAGE(PG8_SA(1, 0), a3, vA_);
;             PG8_WAIT_V(8); PG8_WAIT_L(0); PG8_BAR; PG8_MMA(1, 0, At, B0); PG8_MMA(1, 1, At, B1); PG8_BAR; PG8_SCHED;
;     ...
;         if constexpr (ALIGN_EPI) { if (wr == 0) PG8_BAR; }
	ds_read_b128 v[168:171], v180 offset:49152
	ds_read_b128 v[172:175], v180 offset:50176
	ds_read_b128 v[176:179], v180 offset:51200
	ds_read_b128 v[182:185], v180 offset:52224
	ds_read_b128 v[186:189], v180 offset:53248
	ds_read_b128 v[190:193], v180 offset:54272
	ds_read_b128 v[194:197], v180 offset:55296
	ds_read_b128 v[198:201], v180 offset:56320
	s_nop 0
	global_load_lds_dwordx4 v203, s[30:31]
	s_add_i32 m0, s40, 0x2000
	s_nop 0
	global_load_lds_dwordx4 v181, s[30:31]
	s_add_u32 s30, s38, 0x100080
	s_addc_u32 s31, s39, 0
	s_add_i32 s38, s62, s33
	s_mov_b32 m0, s38
	s_nop 0
	global_load_lds_dwordx4 v203, s[30:31]
	s_add_i32 m0, s38, 0x2000
	s_nop 0
	global_load_lds_dwordx4 v181, s[30:31]
	s_mov_b32 m0, s53
	s_nop 0
	global_load_lds_dwordx4 v202, s[36:37]
	s_mov_b32 m0, s54
	s_nop 0
	global_load_lds_dwordx4 v204, s[36:37]
	s_waitcnt vmcnt(8)
	s_waitcnt lgkmcnt(0)
	s_barrier
	s_setprio 1
	s_waitcnt lgkmcnt(0)
	v_mfma_f32_16x16x32_bf16 v[92:95], v[128:131], v[168:171], v[92:95]
	v_mfma_f32_16x16x32_bf16 v[88:91], v[136:139], v[168:171], v[88:91]
	v_mfma_f32_16x16x32_bf16 v[84:87], v[128:131], v[176:179], v[84:87]
	v_mfma_f32_16x16x32_bf16 v[80:83], v[136:139], v[176:179], v[80:83]
	v_mfma_f32_16x16x32_bf16 v[76:79], v[128:131], v[186:189], v[76:79]
	v_mfma_f32_16x16x32_bf16 v[72:75], v[136:139], v[186:189], v[72:75]
	v_mfma_f32_16x16x32_bf16 v[68:71], v[128:131], v[194:197], v[68:71]
	v_mfma_f32_16x16x32_bf16 v[64:67], v[136:139], v[194:197], v[64:67]
	v_mfma_f32_16x16x32_bf16 v[92:95], v[132:135], v[172:175], v[92:95]
	v_mfma_f32_16x16x32_bf16 v[88:91], v[140:143], v[172:175], v[88:91]
	v_mfma_f32_16x16x32_bf16 v[84:87], v[132:135], v[182:185], v[84:87]
	v_mfma_f32_16x16x32_bf16 v[80:83], v[140:143], v[182:185], v[80:83]
	v_mfma_f32_16x16x32_bf16 v[76:79], v[132:135], v[190:193], v[76:79]
	v_mfma_f32_16x16x32_bf16 v[72:75], v[140:143], v[190:193], v[72:75]
	v_mfma_f32_16x16x32_bf16 v[68:71], v[132:135], v[198:201], v[68:71]
	v_mfma_f32_16x16x32_bf16 v[64:67], v[140:143], v[198:201], v[64:67]
	s_setprio 0
	s_setprio 1
	v_mfma_f32_16x16x32_bf16 v[28:31], v[144:147], v[168:171], v[28:31]
	v_mfma_f32_16x16x32_bf16 v[24:27], v[152:155], v[168:171], v[24:27]
	v_mfma_f32_16x16x32_bf16 v[20:23], v[144:147], v[176:179], v[20:23]
	v_mfma_f32_16x16x32_bf16 v[16:19], v[152:155], v[176:179], v[16:19]
	v_mfma_f32_16x16x32_bf16 v[12:15], v[144:147], v[186:189], v[12:15]
	v_mfma_f32_16x16x32_bf16 v[8:11], v[152:155], v[186:189], v[8:11]
	v_mfma_f32_16x16x32_bf16 v[4:7], v[144:147], v[194:197], v[4:7]
	v_mfma_f32_16x16x32_bf16 v[0:3], v[152:155], v[194:197], v[0:3]
	v_mfma_f32_16x16x32_bf16 v[28:31], v[148:151], v[172:175], v[28:31]
	v_mfma_f32_16x16x32_bf16 v[24:27], v[164:167], v[172:175], v[24:27]
	v_mfma_f32_16x16x32_bf16 v[20:23], v[148:151], v[182:185], v[20:23]
	v_mfma_f32_16x16x32_bf16 v[16:19], v[164:167], v[182:185], v[16:19]
	s_add_i32 s60, s60, 2
	s_add_u32 s58, s58, 0x100
	s_addc_u32 s59, s59, 0
	s_cmp_gt_u32 s60, 61
	s_mov_b64 s[30:31], s[34:35]
	v_mfma_f32_16x16x32_bf16 v[12:15], v[148:151], v[190:193], v[12:15]
	v_mfma_f32_16x16x32_bf16 v[8:11], v[164:167], v[190:193], v[8:11]
	v_mfma_f32_16x16x32_bf16 v[4:7], v[148:151], v[198:201], v[4:7]
	v_mfma_f32_16x16x32_bf16 v[0:3], v[164:167], v[198:201], v[0:3]
	s_setprio 0
	s_barrier
	s_cbranch_scc0 .LBB13_1187
	s_and_b64 vcc, exec, s[14:15]
	s_cbranch_vccz .LBB13_1190
	s_barrier

;     __device__ float mid(int row) const { return rg(row) / ra(row); }
; #define PG8_WAIT_V(n) asm volatile("s_waitcnt vmcnt(" #n ")" ::: "memory")
; #define PG8_WAIT_L(n) asm volatile("s_waitcnt lgkmcnt(" #n ")" ::: "memory")
; #define PG8_BAR __builtin_amdgcn_s_barrier()
; template <class Epi, class Sched, bool ALIGN_EPI = false, bool SP2 = false>
; __device__ __forceinline__ void gemm_phase(PG8_LAS unsigned char* lds, const Gemm g, const Sched& S, const Epi& E, int wid0) {
;     ...
;         const char* nA = has_next ? (const char*)g.A + (size_t)nxt.pm * tstepA : cA; const char* nB = has_next ? (const char*)g.Bt + (size_t)nxt.pn * tstep : cB;
; #pragma nounroll
;         for (int t = 0; t < nt; t += 2) {
;             const bool last = (t == nt - 2);
;             const char* a1 = cA + (size_t)(t + 1) * kstep;
;             const char* a2 = last ? nA : cA + (size_t)(t + 2) * kstep; const char* b2 = last ? nB : cB + (size_t)(t + 2) * kstep;
;             const char* a3 = a2 + kstep; const char* b3 = b2 + kstep;
;             if (last && has_next) S.a_ready(nxt);
;             if constexpr (Epi::HAS_MID) { if (t == Epi::MID_T) E.mid(acc, cur, wr, fr); }
;             unsigned vA_[2] = {voffA[0], voffA[1]}, vB_[2] = {voffB[0], voffB[1]};
;             asm volatile("" : "+v"(vA_[0]), "+v"(vA_[1]), "+v"(vB_[0]), "+v"(vB_[1]));
;             if constexpr (SP2) {
;             PG8_LDB(B0, 0, 0); PG8_LDB(B1, 0, 1); PG8_SCHED; PG8_LDA(At, 0, 0); PG8_STAGE(PG8_SA(1, 1), a1 + hstepA, vA_);
;             PG8_WAIT_V(8); PG8_WAIT_L(0); PG8_BAR; PG8_MMA(0, 0, At, B0); PG8_MMA(0, 1, At, B1); PG8_BAR; PG8_SCHED;
;             PG8_LDA(At, 0, 1); PG8_STAGE(PG8_SB(0, 0), b2, vB_); PG8_STAGE(PG8_SB(0, 1), b2 + hstep, vB_); PG8_STAGE(PG8_SA(0, 0), a2, vA_);
;             PG8_WAIT_V(8); PG8_WAIT_L(0); PG8_BAR; PG8_MMA(1, 0, At, B0); PG8_MMA(1, 1, At, B1); PG8_BAR; PG8_SCHED;
;             PG8_LDB(B0, 1, 0); PG8_LDB(B1, 1, 1); PG8_SCHED; PG8_LDA(At, 1, 0); PG8_STAGE(PG8_SA(0, 1), a2 + hstepA, vA_);
;             PG8_WAIT_V(8); PG8_WAIT_L(0); PG8_BAR; PG8_MMA(0, 0, At, B0); PG8_MMA(0, 1, At, B1); PG8_BAR; PG8_SCHED;
;             PG8_LDA(At, 1, 1); PG8_STAGE(PG8_SB(1, 0), b3, vB_); PG8_STAGE(PG8_SB(1, 1), b3 + hstep, vB_); PG8_STAGE(PG8_SA(1, 0), a3, vA_);
;             PG8_WAIT_V(8); PG8_WAIT_L(0); PG8_BAR; PG8_MMA(1, 0, At, B0); PG8_MMA(1, 1, At, B1); PG8_BAR; PG8_SCHED;
.LBB13_1336:
	v_mov_b32_e32 v8, v178
	v_mov_b32_e32 v220, v174
	v_mov_b32_e32 v221, v200
	v_mov_b32_e32 v222, v176
	ds_read_b128 v[82:85], v201
	ds_read_b128 v[90:93], v201 offset:1024
	ds_read_b128 v[94:97], v201 offset:2048
	ds_read_b128 v[102:105], v201 offset:3072
	ds_read_b128 v[158:161], v202
	ds_read_b128 v[162:165], v202 offset:1024
	ds_read_b128 v[166:169], v202 offset:2048
	ds_read_b128 v[170:173], v202 offset:3072
	s_add_u32 s8, s2, 0x100
	s_addc_u32 s9, s3, 0
	s_cmp_eq_u32 s82, 12
	s_cselect_b32 s58, s78, s8
	s_cselect_b32 s59, s47, s9
	s_cselect_b32 s12, s79, s80
	s_cselect_b32 s13, s49, s81
	s_add_u32 s10, s58, 0x80
	s_addc_u32 s11, s59, 0
	s_add_u32 s2, s2, 0x40080
	s_addc_u32 s3, s3, 0
	s_add_i32 m0, s57, 0xc000
	ds_read_b128 v[180:183], v203
	ds_read_b128 v[184:187], v203 offset:1024
	ds_read_b128 v[188:191], v203 offset:2048
	ds_read_b128 v[192:195], v203 offset:3072
	ds_read_b128 v[204:207], v203 offset:4096
	ds_read_b128 v[208:211], v203 offset:5120
	ds_read_b128 v[212:215], v203 offset:6144
	ds_read_b128 v[216:219], v203 offset:7168
	s_nop 0
	global_load_lds_dwordx4 v220, s[2:3]
	s_add_i32 m0, s57, 0xe000
	s_nop 0
	global_load_lds_dwordx4 v222, s[2:3]
	s_waitcnt vmcnt(8)
	s_waitcnt lgkmcnt(0)
	s_barrier
	s_setprio 1
	s_waitcnt lgkmcnt(0)
	v_mfma_f32_16x16x32_bf16 v[154:157], v[82:85], v[180:183], v[154:157]
	v_mfma_f32_16x16x32_bf16 v[150:153], v[94:97], v[180:183], v[150:153]
	v_mfma_f32_16x16x32_bf16 v[138:141], v[82:85], v[188:191], v[138:141]
	v_mfma_f32_16x16x32_bf16 v[134:137], v[94:97], v[188:191], v[134:137]
	v_mfma_f32_16x16x32_bf16 v[122:125], v[82:85], v[204:207], v[122:125]
	v_mfma_f32_16x16x32_bf16 v[118:121], v[94:97], v[204:207], v[118:121]
	v_mfma_f32_16x16x32_bf16 v[106:109], v[82:85], v[212:215], v[106:109]
	v_mfma_f32_16x16x32_bf16 v[98:101], v[94:97], v[212:215], v[98:101]
	v_mfma_f32_16x16x32_bf16 v[154:157], v[90:93], v[184:187], v[154:157]
	v_mfma_f32_16x16x32_bf16 v[150:153], v[102:105], v[184:187], v[150:153]
	v_mfma_f32_16x16x32_bf16 v[138:141], v[90:93], v[192:195], v[138:141]
	v_mfma_f32_16x16x32_bf16 v[134:137], v[102:105], v[192:195], v[134:137]
	v_mfma_f32_16x16x32_bf16 v[122:125], v[90:93], v[208:211], v[122:125]
	v_mfma_f32_16x16x32_bf16 v[118:121], v[102:105], v[208:211], v[118:121]
	v_mfma_f32_16x16x32_bf16 v[106:109], v[90:93], v[216:219], v[106:109]
	v_mfma_f32_16x16x32_bf16 v[98:101], v[102:105], v[216:219], v[98:101]
	s_setprio 0
	s_setprio 1
	v_mfma_f32_16x16x32_bf16 v[146:149], v[158:161], v[180:183], v[146:149]
	v_mfma_f32_16x16x32_bf16 v[142:145], v[166:169], v[180:183], v[142:145]
	v_mfma_f32_16x16x32_bf16 v[130:133], v[158:161], v[188:191], v[130:133]
	v_mfma_f32_16x16x32_bf16 v[126:129], v[166:169], v[188:191], v[126:129]
	v_mfma_f32_16x16x32_bf16 v[114:117], v[158:161], v[204:207], v[114:117]
	v_mfma_f32_16x16x32_bf16 v[110:113], v[166:169], v[204:207], v[110:113]
	v_mfma_f32_16x16x32_bf16 v[86:89], v[158:161], v[212:215], v[86:89]
	v_mfma_f32_16x16x32_bf16 v[78:81], v[166:169], v[212:215], v[78:81]
	v_mfma_f32_16x16x32_bf16 v[146:149], v[162:165], v[184:187], v[146:149]
	v_mfma_f32_16x16x32_bf16 v[142:145], v[170:173], v[184:187], v[142:145]
	v_mfma_f32_16x16x32_bf16 v[130:133], v[162:165], v[192:195], v[130:133]
	v_mfma_f32_16x16x32_bf16 v[126:129], v[170:173], v[192:195], v[126:129]
	s_add_i32 s83, s75, s55
	s_mov_b64 s[2:3], s[12:13]
	s_mov_b32 m0, s83
	v_mfma_f32_16x16x32_bf16 v[114:117], v[162:165], v[208:211], v[114:117]
	v_mfma_f32_16x16x32_bf16 v[110:113], v[170:173], v[208:211], v[110:113]
	v_mfma_f32_16x16x32_bf16 v[86:89], v[162:165], v[216:219], v[86:89]
	v_mfma_f32_16x16x32_bf16 v[78:81], v[170:173], v[216:219], v[78:81]
	s_setprio 0
	s_barrier
	ds_read_b128 v[180:183], v203 offset:16384
	ds_read_b128 v[184:187], v203 offset:17408
	ds_read_b128 v[188:191], v203 offset:18432
	ds_read_b128 v[192:195], v203 offset:19456
	ds_read_b128 v[204:207], v203 offset:20480
	ds_read_b128 v[208:211], v203 offset:21504
	ds_read_b128 v[212:215], v203 offset:22528
	ds_read_b128 v[216:219], v203 offset:23552
	s_nop 0
	global_load_lds_dwordx4 v221, s[2:3]
	s_add_i32 m0, s83, 0x2000
	s_nop 0
	global_load_lds_dwordx4 v8, s[2:3]
	s_add_u32 s2, s12, 0x40000
	s_addc_u32 s3, s13, 0
	s_add_i32 s83, s76, s55
	s_mov_b32 m0, s83
	s_nop 0
	global_load_lds_dwordx4 v221, s[2:3]
	s_add_i32 m0, s83, 0x2000
	s_nop 0
	global_load_lds_dwordx4 v8, s[2:3]
	s_mov_b64 s[2:3], s[58:59]
	s_mov_b32 m0, s57
	s_nop 0
	global_load_lds_dwordx4 v220, s[2:3]
	s_mov_b32 m0, s64
	s_nop 0
	global_load_lds_dwordx4 v222, s[2:3]
	s_waitcnt vmcnt(8)
	s_waitcnt lgkmcnt(0)
	s_barrier
; #define PG8_STAGE(bufoff, gbase, voff) do { const char* gb_ = (const char*)(gbase); asm volatile("" : "+s"(gb_));     \
;         _Pragma("unroll") for (int _i = 0; _i < 2; ++_i) \
;         __builtin_amdgcn_global_load_lds((const unsigned*)(gb_ + (voff)[_i]), (PG8_LAS unsigned*)(lds + (bufoff) + ldsw + _i * 8192), 16, 0, 0); } while (0)
; #define PG8_LDA(dst, b, h) do { _Pragma("unroll") for (int m = 0; m < 4; ++m) _Pragma("unroll") for (int k = 0; k < 2; ++k) dst[m][k] = *(const PG8_LAS bf16x8*)(lds + PG8_SA(b, h) + aoff + m * 2048 + k * 1024); } while (0)
; #define PG8_LDB(dst, b, h) do { _Pragma("unroll") for (int n = 0; n < 2; ++n) _Pragma("unroll") for (int k = 0; k < 2; ++k) dst[n][k] = *(const PG8_LAS bf16x8*)(lds + PG8_SB(b, h) + boff + n * 2048 + k * 1024); } while (0)
; #define PG8_MMA(ai, bj, At, Bt) do { __builtin_amdgcn_s_setprio(1); _Pragma("unroll") for (int m = 0; m < 4; ++m) _Pragma("unroll") for (int n = 0; n < 2; ++n) _Pragma("unroll") for (int k = 0; k < 2; ++k) \
;         acc[ai][bj][m][n] = __builtin_amdgcn_mfma_f32_16x16x32_bf16(Bt[n][k], At[m][k], acc[ai][bj][m][n], 0, 0, 0); __builtin_amdgcn_s_setprio(0); } while (0)
; template <class Epi, class Sched, bool ALIGN_EPI = false, bool SP2 = false>
; __device__ __forceinline__ void gemm_phase(PG8_LAS unsigned char* lds, const Gemm g, const Sched& S, const Epi& E, int wid0) {
;     ...
;             PG8_LDB(B0, 0, 0); PG8_LDB(B1, 0, 1); PG8_SCHED; PG8_LDA(At, 0, 0); PG8_STAGE(PG8_SA(1, 1), a1 + hstepA, vA_);
;             PG8_WAIT_V(8); PG8_WAIT_L(0); PG8_BAR; PG8_MMA(0, 0, At, B0); PG8_MMA(0, 1, At, B1); PG8_BAR; PG8_SCHED;
;             PG8_LDA(At, 0, 1); PG8_STAGE(PG8_SB(0, 0), b2, vB_); PG8_STAGE(PG8_SB(0, 1), b2 + hstep, vB_); PG8_STAGE(PG8_SA(0, 0), a2, vA_);
;             PG8_WAIT_V(8); PG8_WAIT_L(0); PG8_BAR; PG8_MMA(1, 0, At, B0); PG8_MMA(1, 1, At, B1); PG8_BAR; PG8_SCHED;
;             PG8_LDB(B0, 1, 0); PG8_LDB(B1, 1, 1); PG8_SCHED; PG8_LDA(At, 1, 0); PG8_STAGE(PG8_SA(0, 1), a2 + hstepA, vA_);
;             PG8_WAIT_V(8); PG8_WAIT_L(0); PG8_BAR; PG8_MMA(0, 0, At, B0); PG8_MMA(0, 1, At, B1); PG8_BAR; PG8_SCHED;
;             PG8_LDA(At, 1, 1); PG8_STAGE(PG8_SB(1, 0), b3, vB_); PG8_STAGE(PG8_SB(1, 1), b3 + hstep, vB_); PG8_STAGE(PG8_SA(1, 0), a3, vA_);
;             PG8_WAIT_V(8); PG8_WAIT_L(0); PG8_BAR; PG8_MMA(1, 0, At, B0); PG8_MMA(1, 1, At, B1); PG8_BAR; PG8_SCHED;
	s_setprio 1
	s_waitcnt lgkmcnt(0)
	v_mfma_f32_16x16x32_bf16 v[74:77], v[82:85], v[180:183], v[74:77]
	v_mfma_f32_16x16x32_bf16 v[70:73], v[94:97], v[180:183], v[70:73]
	v_mfma_f32_16x16x32_bf16 v[58:61], v[82:85], v[188:191], v[58:61]
	v_mfma_f32_16x16x32_bf16 v[54:57], v[94:97], v[188:191], v[54:57]
	v_mfma_f32_16x16x32_bf16 v[42:45], v[82:85], v[204:207], v[42:45]
	v_mfma_f32_16x16x32_bf16 v[38:41], v[94:97], v[204:207], v[38:41]
	v_mfma_f32_16x16x32_bf16 v[26:29], v[82:85], v[212:215], v[26:29]
	v_mfma_f32_16x16x32_bf16 v[22:25], v[94:97], v[212:215], v[22:25]
	v_mfma_f32_16x16x32_bf16 v[74:77], v[90:93], v[184:187], v[74:77]
	v_mfma_f32_16x16x32_bf16 v[70:73], v[102:105], v[184:187], v[70:73]
	v_mfma_f32_16x16x32_bf16 v[58:61], v[90:93], v[192:195], v[58:61]
	v_mfma_f32_16x16x32_bf16 v[54:57], v[102:105], v[192:195], v[54:57]
	v_mfma_f32_16x16x32_bf16 v[42:45], v[90:93], v[208:211], v[42:45]
	v_mfma_f32_16x16x32_bf16 v[38:41], v[102:105], v[208:211], v[38:41]
	v_mfma_f32_16x16x32_bf16 v[26:29], v[90:93], v[216:219], v[26:29]
	v_mfma_f32_16x16x32_bf16 v[22:25], v[102:105], v[216:219], v[22:25]
	s_setprio 0
	s_setprio 1
	v_mfma_f32_16x16x32_bf16 v[66:69], v[158:161], v[180:183], v[66:69]
	v_mfma_f32_16x16x32_bf16 v[62:65], v[166:169], v[180:183], v[62:65]
	v_mfma_f32_16x16x32_bf16 v[50:53], v[158:161], v[188:191], v[50:53]
	v_mfma_f32_16x16x32_bf16 v[46:49], v[166:169], v[188:191], v[46:49]
	v_mfma_f32_16x16x32_bf16 v[34:37], v[158:161], v[204:207], v[34:37]
	v_mfma_f32_16x16x32_bf16 v[30:33], v[166:169], v[204:207], v[30:33]
	v_mfma_f32_16x16x32_bf16 v[18:21], v[158:161], v[212:215], v[18:21]
	v_mfma_f32_16x16x32_bf16 v[14:17], v[166:169], v[212:215], v[14:17]
	v_mfma_f32_16x16x32_bf16 v[66:69], v[162:165], v[184:187], v[66:69]
	v_mfma_f32_16x16x32_bf16 v[62:65], v[170:173], v[184:187], v[62:65]
	v_mfma_f32_16x16x32_bf16 v[50:53], v[162:165], v[192:195], v[50:53]
	v_mfma_f32_16x16x32_bf16 v[46:49], v[170:173], v[192:195], v[46:49]
	s_add_i32 s83, 0, 0x18000
	s_add_i32 s84, 0, 0x1c000
	v_mfma_f32_16x16x32_bf16 v[34:37], v[162:165], v[208:211], v[34:37]
	v_mfma_f32_16x16x32_bf16 v[30:33], v[170:173], v[208:211], v[30:33]
	v_mfma_f32_16x16x32_bf16 v[18:21], v[162:165], v[216:219], v[18:21]
	v_mfma_f32_16x16x32_bf16 v[14:17], v[170:173], v[216:219], v[14:17]
	s_setprio 0
	s_barrier
	v_add_u32_e32 v102, s83, v175
	v_add_u32_e32 v170, s84, v175
	ds_read_b128 v[82:85], v102
	ds_read_b128 v[90:93], v102 offset:1024
	ds_read_b128 v[94:97], v102 offset:2048
	ds_read_b128 v[102:105], v102 offset:3072
	ds_read_b128 v[158:161], v170
	ds_read_b128 v[162:165], v170 offset:1024
	ds_read_b128 v[166:169], v170 offset:2048
	ds_read_b128 v[170:173], v170 offset:3072
	s_add_u32 s2, s58, 0x40000
	s_addc_u32 s3, s59, 0
	s_mov_b32 m0, s65
	ds_read_b128 v[180:183], v203 offset:32768
	ds_read_b128 v[184:187], v203 offset:33792
	ds_read_b128 v[188:191], v203 offset:34816
	ds_read_b128 v[192:195], v203 offset:35840
	ds_read_b128 v[204:207], v203 offset:36864
	ds_read_b128 v[208:211], v203 offset:37888
	ds_read_b128 v[212:215], v203 offset:38912
	ds_read_b128 v[216:219], v203 offset:39936
	s_nop 0
	global_load_lds_dwordx4 v220, s[2:3]
	s_mov_b32 m0, s66
	s_nop 0
	global_load_lds_dwordx4 v222, s[2:3]
	s_waitcnt vmcnt(8)
	s_waitcnt lgkmcnt(0)
	s_barrier
	s_setprio 1
	s_waitcnt lgkmcnt(0)
	v_mfma_f32_16x16x32_bf16 v[154:157], v[82:85], v[180:183], v[154:157]
	v_mfma_f32_16x16x32_bf16 v[150:153], v[94:97], v[180:183], v[150:153]
	v_mfma_f32_16x16x32_bf16 v[138:141], v[82:85], v[188:191], v[138:141]
	v_mfma_f32_16x16x32_bf16 v[134:137], v[94:97], v[188:191], v[134:137]
	v_mfma_f32_16x16x32_bf16 v[122:125], v[82:85], v[204:207], v[122:125]
	v_mfma_f32_16x16x32_bf16 v[118:121], v[94:97], v[204:207], v[118:121]
	v_mfma_f32_16x16x32_bf16 v[106:109], v[82:85], v[212:215], v[106:109]
	v_mfma_f32_16x16x32_bf16 v[98:101], v[94:97], v[212:215], v[98:101]
	v_mfma_f32_16x16x32_bf16 v[154:157], v[90:93], v[184:187], v[154:157]
	v_mfma_f32_16x16x32_bf16 v[150:153], v[102:105], v[184:187], v[150:153]
	v_mfma_f32_16x16x32_bf16 v[138:141], v[90:93], v[192:195], v[138:141]
	v_mfma_f32_16x16x32_bf16 v[134:137], v[102:105], v[192:195], v[134:137]
	v_mfma_f32_16x16x32_bf16 v[122:125], v[90:93], v[208:211], v[122:125]
	v_mfma_f32_16x16x32_bf16 v[118:121], v[102:105], v[208:211], v[118:121]
	v_mfma_f32_16x16x32_bf16 v[106:109], v[90:93], v[216:219], v[106:109]
	v_mfma_f32_16x16x32_bf16 v[98:101], v[102:105], v[216:219], v[98:101]
	s_setprio 0
	s_setprio 1
	v_mfma_f32_16x16x32_bf16 v[146:149], v[158:161], v[180:183], v[146:149]
	v_mfma_f32_16x16x32_bf16 v[142:145], v[166:169], v[180:183], v[142:145]
	v_mfma_f32_16x16x32_bf16 v[130:133], v[158:161], v[188:191], v[130:133]
	v_mfma_f32_16x16x32_bf16 v[126:129], v[166:169], v[188:191], v[126:129]
	v_mfma_f32_16x16x32_bf16 v[114:117], v[158:161], v[204:207], v[114:117]
	v_mfma_f32_16x16x32_bf16 v[110:113], v[166:169], v[204:207], v[110:113]
	v_mfma_f32_16x16x32_bf16 v[86:89], v[158:161], v[212:215], v[86:89]
	v_mfma_f32_16x16x32_bf16 v[78:81], v[166:169], v[212:215], v[78:81]
	v_mfma_f32_16x16x32_bf16 v[146:149], v[162:165], v[184:187], v[146:149]
	v_mfma_f32_16x16x32_bf16 v[142:145], v[170:173], v[184:187], v[142:145]
	v_mfma_f32_16x16x32_bf16 v[130:133], v[162:165], v[192:195], v[130:133]
	v_mfma_f32_16x16x32_bf16 v[126:129], v[170:173], v[192:195], v[126:129]
	s_add_u32 s2, s12, 0x80
	s_addc_u32 s3, s13, 0
	s_add_i32 s58, s83, s55
	s_mov_b32 m0, s58
	v_mfma_f32_16x16x32_bf16 v[114:117], v[162:165], v[208:211], v[114:117]
	v_mfma_f32_16x16x32_bf16 v[110:113], v[170:173], v[208:211], v[110:113]
	v_mfma_f32_16x16x32_bf16 v[86:89], v[162:165], v[216:219], v[86:89]
	v_mfma_f32_16x16x32_bf16 v[78:81], v[170:173], v[216:219], v[78:81]
	s_setprio 0
	s_barrier
; #define PG8_STAGE(bufoff, gbase, voff) do { const char* gb_ = (const char*)(gbase); asm volatile("" : "+s"(gb_));     \
;         _Pragma("unroll") for (int _i = 0; _i < 2; ++_i) \
;         __builtin_amdgcn_global_load_lds((const unsigned*)(gb_ + (voff)[_i]), (PG8_LAS unsigned*)(lds + (bufoff) + ldsw + _i * 8192), 16, 0, 0); } while (0)
; #define PG8_LDA(dst, b, h) do { _Pragma("unroll") for (int m = 0; m < 4; ++m) _Pragma("unroll") for (int k = 0; k < 2; ++k) dst[m][k] = *(const PG8_LAS bf16x8*)(lds + PG8_SA(b, h) + aoff + m * 2048 + k * 1024); } while (0)
; #define PG8_LDB(dst, b, h) do { _Pragma("unroll") for (int n = 0; n < 2; ++n) _Pragma("unroll") for (int k = 0; k < 2; ++k) dst[n][k] = *(const PG8_LAS bf16x8*)(lds + PG8_SB(b, h) + boff + n * 2048 + k * 1024); } while (0)
; #define PG8_WAIT_V(n) asm volatile("s_waitcnt vmcnt(" #n ")" ::: "memory")
; #define PG8_WAIT_L(n) asm volatile("s_waitcnt lgkmcnt(" #n ")" ::: "memory")
; #define PG8_BAR __builtin_amdgcn_s_barrier()
; #define PG8_SCHED __builtin_amdgcn_sched_barrier(0)
; template <class Epi, class Sched, bool ALIGN_EPI = false, bool SP2 = false>
; __device__ __forceinline__ void gemm_phase(PG8_LAS unsigned char* lds, const Gemm g, const Sched& S, const Epi& E, int wid0) {
;     ...
;             PG8_LDB(B0, 0, 0); PG8_LDB(B1, 0, 1); PG8_SCHED; PG8_LDA(At, 0, 0); PG8_STAGE(PG8_SA(1, 1), a1 + hstepA, vA_);
;             PG8_WAIT_V(8); PG8_WAIT_L(0); PG8_BAR; PG8_MMA(0, 0, At, B0); PG8_MMA(0, 1, At, B1); PG8_BAR; PG8_SCHED;
;             PG8_LDA(At, 0, 1); PG8_STAGE(PG8_SB(0, 0), b2, vB_); PG8_STAGE(PG8_SB(0, 1), b2 + hstep, vB_); PG8_STAGE(PG8_SA(0, 0), a2, vA_);
;             PG8_WAIT_V(8); PG8_WAIT_L(0); PG8_BAR; PG8_MMA(1, 0, At, B0); PG8_MMA(1, 1, At, B1); PG8_BAR; PG8_SCHED;
;             PG8_LDB(B0, 1, 0); PG8_LDB(B1, 1, 1); PG8_SCHED; PG8_LDA(At, 1, 0); PG8_STAGE(PG8_SA(0, 1), a2 + hstepA, vA_);
;             PG8_WAIT_V(8); PG8_WAIT_L(0); PG8_BAR; PG8_MMA(0, 0, At, B0); PG8_MMA(0, 1, At, B1); PG8_BAR; PG8_SCHED;
;             PG8_LDA(At, 1, 1); PG8_STAGE(PG8_SB(1, 0), b3, vB_); PG8_STAGE(PG8_SB(1, 1), b3 + hstep, vB_); PG8_STAGE(PG8_SA(1, 0), a3, vA_);
;             PG8_WAIT_V(8); PG8_WAIT_L(0); PG8_BAR; PG8_MMA(1, 0, At, B0); PG8_MMA(1, 1, At, B1); PG8_BAR; PG8_SCHED;
;     ...
;         if constexpr (ALIGN_EPI) { if (wr == 0) PG8_BAR; }
	ds_read_b128 v[180:183], v203 offset:49152
	ds_read_b128 v[184:187], v203 offset:50176
	ds_read_b128 v[188:191], v203 offset:51200
	ds_read_b128 v[192:195], v203 offset:52224
	ds_read_b128 v[204:207], v203 offset:53248
	ds_read_b128 v[208:211], v203 offset:54272
	ds_read_b128 v[212:215], v203 offset:55296
	ds_read_b128 v[216:219], v203 offset:56320
	s_nop 0
	global_load_lds_dwordx4 v221, s[2:3]
	s_add_i32 m0, s58, 0x2000
	s_nop 0
	global_load_lds_dwordx4 v8, s[2:3]
	s_add_u32 s2, s12, 0x40080
	s_addc_u32 s3, s13, 0
	s_add_i32 s12, s84, s55
	s_mov_b32 m0, s12
	s_nop 0
	global_load_lds_dwordx4 v221, s[2:3]
	s_add_i32 m0, s12, 0x2000
	s_nop 0
	global_load_lds_dwordx4 v8, s[2:3]
	s_mov_b32 m0, s69
	s_nop 0
	global_load_lds_dwordx4 v220, s[10:11]
	s_mov_b32 m0, s70
	s_nop 0
	global_load_lds_dwordx4 v222, s[10:11]
	s_waitcnt vmcnt(8)
	s_waitcnt lgkmcnt(0)
	s_barrier
	s_setprio 1
	s_waitcnt lgkmcnt(0)
	v_mfma_f32_16x16x32_bf16 v[74:77], v[82:85], v[180:183], v[74:77]
	v_mfma_f32_16x16x32_bf16 v[70:73], v[94:97], v[180:183], v[70:73]
	v_mfma_f32_16x16x32_bf16 v[58:61], v[82:85], v[188:191], v[58:61]
	v_mfma_f32_16x16x32_bf16 v[54:57], v[94:97], v[188:191], v[54:57]
	v_mfma_f32_16x16x32_bf16 v[42:45], v[82:85], v[204:207], v[42:45]
	v_mfma_f32_16x16x32_bf16 v[38:41], v[94:97], v[204:207], v[38:41]
	v_mfma_f32_16x16x32_bf16 v[26:29], v[82:85], v[212:215], v[26:29]
	v_mfma_f32_16x16x32_bf16 v[22:25], v[94:97], v[212:215], v[22:25]
	v_mfma_f32_16x16x32_bf16 v[74:77], v[90:93], v[184:187], v[74:77]
	v_mfma_f32_16x16x32_bf16 v[70:73], v[102:105], v[184:187], v[70:73]
	v_mfma_f32_16x16x32_bf16 v[58:61], v[90:93], v[192:195], v[58:61]
	v_mfma_f32_16x16x32_bf16 v[54:57], v[102:105], v[192:195], v[54:57]
	v_mfma_f32_16x16x32_bf16 v[42:45], v[90:93], v[208:211], v[42:45]
	v_mfma_f32_16x16x32_bf16 v[38:41], v[102:105], v[208:211], v[38:41]
	v_mfma_f32_16x16x32_bf16 v[26:29], v[90:93], v[216:219], v[26:29]
	v_mfma_f32_16x16x32_bf16 v[22:25], v[102:105], v[216:219], v[22:25]
	s_setprio 0
	s_setprio 1
	v_mfma_f32_16x16x32_bf16 v[66:69], v[158:161], v[180:183], v[66:69]
	v_mfma_f32_16x16x32_bf16 v[62:65], v[166:169], v[180:183], v[62:65]
	v_mfma_f32_16x16x32_bf16 v[50:53], v[158:161], v[188:191], v[50:53]
	v_mfma_f32_16x16x32_bf16 v[46:49], v[166:169], v[188:191], v[46:49]
	v_mfma_f32_16x16x32_bf16 v[34:37], v[158:161], v[204:207], v[34:37]
	v_mfma_f32_16x16x32_bf16 v[30:33], v[166:169], v[204:207], v[30:33]
	v_mfma_f32_16x16x32_bf16 v[18:21], v[158:161], v[212:215], v[18:21]
	v_mfma_f32_16x16x32_bf16 v[14:17], v[166:169], v[212:215], v[14:17]
	v_mfma_f32_16x16x32_bf16 v[66:69], v[162:165], v[184:187], v[66:69]
	v_mfma_f32_16x16x32_bf16 v[62:65], v[170:173], v[184:187], v[62:65]
	v_mfma_f32_16x16x32_bf16 v[50:53], v[162:165], v[192:195], v[50:53]
	v_mfma_f32_16x16x32_bf16 v[46:49], v[170:173], v[192:195], v[46:49]
	s_add_i32 s82, s82, 2
	s_add_u32 s80, s80, 0x100
	s_addc_u32 s81, s81, 0
	s_cmp_gt_u32 s82, 13
	s_mov_b64 s[2:3], s[8:9]
	v_mfma_f32_16x16x32_bf16 v[34:37], v[162:165], v[208:211], v[34:37]
	v_mfma_f32_16x16x32_bf16 v[30:33], v[170:173], v[208:211], v[30:33]
	v_mfma_f32_16x16x32_bf16 v[18:21], v[162:165], v[216:219], v[18:21]
	v_mfma_f32_16x16x32_bf16 v[14:17], v[170:173], v[216:219], v[14:17]
	s_setprio 0
	s_barrier
	s_cbranch_scc0 .LBB13_1336
	s_and_b64 vcc, exec, s[42:43]
	s_cbranch_vccz .LBB13_1339
	s_barrier

;     __device__ float mid(int row) const { return rg(row) / ra(row); }
;     __device__ __forceinline__ bool next(int i, Unit& u) const { return map(rank + i * nloc, u); }
;     __device__ __forceinline__ bool next(int i, Unit& u) const { if (i >= __builtin_amdgcn_readfirstlane(tab[0])) return false; u.pm = __builtin_amdgcn_readfirstlane(tab[1 + 2 * i]); u.pn = __builtin_amdgcn_readfirstlane(tab[2 + 2 * i]); return true; }
; #define PG8_LDA(dst, b, h) do { _Pragma("unroll") for (int m = 0; m < 4; ++m) _Pragma("unroll") for (int k = 0; k < 2; ++k) dst[m][k] = *(const PG8_LAS bf16x8*)(lds + PG8_SA(b, h) + aoff + m * 2048 + k * 1024); } while (0)
; #define PG8_WAIT_V(n) asm volatile("s_waitcnt vmcnt(" #n ")" ::: "memory")
; template <class Epi, class Sched, bool ALIGN_EPI = false, bool SP2 = false>
; __device__ __forceinline__ void gemm_phase(PG8_LAS unsigned char* lds, const Gemm g, const Sched& S, const Epi& E, int wid0) {
;     ...
;         const bool has_next = S.next(ui + 1, nxt); nxt.ui = ui + 1;
;         if constexpr (Epi::HAS_PRE) E.pre_finish(lds, cur, tid, pq0, pq1, pq2);
;         const char* nA = has_next ? (const char*)g.A + (size_t)nxt.pm * tstepA : cA; const char* nB = has_next ? (const char*)g.Bt + (size_t)nxt.pn * tstep : cB;
; #pragma nounroll
;         for (int t = 0; t < nt; t += 2) {
;             const bool last = (t == nt - 2);
;             const char* a1 = cA + (size_t)(t + 1) * kstep;
;             const char* a2 = last ? nA : cA + (size_t)(t + 2) * kstep; const char* b2 = last ? nB : cB + (size_t)(t + 2) * kstep;
;             const char* a3 = a2 + kstep; const char* b3 = b2 + kstep;
;             if (last && has_next) S.a_ready(nxt);
;             if constexpr (Epi::HAS_MID) { if (t == Epi::MID_T) E.mid(acc, cur, wr, fr); }
;             unsigned vA_[2] = {voffA[0], voffA[1]}, vB_[2] = {voffB[0], voffB[1]};
;             asm volatile("" : "+v"(vA_[0]), "+v"(vA_[1]), "+v"(vB_[0]), "+v"(vB_[1]));
;             if constexpr (SP2) {
;             PG8_LDB(B0, 0, 0); PG8_LDB(B1, 0, 1); PG8_SCHED; PG8_LDA(At, 0, 0); PG8_STAGE(PG8_SA(1, 1), a1 + hstepA, vA_);
;             PG8_WAIT_V(8); PG8_WAIT_L(0); PG8_BAR; PG8_MMA(0, 0, At, B0); PG8_MMA(0, 1, At, B1); PG8_BAR; PG8_SCHED;
;             PG8_LDA(At, 0, 1); PG8_STAGE(PG8_SB(0, 0), b2, vB_); PG8_STAGE(PG8_SB(0, 1), b2 + hstep, vB_); PG8_STAGE(PG8_SA(0, 0), a2, vA_);
.LBB13_1920:
	v_mov_b32_e32 v9, v172
	v_mov_b32_e32 v170, v174
	v_mov_b32_e32 v171, v176
	v_mov_b32_e32 v182, v178
	v_add_u32_e32 v10, s62, v173
	ds_read_b128 v[142:145], v10
	ds_read_b128 v[146:149], v10 offset:1024
	ds_read_b128 v[150:153], v10 offset:2048
	ds_read_b128 v[154:157], v10 offset:3072
	v_add_u32_e32 v10, s63, v173
	s_add_u32 s6, s40, 0x100
	ds_read_b128 v[158:161], v10
	ds_read_b128 v[162:165], v10 offset:1024
	ds_read_b128 v[166:169], v10 offset:2048
	ds_read_b128 v[184:187], v10 offset:3072
	s_addc_u32 s7, s41, 0
	s_cmp_eq_u32 s68, 12
	s_cselect_b32 s48, s31, s6
	s_cselect_b32 s49, s27, s7
	s_cselect_b32 s43, s29, s67
	s_cselect_b32 s42, s65, s66
	s_add_u32 s44, s48, 0x80
	s_addc_u32 s45, s49, 0
	s_add_u32 s46, s42, 0x80
	s_addc_u32 s47, s43, 0
	s_add_u32 s40, s40, 0x80080
	s_addc_u32 s41, s41, 0
	s_add_i32 m0, s13, 0xc000
	ds_read_b128 v[188:191], v183
	ds_read_b128 v[192:195], v183 offset:1024
	ds_read_b128 v[196:199], v183 offset:2048
	ds_read_b128 v[200:203], v183 offset:3072
	ds_read_b128 v[204:207], v183 offset:4096
	ds_read_b128 v[208:211], v183 offset:5120
	ds_read_b128 v[212:215], v183 offset:6144
	ds_read_b128 v[216:219], v183 offset:7168
	s_nop 0
	global_load_lds_dwordx4 v9, s[40:41]
	s_add_i32 m0, s13, 0xe000
	s_nop 0
	global_load_lds_dwordx4 v171, s[40:41]
	s_waitcnt vmcnt(8)
	s_waitcnt lgkmcnt(0)
	s_barrier
	s_setprio 1
	s_waitcnt lgkmcnt(0)
	v_mfma_f32_16x16x32_bf16 v[136:139], v[142:145], v[188:191], v[136:139]
	v_mfma_f32_16x16x32_bf16 v[132:135], v[150:153], v[188:191], v[132:135]
	v_mfma_f32_16x16x32_bf16 v[128:131], v[142:145], v[196:199], v[128:131]
	v_mfma_f32_16x16x32_bf16 v[124:127], v[150:153], v[196:199], v[124:127]
	v_mfma_f32_16x16x32_bf16 v[120:123], v[142:145], v[204:207], v[120:123]
	v_mfma_f32_16x16x32_bf16 v[116:119], v[150:153], v[204:207], v[116:119]
	v_mfma_f32_16x16x32_bf16 v[112:115], v[142:145], v[212:215], v[112:115]
	v_mfma_f32_16x16x32_bf16 v[108:111], v[150:153], v[212:215], v[108:111]
	v_mfma_f32_16x16x32_bf16 v[136:139], v[146:149], v[192:195], v[136:139]
	v_mfma_f32_16x16x32_bf16 v[132:135], v[154:157], v[192:195], v[132:135]
	v_mfma_f32_16x16x32_bf16 v[128:131], v[146:149], v[200:203], v[128:131]
	v_mfma_f32_16x16x32_bf16 v[124:127], v[154:157], v[200:203], v[124:127]
	v_mfma_f32_16x16x32_bf16 v[120:123], v[146:149], v[208:211], v[120:123]
	v_mfma_f32_16x16x32_bf16 v[116:119], v[154:157], v[208:211], v[116:119]
	v_mfma_f32_16x16x32_bf16 v[112:115], v[146:149], v[216:219], v[112:115]
	v_mfma_f32_16x16x32_bf16 v[108:111], v[154:157], v[216:219], v[108:111]
	s_setprio 0
	s_setprio 1
	v_mfma_f32_16x16x32_bf16 v[72:75], v[158:161], v[188:191], v[72:75]
	v_mfma_f32_16x16x32_bf16 v[68:71], v[166:169], v[188:191], v[68:71]
	v_mfma_f32_16x16x32_bf16 v[64:67], v[158:161], v[196:199], v[64:67]
	v_mfma_f32_16x16x32_bf16 v[60:63], v[166:169], v[196:199], v[60:63]
	v_mfma_f32_16x16x32_bf16 v[56:59], v[158:161], v[204:207], v[56:59]
	v_mfma_f32_16x16x32_bf16 v[52:55], v[166:169], v[204:207], v[52:55]
	v_mfma_f32_16x16x32_bf16 v[48:51], v[158:161], v[212:215], v[48:51]
	v_mfma_f32_16x16x32_bf16 v[44:47], v[166:169], v[212:215], v[44:47]
	v_mfma_f32_16x16x32_bf16 v[72:75], v[162:165], v[192:195], v[72:75]
	v_mfma_f32_16x16x32_bf16 v[68:71], v[184:187], v[192:195], v[68:71]
	v_mfma_f32_16x16x32_bf16 v[64:67], v[162:165], v[200:203], v[64:67]
	v_mfma_f32_16x16x32_bf16 v[60:63], v[184:187], v[200:203], v[60:63]
	s_add_i32 s69, s62, s25
	s_mov_b64 s[40:41], s[42:43]
	s_mov_b32 m0, s69
	v_mfma_f32_16x16x32_bf16 v[56:59], v[162:165], v[208:211], v[56:59]
	v_mfma_f32_16x16x32_bf16 v[52:55], v[184:187], v[208:211], v[52:55]
	v_mfma_f32_16x16x32_bf16 v[48:51], v[162:165], v[216:219], v[48:51]
	v_mfma_f32_16x16x32_bf16 v[44:47], v[184:187], v[216:219], v[44:47]
	s_setprio 0
	s_barrier
	ds_read_b128 v[188:191], v183 offset:16384
	ds_read_b128 v[192:195], v183 offset:17408
	ds_read_b128 v[196:199], v183 offset:18432
	ds_read_b128 v[200:203], v183 offset:19456
	ds_read_b128 v[204:207], v183 offset:20480
	ds_read_b128 v[208:211], v183 offset:21504
	ds_read_b128 v[212:215], v183 offset:22528
	ds_read_b128 v[216:219], v183 offset:23552
	s_nop 0
	global_load_lds_dwordx4 v170, s[40:41]
	s_add_i32 m0, s69, 0x2000
	s_nop 0
	global_load_lds_dwordx4 v182, s[40:41]
	s_add_u32 s40, s42, 0x40000
	s_addc_u32 s41, s43, 0
	s_add_i32 s69, s63, s25
	s_mov_b32 m0, s69
	s_nop 0
	global_load_lds_dwordx4 v170, s[40:41]
	s_add_i32 m0, s69, 0x2000
	s_nop 0
	global_load_lds_dwordx4 v182, s[40:41]
	s_mov_b64 s[40:41], s[48:49]
	s_mov_b32 m0, s13
	s_nop 0
	global_load_lds_dwordx4 v9, s[40:41]
	s_mov_b32 m0, s51
	s_nop 0
	global_load_lds_dwordx4 v171, s[40:41]
	s_waitcnt vmcnt(8)
	s_waitcnt lgkmcnt(0)
	s_barrier
; #define PG8_STAGE(bufoff, gbase, voff) do { const char* gb_ = (const char*)(gbase); asm volatile("" : "+s"(gb_));     \
;         _Pragma("unroll") for (int _i = 0; _i < 2; ++_i) \
;         __builtin_amdgcn_global_load_lds((const unsigned*)(gb_ + (voff)[_i]), (PG8_LAS unsigned*)(lds + (bufoff) + ldsw + _i * 8192), 16, 0, 0); } while (0)
; #define PG8_LDA(dst, b, h) do { _Pragma("unroll") for (int m = 0; m < 4; ++m) _Pragma("unroll") for (int k = 0; k < 2; ++k) dst[m][k] = *(const PG8_LAS bf16x8*)(lds + PG8_SA(b, h) + aoff + m * 2048 + k * 1024); } while (0)
; #define PG8_LDB(dst, b, h) do { _Pragma("unroll") for (int n = 0; n < 2; ++n) _Pragma("unroll") for (int k = 0; k < 2; ++k) dst[n][k] = *(const PG8_LAS bf16x8*)(lds + PG8_SB(b, h) + boff + n * 2048 + k * 1024); } while (0)
; #define PG8_MMA(ai, bj, At, Bt) do { __builtin_amdgcn_s_setprio(1); _Pragma("unroll") for (int m = 0; m < 4; ++m) _Pragma("unroll") for (int n = 0; n < 2; ++n) _Pragma("unroll") for (int k = 0; k < 2; ++k) \
;         acc[ai][bj][m][n] = __builtin_amdgcn_mfma_f32_16x16x32_bf16(Bt[n][k], At[m][k], acc[ai][bj][m][n], 0, 0, 0); __builtin_amdgcn_s_setprio(0); } while (0)
; #define PG8_WAIT_V(n) asm volatile("s_waitcnt vmcnt(" #n ")" ::: "memory")
; #define PG8_WAIT_L(n) asm volatile("s_waitcnt lgkmcnt(" #n ")" ::: "memory")
; #define PG8_BAR __builtin_amdgcn_s_barrier()
; #define PG8_SCHED __builtin_amdgcn_sched_barrier(0)
; template <class Epi, class Sched, bool ALIGN_EPI = false, bool SP2 = false>
; __device__ __forceinline__ void gemm_phase(PG8_LAS unsigned char* lds, const Gemm g, const Sched& S, const Epi& E, int wid0) {
;     ...
;             PG8_WAIT_V(8); PG8_WAIT_L(0); PG8_BAR; PG8_MMA(0, 0, At, B0); PG8_MMA(0, 1, At, B1); PG8_BAR; PG8_SCHED;
;             PG8_LDA(At, 0, 1); PG8_STAGE(PG8_SB(0, 0), b2, vB_); PG8_STAGE(PG8_SB(0, 1), b2 + hstep, vB_); PG8_STAGE(PG8_SA(0, 0), a2, vA_);
;             PG8_WAIT_V(8); PG8_WAIT_L(0); PG8_BAR; PG8_MMA(1, 0, At, B0); PG8_MMA(1, 1, At, B1); PG8_BAR; PG8_SCHED;
;             PG8_LDB(B0, 1, 0); PG8_LDB(B1, 1, 1); PG8_SCHED; PG8_LDA(At, 1, 0); PG8_STAGE(PG8_SA(0, 1), a2 + hstepA, vA_);
;             PG8_WAIT_V(8); PG8_WAIT_L(0); PG8_BAR; PG8_MMA(0, 0, At, B0); PG8_MMA(0, 1, At, B1); PG8_BAR; PG8_SCHED;
	s_setprio 1
	s_waitcnt lgkmcnt(0)
	v_mfma_f32_16x16x32_bf16 v[104:107], v[142:145], v[188:191], v[104:107]
	v_mfma_f32_16x16x32_bf16 v[100:103], v[150:153], v[188:191], v[100:103]
	v_mfma_f32_16x16x32_bf16 v[96:99], v[142:145], v[196:199], v[96:99]
	v_mfma_f32_16x16x32_bf16 v[92:95], v[150:153], v[196:199], v[92:95]
	v_mfma_f32_16x16x32_bf16 v[88:91], v[142:145], v[204:207], v[88:91]
	v_mfma_f32_16x16x32_bf16 v[84:87], v[150:153], v[204:207], v[84:87]
	v_mfma_f32_16x16x32_bf16 v[80:83], v[142:145], v[212:215], v[80:83]
	v_mfma_f32_16x16x32_bf16 v[76:79], v[150:153], v[212:215], v[76:79]
	v_mfma_f32_16x16x32_bf16 v[104:107], v[146:149], v[192:195], v[104:107]
	v_mfma_f32_16x16x32_bf16 v[100:103], v[154:157], v[192:195], v[100:103]
	v_mfma_f32_16x16x32_bf16 v[96:99], v[146:149], v[200:203], v[96:99]
	v_mfma_f32_16x16x32_bf16 v[92:95], v[154:157], v[200:203], v[92:95]
	v_mfma_f32_16x16x32_bf16 v[88:91], v[146:149], v[208:211], v[88:91]
	v_mfma_f32_16x16x32_bf16 v[84:87], v[154:157], v[208:211], v[84:87]
	v_mfma_f32_16x16x32_bf16 v[80:83], v[146:149], v[216:219], v[80:83]
	v_mfma_f32_16x16x32_bf16 v[76:79], v[154:157], v[216:219], v[76:79]
	s_setprio 0
	s_setprio 1
	v_mfma_f32_16x16x32_bf16 v[40:43], v[158:161], v[188:191], v[40:43]
	v_mfma_f32_16x16x32_bf16 v[36:39], v[166:169], v[188:191], v[36:39]
	v_mfma_f32_16x16x32_bf16 v[32:35], v[158:161], v[196:199], v[32:35]
	v_mfma_f32_16x16x32_bf16 v[28:31], v[166:169], v[196:199], v[28:31]
	v_mfma_f32_16x16x32_bf16 v[24:27], v[158:161], v[204:207], v[24:27]
	v_mfma_f32_16x16x32_bf16 v[20:23], v[166:169], v[204:207], v[20:23]
	v_mfma_f32_16x16x32_bf16 v[16:19], v[158:161], v[212:215], v[16:19]
	v_mfma_f32_16x16x32_bf16 v[10:13], v[166:169], v[212:215], v[12:15]
	v_mfma_f32_16x16x32_bf16 v[40:43], v[162:165], v[192:195], v[40:43]
	v_mfma_f32_16x16x32_bf16 v[36:39], v[184:187], v[192:195], v[36:39]
	v_mfma_f32_16x16x32_bf16 v[32:35], v[162:165], v[200:203], v[32:35]
	v_mfma_f32_16x16x32_bf16 v[28:31], v[184:187], v[200:203], v[28:31]
	s_add_i32 s69, 0, 0x18000
	v_mfma_f32_16x16x32_bf16 v[24:27], v[162:165], v[208:211], v[24:27]
	v_mfma_f32_16x16x32_bf16 v[20:23], v[184:187], v[208:211], v[20:23]
	v_mfma_f32_16x16x32_bf16 v[16:19], v[162:165], v[216:219], v[16:19]
	v_mfma_f32_16x16x32_bf16 v[10:13], v[184:187], v[216:219], v[10:13]
	s_setprio 0
	s_barrier
	v_add_u32_e32 v14, s69, v173
	s_add_i32 s70, 0, 0x1c000
	ds_read_b128 v[142:145], v14
	ds_read_b128 v[146:149], v14 offset:1024
	ds_read_b128 v[150:153], v14 offset:2048
	ds_read_b128 v[154:157], v14 offset:3072
	v_add_u32_e32 v14, s70, v173
	ds_read_b128 v[158:161], v14
	ds_read_b128 v[162:165], v14 offset:1024
	ds_read_b128 v[166:169], v14 offset:2048
	ds_read_b128 v[184:187], v14 offset:3072
	s_add_u32 s40, s48, 0x80000
	s_addc_u32 s41, s49, 0
	s_mov_b32 m0, s52
	ds_read_b128 v[188:191], v183 offset:32768
	ds_read_b128 v[192:195], v183 offset:33792
	ds_read_b128 v[196:199], v183 offset:34816
	ds_read_b128 v[200:203], v183 offset:35840
	ds_read_b128 v[204:207], v183 offset:36864
	ds_read_b128 v[208:211], v183 offset:37888
	ds_read_b128 v[212:215], v183 offset:38912
	ds_read_b128 v[216:219], v183 offset:39936
	s_nop 0
	global_load_lds_dwordx4 v9, s[40:41]
	s_mov_b32 m0, s53
	s_nop 0
	global_load_lds_dwordx4 v171, s[40:41]
	s_waitcnt vmcnt(8)
	s_waitcnt lgkmcnt(0)
	s_barrier
	s_setprio 1
	s_waitcnt lgkmcnt(0)
	v_mfma_f32_16x16x32_bf16 v[136:139], v[142:145], v[188:191], v[136:139]
	v_mfma_f32_16x16x32_bf16 v[132:135], v[150:153], v[188:191], v[132:135]
	v_mfma_f32_16x16x32_bf16 v[128:131], v[142:145], v[196:199], v[128:131]
	v_mfma_f32_16x16x32_bf16 v[124:127], v[150:153], v[196:199], v[124:127]
	v_mfma_f32_16x16x32_bf16 v[120:123], v[142:145], v[204:207], v[120:123]
	v_mfma_f32_16x16x32_bf16 v[116:119], v[150:153], v[204:207], v[116:119]
	v_mfma_f32_16x16x32_bf16 v[112:115], v[142:145], v[212:215], v[112:115]
	v_mfma_f32_16x16x32_bf16 v[108:111], v[150:153], v[212:215], v[108:111]
	v_mfma_f32_16x16x32_bf16 v[136:139], v[146:149], v[192:195], v[136:139]
	v_mfma_f32_16x16x32_bf16 v[132:135], v[154:157], v[192:195], v[132:135]
	v_mfma_f32_16x16x32_bf16 v[128:131], v[146:149], v[200:203], v[128:131]
	v_mfma_f32_16x16x32_bf16 v[124:127], v[154:157], v[200:203], v[124:127]
	v_mfma_f32_16x16x32_bf16 v[120:123], v[146:149], v[208:211], v[120:123]
	v_mfma_f32_16x16x32_bf16 v[116:119], v[154:157], v[208:211], v[116:119]
	v_mfma_f32_16x16x32_bf16 v[112:115], v[146:149], v[216:219], v[112:115]
	v_mfma_f32_16x16x32_bf16 v[108:111], v[154:157], v[216:219], v[108:111]
	s_setprio 0
	s_setprio 1
	v_mfma_f32_16x16x32_bf16 v[72:75], v[158:161], v[188:191], v[72:75]
	v_mfma_f32_16x16x32_bf16 v[68:71], v[166:169], v[188:191], v[68:71]
	v_mfma_f32_16x16x32_bf16 v[64:67], v[158:161], v[196:199], v[64:67]
	v_mfma_f32_16x16x32_bf16 v[60:63], v[166:169], v[196:199], v[60:63]
	v_mfma_f32_16x16x32_bf16 v[56:59], v[158:161], v[204:207], v[56:59]
	v_mfma_f32_16x16x32_bf16 v[52:55], v[166:169], v[204:207], v[52:55]
	v_mfma_f32_16x16x32_bf16 v[48:51], v[158:161], v[212:215], v[48:51]
	v_mfma_f32_16x16x32_bf16 v[44:47], v[166:169], v[212:215], v[44:47]
	v_mfma_f32_16x16x32_bf16 v[72:75], v[162:165], v[192:195], v[72:75]
	v_mfma_f32_16x16x32_bf16 v[68:71], v[184:187], v[192:195], v[68:71]
	v_mfma_f32_16x16x32_bf16 v[64:67], v[162:165], v[200:203], v[64:67]
	v_mfma_f32_16x16x32_bf16 v[60:63], v[184:187], v[200:203], v[60:63]
	s_add_i32 s40, s69, s25
	s_mov_b32 m0, s40
	v_mfma_f32_16x16x32_bf16 v[56:59], v[162:165], v[208:211], v[56:59]
	v_mfma_f32_16x16x32_bf16 v[52:55], v[184:187], v[208:211], v[52:55]
	v_mfma_f32_16x16x32_bf16 v[48:51], v[162:165], v[216:219], v[48:51]
	v_mfma_f32_16x16x32_bf16 v[44:47], v[184:187], v[216:219], v[44:47]
	s_setprio 0
	s_barrier
; #define PG8_STAGE(bufoff, gbase, voff) do { const char* gb_ = (const char*)(gbase); asm volatile("" : "+s"(gb_));     \
;         _Pragma("unroll") for (int _i = 0; _i < 2; ++_i) \
;         __builtin_amdgcn_global_load_lds((const unsigned*)(gb_ + (voff)[_i]), (PG8_LAS unsigned*)(lds + (bufoff) + ldsw + _i * 8192), 16, 0, 0); } while (0)
; #define PG8_LDA(dst, b, h) do { _Pragma("unroll") for (int m = 0; m < 4; ++m) _Pragma("unroll") for (int k = 0; k < 2; ++k) dst[m][k] = *(const PG8_LAS bf16x8*)(lds + PG8_SA(b, h) + aoff + m * 2048 + k * 1024); } while (0)
; #define PG8_MMA(ai, bj, At, Bt) do { __builtin_amdgcn_s_setprio(1); _Pragma("unroll") for (int m = 0; m < 4; ++m) _Pragma("unroll") for (int n = 0; n < 2; ++n) _Pragma("unroll") for (int k = 0; k < 2; ++k) \
;         acc[ai][bj][m][n] = __builtin_amdgcn_mfma_f32_16x16x32_bf16(Bt[n][k], At[m][k], acc[ai][bj][m][n], 0, 0, 0); __builtin_amdgcn_s_setprio(0); } while (0)
; #define PG8_WAIT_V(n) asm volatile("s_waitcnt vmcnt(" #n ")" ::: "memory")
; #define PG8_WAIT_L(n) asm volatile("s_waitcnt lgkmcnt(" #n ")" ::: "memory")
; #define PG8_BAR __builtin_amdgcn_s_barrier()
; #define PG8_SCHED __builtin_amdgcn_sched_barrier(0)
; template <class Epi, class Sched, bool ALIGN_EPI = false, bool SP2 = false>
; __device__ __forceinline__ void gemm_phase(PG8_LAS unsigned char* lds, const Gemm g, const Sched& S, const Epi& E, int wid0) {
;     ...
;             PG8_LDA(At, 1, 1); PG8_STAGE(PG8_SB(1, 0), b3, vB_); PG8_STAGE(PG8_SB(1, 1), b3 + hstep, vB_); PG8_STAGE(PG8_SA(1, 0), a3, vA_);
;             PG8_WAIT_V(8); PG8_WAIT_L(0); PG8_BAR; PG8_MMA(1, 0, At, B0); PG8_MMA(1, 1, At, B1); PG8_BAR; PG8_SCHED;
	ds_read_b128 v[188:191], v183 offset:49152
	ds_read_b128 v[192:195], v183 offset:50176
	ds_read_b128 v[196:199], v183 offset:51200
	ds_read_b128 v[200:203], v183 offset:52224
	ds_read_b128 v[204:207], v183 offset:53248
	ds_read_b128 v[208:211], v183 offset:54272
	ds_read_b128 v[212:215], v183 offset:55296
	ds_read_b128 v[216:219], v183 offset:56320
	s_nop 0
	global_load_lds_dwordx4 v170, s[46:47]
	s_add_i32 m0, s40, 0x2000
	s_add_u32 s40, s42, 0x40080
	s_addc_u32 s41, s43, 0
	s_add_i32 s42, s70, s25
	global_load_lds_dwordx4 v182, s[46:47]
	s_mov_b32 m0, s42
	s_nop 0
	global_load_lds_dwordx4 v170, s[40:41]
	s_add_i32 m0, s42, 0x2000
	s_nop 0
	global_load_lds_dwordx4 v182, s[40:41]
	s_mov_b32 m0, s57
	s_nop 0
	global_load_lds_dwordx4 v9, s[44:45]
	s_mov_b32 m0, s58
	s_nop 0
	global_load_lds_dwordx4 v171, s[44:45]
	s_waitcnt vmcnt(8)
	s_waitcnt lgkmcnt(0)
	s_barrier
	s_setprio 1
	s_waitcnt lgkmcnt(0)
	v_mfma_f32_16x16x32_bf16 v[104:107], v[142:145], v[188:191], v[104:107]
	v_mfma_f32_16x16x32_bf16 v[100:103], v[150:153], v[188:191], v[100:103]
	v_mfma_f32_16x16x32_bf16 v[96:99], v[142:145], v[196:199], v[96:99]
	v_mfma_f32_16x16x32_bf16 v[92:95], v[150:153], v[196:199], v[92:95]
	v_mfma_f32_16x16x32_bf16 v[88:91], v[142:145], v[204:207], v[88:91]
	v_mfma_f32_16x16x32_bf16 v[84:87], v[150:153], v[204:207], v[84:87]
	v_mfma_f32_16x16x32_bf16 v[80:83], v[142:145], v[212:215], v[80:83]
	v_mfma_f32_16x16x32_bf16 v[76:79], v[150:153], v[212:215], v[76:79]
	v_mfma_f32_16x16x32_bf16 v[104:107], v[146:149], v[192:195], v[104:107]
	v_mfma_f32_16x16x32_bf16 v[100:103], v[154:157], v[192:195], v[100:103]
	v_mfma_f32_16x16x32_bf16 v[96:99], v[146:149], v[200:203], v[96:99]
	v_mfma_f32_16x16x32_bf16 v[92:95], v[154:157], v[200:203], v[92:95]
	v_mfma_f32_16x16x32_bf16 v[88:91], v[146:149], v[208:211], v[88:91]
	v_mfma_f32_16x16x32_bf16 v[84:87], v[154:157], v[208:211], v[84:87]
	v_mfma_f32_16x16x32_bf16 v[80:83], v[146:149], v[216:219], v[80:83]
	v_mfma_f32_16x16x32_bf16 v[76:79], v[154:157], v[216:219], v[76:79]
	s_setprio 0
	s_setprio 1
	v_mfma_f32_16x16x32_bf16 v[40:43], v[158:161], v[188:191], v[40:43]
	v_mfma_f32_16x16x32_bf16 v[36:39], v[166:169], v[188:191], v[36:39]
	v_mfma_f32_16x16x32_bf16 v[32:35], v[158:161], v[196:199], v[32:35]
	v_mfma_f32_16x16x32_bf16 v[28:31], v[166:169], v[196:199], v[28:31]
	v_mfma_f32_16x16x32_bf16 v[24:27], v[158:161], v[204:207], v[24:27]
	v_mfma_f32_16x16x32_bf16 v[20:23], v[166:169], v[204:207], v[20:23]
	v_mfma_f32_16x16x32_bf16 v[14:17], v[158:161], v[212:215], v[16:19]
	v_mfma_f32_16x16x32_bf16 v[10:13], v[166:169], v[212:215], v[10:13]
	v_mfma_f32_16x16x32_bf16 v[40:43], v[162:165], v[192:195], v[40:43]
	v_mfma_f32_16x16x32_bf16 v[36:39], v[184:187], v[192:195], v[36:39]
	v_mfma_f32_16x16x32_bf16 v[32:35], v[162:165], v[200:203], v[32:35]
	v_mfma_f32_16x16x32_bf16 v[28:31], v[184:187], v[200:203], v[28:31]
	s_add_i32 s68, s68, 2
	s_add_u32 s66, s66, 0x100
	s_addc_u32 s67, s67, 0
	s_cmp_gt_u32 s68, 13
	v_mfma_f32_16x16x32_bf16 v[24:27], v[162:165], v[208:211], v[24:27]
	v_mfma_f32_16x16x32_bf16 v[20:23], v[184:187], v[208:211], v[20:23]
	v_mfma_f32_16x16x32_bf16 v[16:19], v[162:165], v[216:219], v[14:17]
	v_mfma_f32_16x16x32_bf16 v[12:15], v[184:187], v[216:219], v[10:13]
	s_setprio 0
	s_barrier
	s_cbranch_scc1 .LBB13_1922
	s_mov_b64 s[40:41], s[6:7]
	s_cmp_lg_u32 s68, 6
	s_cbranch_scc0 .LBB13_1919
	s_branch .LBB13_1920

;     __device__ float mid(int row) const { return rg(row) / ra(row); }
;     __device__ __forceinline__ bool next(int i, Unit& u) const { return map(rank + i * nloc, u); }
;     __device__ __forceinline__ bool next(int i, Unit& u) const { if (i >= __builtin_amdgcn_readfirstlane(tab[0])) return false; u.pm = __builtin_amdgcn_readfirstlane(tab[1 + 2 * i]); u.pn = __builtin_amdgcn_readfirstlane(tab[2 + 2 * i]); return true; }
; #define PG8_LDA(dst, b, h) do { _Pragma("unroll") for (int m = 0; m < 4; ++m) _Pragma("unroll") for (int k = 0; k < 2; ++k) dst[m][k] = *(const PG8_LAS bf16x8*)(lds + PG8_SA(b, h) + aoff + m * 2048 + k * 1024); } while (0)
; #define PG8_WAIT_V(n) asm volatile("s_waitcnt vmcnt(" #n ")" ::: "memory")
; template <class Epi, class Sched, bool ALIGN_EPI = false, bool SP2 = false>
; __device__ __forceinline__ void gemm_phase(PG8_LAS unsigned char* lds, const Gemm g, const Sched& S, const Epi& E, int wid0) {
;     ...
;         const bool has_next = S.next(ui + 1, nxt); nxt.ui = ui + 1;
;         if constexpr (Epi::HAS_PRE) E.pre_finish(lds, cur, tid, pq0, pq1, pq2);
;         const char* nA = has_next ? (const char*)g.A + (size_t)nxt.pm * tstepA : cA; const char* nB = has_next ? (const char*)g.Bt + (size_t)nxt.pn * tstep : cB;
; #pragma nounroll
;         for (int t = 0; t < nt; t += 2) {
;             const bool last = (t == nt - 2);
;             const char* a1 = cA + (size_t)(t + 1) * kstep;
;             const char* a2 = last ? nA : cA + (size_t)(t + 2) * kstep; const char* b2 = last ? nB : cB + (size_t)(t + 2) * kstep;
;             const char* a3 = a2 + kstep; const char* b3 = b2 + kstep;
;             if (last && has_next) S.a_ready(nxt);
;             if constexpr (Epi::HAS_MID) { if (t == Epi::MID_T) E.mid(acc, cur, wr, fr); }
;             unsigned vA_[2] = {voffA[0], voffA[1]}, vB_[2] = {voffB[0], voffB[1]};
;             asm volatile("" : "+v"(vA_[0]), "+v"(vA_[1]), "+v"(vB_[0]), "+v"(vB_[1]));
;             if constexpr (SP2) {
;             PG8_LDB(B0, 0, 0); PG8_LDB(B1, 0, 1); PG8_SCHED; PG8_LDA(At, 0, 0); PG8_STAGE(PG8_SA(1, 1), a1 + hstepA, vA_);
;             PG8_WAIT_V(8); PG8_WAIT_L(0); PG8_BAR; PG8_MMA(0, 0, At, B0); PG8_MMA(0, 1, At, B1); PG8_BAR; PG8_SCHED;
;             PG8_LDA(At, 0, 1); PG8_STAGE(PG8_SB(0, 0), b2, vB_); PG8_STAGE(PG8_SB(0, 1), b2 + hstep, vB_); PG8_STAGE(PG8_SA(0, 0), a2, vA_);
.LBB13_2163:
	v_mov_b32_e32 v202, v150
	v_mov_b32_e32 v203, v152
	v_mov_b32_e32 v204, v154
	v_mov_b32_e32 v205, v148
	ds_read_b128 v[128:131], v153
	ds_read_b128 v[132:135], v153 offset:1024
	ds_read_b128 v[136:139], v153 offset:2048
	ds_read_b128 v[140:143], v153 offset:3072
	ds_read_b128 v[144:147], v155
	ds_read_b128 v[158:161], v155 offset:1024
	ds_read_b128 v[162:165], v155 offset:2048
	ds_read_b128 v[166:169], v155 offset:3072
	s_add_u32 s26, s24, 0x100
	s_addc_u32 s27, s25, 0
	s_cmp_eq_u32 s53, 60
	s_cselect_b32 s34, s49, s26
	s_cselect_b32 s35, s11, s27
	s_cselect_b32 s30, s50, s51
	s_cselect_b32 s31, s13, s52
	s_add_u32 s28, s34, 0x80
	s_addc_u32 s29, s35, 0
	s_add_u32 s24, s24, 0x100080
	s_addc_u32 s25, s25, 0
	s_add_i32 m0, s21, 0xc000
	ds_read_b128 v[170:173], v156
	ds_read_b128 v[174:177], v156 offset:1024
	ds_read_b128 v[178:181], v156 offset:2048
	ds_read_b128 v[182:185], v156 offset:3072
	ds_read_b128 v[186:189], v156 offset:4096
	ds_read_b128 v[190:193], v156 offset:5120
	ds_read_b128 v[194:197], v156 offset:6144
	ds_read_b128 v[198:201], v156 offset:7168
	s_nop 0
	global_load_lds_dwordx4 v205, s[24:25]
	s_add_i32 m0, s21, 0xe000
	s_nop 0
	global_load_lds_dwordx4 v203, s[24:25]
	s_waitcnt vmcnt(8)
	s_waitcnt lgkmcnt(0)
	s_barrier
	s_setprio 1
	s_waitcnt lgkmcnt(0)
	v_mfma_f32_16x16x32_bf16 v[124:127], v[128:131], v[170:173], v[124:127]
	v_mfma_f32_16x16x32_bf16 v[120:123], v[136:139], v[170:173], v[120:123]
	v_mfma_f32_16x16x32_bf16 v[116:119], v[128:131], v[178:181], v[116:119]
	v_mfma_f32_16x16x32_bf16 v[112:115], v[136:139], v[178:181], v[112:115]
	v_mfma_f32_16x16x32_bf16 v[108:111], v[128:131], v[186:189], v[108:111]
	v_mfma_f32_16x16x32_bf16 v[104:107], v[136:139], v[186:189], v[104:107]
	v_mfma_f32_16x16x32_bf16 v[100:103], v[128:131], v[194:197], v[100:103]
	v_mfma_f32_16x16x32_bf16 v[96:99], v[136:139], v[194:197], v[96:99]
	v_mfma_f32_16x16x32_bf16 v[124:127], v[132:135], v[174:177], v[124:127]
	v_mfma_f32_16x16x32_bf16 v[120:123], v[140:143], v[174:177], v[120:123]
	v_mfma_f32_16x16x32_bf16 v[116:119], v[132:135], v[182:185], v[116:119]
	v_mfma_f32_16x16x32_bf16 v[112:115], v[140:143], v[182:185], v[112:115]
	v_mfma_f32_16x16x32_bf16 v[108:111], v[132:135], v[190:193], v[108:111]
	v_mfma_f32_16x16x32_bf16 v[104:107], v[140:143], v[190:193], v[104:107]
	v_mfma_f32_16x16x32_bf16 v[100:103], v[132:135], v[198:201], v[100:103]
	v_mfma_f32_16x16x32_bf16 v[96:99], v[140:143], v[198:201], v[96:99]
	s_setprio 0
	s_setprio 1
	v_mfma_f32_16x16x32_bf16 v[60:63], v[144:147], v[170:173], v[60:63]
	v_mfma_f32_16x16x32_bf16 v[56:59], v[162:165], v[170:173], v[56:59]
	v_mfma_f32_16x16x32_bf16 v[52:55], v[144:147], v[178:181], v[52:55]
	v_mfma_f32_16x16x32_bf16 v[48:51], v[162:165], v[178:181], v[48:51]
	v_mfma_f32_16x16x32_bf16 v[44:47], v[144:147], v[186:189], v[44:47]
	v_mfma_f32_16x16x32_bf16 v[40:43], v[162:165], v[186:189], v[40:43]
	v_mfma_f32_16x16x32_bf16 v[36:39], v[144:147], v[194:197], v[36:39]
	v_mfma_f32_16x16x32_bf16 v[32:35], v[162:165], v[194:197], v[32:35]
	v_mfma_f32_16x16x32_bf16 v[60:63], v[158:161], v[174:177], v[60:63]
	v_mfma_f32_16x16x32_bf16 v[56:59], v[166:169], v[174:177], v[56:59]
	v_mfma_f32_16x16x32_bf16 v[52:55], v[158:161], v[182:185], v[52:55]
	v_mfma_f32_16x16x32_bf16 v[48:51], v[166:169], v[182:185], v[48:51]
	s_add_i32 s54, s47, s33
	s_mov_b64 s[24:25], s[30:31]
	s_mov_b32 m0, s54
	v_mfma_f32_16x16x32_bf16 v[44:47], v[158:161], v[190:193], v[44:47]
	v_mfma_f32_16x16x32_bf16 v[40:43], v[166:169], v[190:193], v[40:43]
	v_mfma_f32_16x16x32_bf16 v[36:39], v[158:161], v[198:201], v[36:39]
	v_mfma_f32_16x16x32_bf16 v[32:35], v[166:169], v[198:201], v[32:35]
	s_setprio 0
	s_barrier
	ds_read_b128 v[170:173], v156 offset:16384
	ds_read_b128 v[174:177], v156 offset:17408
	ds_read_b128 v[178:181], v156 offset:18432
	ds_read_b128 v[182:185], v156 offset:19456
	ds_read_b128 v[186:189], v156 offset:20480
	ds_read_b128 v[190:193], v156 offset:21504
	ds_read_b128 v[194:197], v156 offset:22528
	ds_read_b128 v[198:201], v156 offset:23552
	s_nop 0
	global_load_lds_dwordx4 v202, s[24:25]
	s_add_i32 m0, s54, 0x2000
	s_nop 0
	global_load_lds_dwordx4 v204, s[24:25]
	s_add_u32 s24, s30, 0x100000
	s_addc_u32 s25, s31, 0
	s_add_i32 s54, s48, s33
	s_mov_b32 m0, s54
	s_nop 0
	global_load_lds_dwordx4 v202, s[24:25]
	s_add_i32 m0, s54, 0x2000
	s_nop 0
	global_load_lds_dwordx4 v204, s[24:25]
	s_mov_b64 s[24:25], s[34:35]
	s_mov_b32 m0, s21
	s_nop 0
	global_load_lds_dwordx4 v205, s[24:25]
	s_mov_b32 m0, s23
	s_nop 0
	global_load_lds_dwordx4 v203, s[24:25]
	s_waitcnt vmcnt(8)
	s_waitcnt lgkmcnt(0)
	s_barrier
; #define PG8_STAGE(bufoff, gbase, voff) do { const char* gb_ = (const char*)(gbase); asm volatile("" : "+s"(gb_));     \
;         _Pragma("unroll") for (int _i = 0; _i < 2; ++_i) \
;         __builtin_amdgcn_global_load_lds((const unsigned*)(gb_ + (voff)[_i]), (PG8_LAS unsigned*)(lds + (bufoff) + ldsw + _i * 8192), 16, 0, 0); } while (0)
; #define PG8_LDA(dst, b, h) do { _Pragma("unroll") for (int m = 0; m < 4; ++m) _Pragma("unroll") for (int k = 0; k < 2; ++k) dst[m][k] = *(const PG8_LAS bf16x8*)(lds + PG8_SA(b, h) + aoff + m * 2048 + k * 1024); } while (0)
; #define PG8_LDB(dst, b, h) do { _Pragma("unroll") for (int n = 0; n < 2; ++n) _Pragma("unroll") for (int k = 0; k < 2; ++k) dst[n][k] = *(const PG8_LAS bf16x8*)(lds + PG8_SB(b, h) + boff + n * 2048 + k * 1024); } while (0)
; #define PG8_MMA(ai, bj, At, Bt) do { __builtin_amdgcn_s_setprio(1); _Pragma("unroll") for (int m = 0; m < 4; ++m) _Pragma("unroll") for (int n = 0; n < 2; ++n) _Pragma("unroll") for (int k = 0; k < 2; ++k) \
;         acc[ai][bj][m][n] = __builtin_amdgcn_mfma_f32_16x16x32_bf16(Bt[n][k], At[m][k], acc[ai][bj][m][n], 0, 0, 0); __builtin_amdgcn_s_setprio(0); } while (0)
; #define PG8_WAIT_V(n) asm volatile("s_waitcnt vmcnt(" #n ")" ::: "memory")
; #define PG8_WAIT_L(n) asm volatile("s_waitcnt lgkmcnt(" #n ")" ::: "memory")
; #define PG8_BAR __builtin_amdgcn_s_barrier()
; #define PG8_SCHED __builtin_amdgcn_sched_barrier(0)
; template <class Epi, class Sched, bool ALIGN_EPI = false, bool SP2 = false>
; __device__ __forceinline__ void gemm_phase(PG8_LAS unsigned char* lds, const Gemm g, const Sched& S, const Epi& E, int wid0) {
;     ...
;             PG8_WAIT_V(8); PG8_WAIT_L(0); PG8_BAR; PG8_MMA(0, 0, At, B0); PG8_MMA(0, 1, At, B1); PG8_BAR; PG8_SCHED;
;             PG8_LDA(At, 0, 1); PG8_STAGE(PG8_SB(0, 0), b2, vB_); PG8_STAGE(PG8_SB(0, 1), b2 + hstep, vB_); PG8_STAGE(PG8_SA(0, 0), a2, vA_);
;             PG8_WAIT_V(8); PG8_WAIT_L(0); PG8_BAR; PG8_MMA(1, 0, At, B0); PG8_MMA(1, 1, At, B1); PG8_BAR; PG8_SCHED;
;             PG8_LDB(B0, 1, 0); PG8_LDB(B1, 1, 1); PG8_SCHED; PG8_LDA(At, 1, 0); PG8_STAGE(PG8_SA(0, 1), a2 + hstepA, vA_);
;             PG8_WAIT_V(8); PG8_WAIT_L(0); PG8_BAR; PG8_MMA(0, 0, At, B0); PG8_MMA(0, 1, At, B1); PG8_BAR; PG8_SCHED;
	s_setprio 1
	s_waitcnt lgkmcnt(0)
	v_mfma_f32_16x16x32_bf16 v[92:95], v[128:131], v[170:173], v[92:95]
	v_mfma_f32_16x16x32_bf16 v[88:91], v[136:139], v[170:173], v[88:91]
	v_mfma_f32_16x16x32_bf16 v[84:87], v[128:131], v[178:181], v[84:87]
	v_mfma_f32_16x16x32_bf16 v[80:83], v[136:139], v[178:181], v[80:83]
	v_mfma_f32_16x16x32_bf16 v[76:79], v[128:131], v[186:189], v[76:79]
	v_mfma_f32_16x16x32_bf16 v[72:75], v[136:139], v[186:189], v[72:75]
	v_mfma_f32_16x16x32_bf16 v[68:71], v[128:131], v[194:197], v[68:71]
	v_mfma_f32_16x16x32_bf16 v[64:67], v[136:139], v[194:197], v[64:67]
	v_mfma_f32_16x16x32_bf16 v[92:95], v[132:135], v[174:177], v[92:95]
	v_mfma_f32_16x16x32_bf16 v[88:91], v[140:143], v[174:177], v[88:91]
	v_mfma_f32_16x16x32_bf16 v[84:87], v[132:135], v[182:185], v[84:87]
	v_mfma_f32_16x16x32_bf16 v[80:83], v[140:143], v[182:185], v[80:83]
	v_mfma_f32_16x16x32_bf16 v[76:79], v[132:135], v[190:193], v[76:79]
	v_mfma_f32_16x16x32_bf16 v[72:75], v[140:143], v[190:193], v[72:75]
	v_mfma_f32_16x16x32_bf16 v[68:71], v[132:135], v[198:201], v[68:71]
	v_mfma_f32_16x16x32_bf16 v[64:67], v[140:143], v[198:201], v[64:67]
	s_setprio 0
	s_setprio 1
	v_mfma_f32_16x16x32_bf16 v[28:31], v[144:147], v[170:173], v[28:31]
	v_mfma_f32_16x16x32_bf16 v[24:27], v[162:165], v[170:173], v[24:27]
	v_mfma_f32_16x16x32_bf16 v[20:23], v[144:147], v[178:181], v[20:23]
	v_mfma_f32_16x16x32_bf16 v[16:19], v[162:165], v[178:181], v[16:19]
	v_mfma_f32_16x16x32_bf16 v[12:15], v[144:147], v[186:189], v[12:15]
	v_mfma_f32_16x16x32_bf16 v[8:11], v[162:165], v[186:189], v[8:11]
	v_mfma_f32_16x16x32_bf16 v[4:7], v[144:147], v[194:197], v[4:7]
	v_mfma_f32_16x16x32_bf16 v[0:3], v[162:165], v[194:197], v[0:3]
	v_mfma_f32_16x16x32_bf16 v[28:31], v[158:161], v[174:177], v[28:31]
	v_mfma_f32_16x16x32_bf16 v[24:27], v[166:169], v[174:177], v[24:27]
	v_mfma_f32_16x16x32_bf16 v[20:23], v[158:161], v[182:185], v[20:23]
	v_mfma_f32_16x16x32_bf16 v[16:19], v[166:169], v[182:185], v[16:19]
	s_add_i32 s54, 0, 0x18000
	s_add_i32 s55, 0, 0x1c000
	v_mfma_f32_16x16x32_bf16 v[12:15], v[158:161], v[190:193], v[12:15]
	v_mfma_f32_16x16x32_bf16 v[8:11], v[166:169], v[190:193], v[8:11]
	v_mfma_f32_16x16x32_bf16 v[4:7], v[158:161], v[198:201], v[4:7]
	v_mfma_f32_16x16x32_bf16 v[0:3], v[166:169], v[198:201], v[0:3]
	s_setprio 0
	s_barrier
	v_add_u32_e32 v140, s54, v149
	v_add_u32_e32 v166, s55, v149
	ds_read_b128 v[128:131], v140
	ds_read_b128 v[132:135], v140 offset:1024
	ds_read_b128 v[136:139], v140 offset:2048
	ds_read_b128 v[140:143], v140 offset:3072
	ds_read_b128 v[144:147], v166
	ds_read_b128 v[158:161], v166 offset:1024
	ds_read_b128 v[162:165], v166 offset:2048
	ds_read_b128 v[166:169], v166 offset:3072
	s_add_u32 s24, s34, 0x100000
	s_addc_u32 s25, s35, 0
	s_mov_b32 m0, s40
	ds_read_b128 v[170:173], v156 offset:32768
	ds_read_b128 v[174:177], v156 offset:33792
	ds_read_b128 v[178:181], v156 offset:34816
	ds_read_b128 v[182:185], v156 offset:35840
	ds_read_b128 v[186:189], v156 offset:36864
	ds_read_b128 v[190:193], v156 offset:37888
	ds_read_b128 v[194:197], v156 offset:38912
	ds_read_b128 v[198:201], v156 offset:39936
	s_nop 0
	global_load_lds_dwordx4 v205, s[24:25]
	s_mov_b32 m0, s41
	s_nop 0
	global_load_lds_dwordx4 v203, s[24:25]
	s_waitcnt vmcnt(8)
	s_waitcnt lgkmcnt(0)
	s_barrier
	s_setprio 1
	s_waitcnt lgkmcnt(0)
	v_mfma_f32_16x16x32_bf16 v[124:127], v[128:131], v[170:173], v[124:127]
	v_mfma_f32_16x16x32_bf16 v[120:123], v[136:139], v[170:173], v[120:123]
	v_mfma_f32_16x16x32_bf16 v[116:119], v[128:131], v[178:181], v[116:119]
	v_mfma_f32_16x16x32_bf16 v[112:115], v[136:139], v[178:181], v[112:115]
	v_mfma_f32_16x16x32_bf16 v[108:111], v[128:131], v[186:189], v[108:111]
	v_mfma_f32_16x16x32_bf16 v[104:107], v[136:139], v[186:189], v[104:107]
	v_mfma_f32_16x16x32_bf16 v[100:103], v[128:131], v[194:197], v[100:103]
	v_mfma_f32_16x16x32_bf16 v[96:99], v[136:139], v[194:197], v[96:99]
	v_mfma_f32_16x16x32_bf16 v[124:127], v[132:135], v[174:177], v[124:127]
	v_mfma_f32_16x16x32_bf16 v[120:123], v[140:143], v[174:177], v[120:123]
	v_mfma_f32_16x16x32_bf16 v[116:119], v[132:135], v[182:185], v[116:119]
	v_mfma_f32_16x16x32_bf16 v[112:115], v[140:143], v[182:185], v[112:115]
	v_mfma_f32_16x16x32_bf16 v[108:111], v[132:135], v[190:193], v[108:111]
	v_mfma_f32_16x16x32_bf16 v[104:107], v[140:143], v[190:193], v[104:107]
	v_mfma_f32_16x16x32_bf16 v[100:103], v[132:135], v[198:201], v[100:103]
	v_mfma_f32_16x16x32_bf16 v[96:99], v[140:143], v[198:201], v[96:99]
	s_setprio 0
	s_setprio 1
	v_mfma_f32_16x16x32_bf16 v[60:63], v[144:147], v[170:173], v[60:63]
	v_mfma_f32_16x16x32_bf16 v[56:59], v[162:165], v[170:173], v[56:59]
	v_mfma_f32_16x16x32_bf16 v[52:55], v[144:147], v[178:181], v[52:55]
	v_mfma_f32_16x16x32_bf16 v[48:51], v[162:165], v[178:181], v[48:51]
	v_mfma_f32_16x16x32_bf16 v[44:47], v[144:147], v[186:189], v[44:47]
	v_mfma_f32_16x16x32_bf16 v[40:43], v[162:165], v[186:189], v[40:43]
	v_mfma_f32_16x16x32_bf16 v[36:39], v[144:147], v[194:197], v[36:39]
	v_mfma_f32_16x16x32_bf16 v[32:35], v[162:165], v[194:197], v[32:35]
	v_mfma_f32_16x16x32_bf16 v[60:63], v[158:161], v[174:177], v[60:63]
	v_mfma_f32_16x16x32_bf16 v[56:59], v[166:169], v[174:177], v[56:59]
	v_mfma_f32_16x16x32_bf16 v[52:55], v[158:161], v[182:185], v[52:55]
	v_mfma_f32_16x16x32_bf16 v[48:51], v[166:169], v[182:185], v[48:51]
	s_add_u32 s24, s30, 0x80
	s_addc_u32 s25, s31, 0
	s_add_i32 s34, s54, s33
	s_mov_b32 m0, s34
	v_mfma_f32_16x16x32_bf16 v[44:47], v[158:161], v[190:193], v[44:47]
	v_mfma_f32_16x16x32_bf16 v[40:43], v[166:169], v[190:193], v[40:43]
	v_mfma_f32_16x16x32_bf16 v[36:39], v[158:161], v[198:201], v[36:39]
	v_mfma_f32_16x16x32_bf16 v[32:35], v[166:169], v[198:201], v[32:35]
	s_setprio 0
	s_barrier
; #define PG8_STAGE(bufoff, gbase, voff) do { const char* gb_ = (const char*)(gbase); asm volatile("" : "+s"(gb_));     \
;         _Pragma("unroll") for (int _i = 0; _i < 2; ++_i) \
;         __builtin_amdgcn_global_load_lds((const unsigned*)(gb_ + (voff)[_i]), (PG8_LAS unsigned*)(lds + (bufoff) + ldsw + _i * 8192), 16, 0, 0); } while (0)
; #define PG8_LDA(dst, b, h) do { _Pragma("unroll") for (int m = 0; m < 4; ++m) _Pragma("unroll") for (int k = 0; k < 2; ++k) dst[m][k] = *(const PG8_LAS bf16x8*)(lds + PG8_SA(b, h) + aoff + m * 2048 + k * 1024); } while (0)
; #define PG8_MMA(ai, bj, At, Bt) do { __builtin_amdgcn_s_setprio(1); _Pragma("unroll") for (int m = 0; m < 4; ++m) _Pragma("unroll") for (int n = 0; n < 2; ++n) _Pragma("unroll") for (int k = 0; k < 2; ++k) \
;         acc[ai][bj][m][n] = __builtin_amdgcn_mfma_f32_16x16x32_bf16(Bt[n][k], At[m][k], acc[ai][bj][m][n], 0, 0, 0); __builtin_amdgcn_s_setprio(0); } while (0)
; #define PG8_WAIT_V(n) asm volatile("s_waitcnt vmcnt(" #n ")" ::: "memory")
; #define PG8_WAIT_L(n) asm volatile("s_waitcnt lgkmcnt(" #n ")" ::: "memory")
; #define PG8_BAR __builtin_amdgcn_s_barrier()
; #define PG8_SCHED __builtin_amdgcn_sched_barrier(0)
; template <class Epi, class Sched, bool ALIGN_EPI = false, bool SP2 = false>
; __device__ __forceinline__ void gemm_phase(PG8_LAS unsigned char* lds, const Gemm g, const Sched& S, const Epi& E, int wid0) {
;     ...
;             PG8_LDA(At, 1, 1); PG8_STAGE(PG8_SB(1, 0), b3, vB_); PG8_STAGE(PG8_SB(1, 1), b3 + hstep, vB_); PG8_STAGE(PG8_SA(1, 0), a3, vA_);
;             PG8_WAIT_V(8); PG8_WAIT_L(0); PG8_BAR; PG8_MMA(1, 0, At, B0); PG8_MMA(1, 1, At, B1); PG8_BAR; PG8_SCHED;
	ds_read_b128 v[170:173], v156 offset:49152
	ds_read_b128 v[174:177], v156 offset:50176
	ds_read_b128 v[178:181], v156 offset:51200
	ds_read_b128 v[182:185], v156 offset:52224
	ds_read_b128 v[186:189], v156 offset:53248
	ds_read_b128 v[190:193], v156 offset:54272
	ds_read_b128 v[194:197], v156 offset:55296
	ds_read_b128 v[198:201], v156 offset:56320
	s_nop 0
	global_load_lds_dwordx4 v202, s[24:25]
	s_add_i32 m0, s34, 0x2000
	s_nop 0
	global_load_lds_dwordx4 v204, s[24:25]
	s_add_u32 s24, s30, 0x100080
	s_addc_u32 s25, s31, 0
	s_add_i32 s30, s55, s33
	s_mov_b32 m0, s30
	s_nop 0
	global_load_lds_dwordx4 v202, s[24:25]
	s_add_i32 m0, s30, 0x2000
	s_nop 0
	global_load_lds_dwordx4 v204, s[24:25]
	s_mov_b32 m0, s45
	s_nop 0
	global_load_lds_dwordx4 v205, s[28:29]
	s_mov_b32 m0, s46
	s_nop 0
	global_load_lds_dwordx4 v203, s[28:29]
	s_waitcnt vmcnt(8)
	s_waitcnt lgkmcnt(0)
	s_barrier
	s_setprio 1
	s_waitcnt lgkmcnt(0)
	v_mfma_f32_16x16x32_bf16 v[92:95], v[128:131], v[170:173], v[92:95]
	v_mfma_f32_16x16x32_bf16 v[88:91], v[136:139], v[170:173], v[88:91]
	v_mfma_f32_16x16x32_bf16 v[84:87], v[128:131], v[178:181], v[84:87]
	v_mfma_f32_16x16x32_bf16 v[80:83], v[136:139], v[178:181], v[80:83]
	v_mfma_f32_16x16x32_bf16 v[76:79], v[128:131], v[186:189], v[76:79]
	v_mfma_f32_16x16x32_bf16 v[72:75], v[136:139], v[186:189], v[72:75]
	v_mfma_f32_16x16x32_bf16 v[68:71], v[128:131], v[194:197], v[68:71]
	v_mfma_f32_16x16x32_bf16 v[64:67], v[136:139], v[194:197], v[64:67]
	v_mfma_f32_16x16x32_bf16 v[92:95], v[132:135], v[174:177], v[92:95]
	v_mfma_f32_16x16x32_bf16 v[88:91], v[140:143], v[174:177], v[88:91]
	v_mfma_f32_16x16x32_bf16 v[84:87], v[132:135], v[182:185], v[84:87]
	v_mfma_f32_16x16x32_bf16 v[80:83], v[140:143], v[182:185], v[80:83]
	v_mfma_f32_16x16x32_bf16 v[76:79], v[132:135], v[190:193], v[76:79]
	v_mfma_f32_16x16x32_bf16 v[72:75], v[140:143], v[190:193], v[72:75]
	v_mfma_f32_16x16x32_bf16 v[68:71], v[132:135], v[198:201], v[68:71]
	v_mfma_f32_16x16x32_bf16 v[64:67], v[140:143], v[198:201], v[64:67]
	s_setprio 0
	s_setprio 1
	v_mfma_f32_16x16x32_bf16 v[28:31], v[144:147], v[170:173], v[28:31]
	v_mfma_f32_16x16x32_bf16 v[24:27], v[162:165], v[170:173], v[24:27]
	v_mfma_f32_16x16x32_bf16 v[20:23], v[144:147], v[178:181], v[20:23]
	v_mfma_f32_16x16x32_bf16 v[16:19], v[162:165], v[178:181], v[16:19]
	v_mfma_f32_16x16x32_bf16 v[12:15], v[144:147], v[186:189], v[12:15]
	v_mfma_f32_16x16x32_bf16 v[8:11], v[162:165], v[186:189], v[8:11]
	v_mfma_f32_16x16x32_bf16 v[4:7], v[144:147], v[194:197], v[4:7]
	v_mfma_f32_16x16x32_bf16 v[0:3], v[162:165], v[194:197], v[0:3]
	v_mfma_f32_16x16x32_bf16 v[28:31], v[158:161], v[174:177], v[28:31]
	v_mfma_f32_16x16x32_bf16 v[24:27], v[166:169], v[174:177], v[24:27]
	v_mfma_f32_16x16x32_bf16 v[20:23], v[158:161], v[182:185], v[20:23]
	v_mfma_f32_16x16x32_bf16 v[16:19], v[166:169], v[182:185], v[16:19]
	s_add_i32 s53, s53, 2
	s_add_u32 s51, s51, 0x100
	s_addc_u32 s52, s52, 0
	s_cmp_gt_u32 s53, 61
	s_mov_b64 s[24:25], s[26:27]
	v_mfma_f32_16x16x32_bf16 v[12:15], v[158:161], v[190:193], v[12:15]
	v_mfma_f32_16x16x32_bf16 v[8:11], v[166:169], v[190:193], v[8:11]
	v_mfma_f32_16x16x32_bf16 v[4:7], v[158:161], v[198:201], v[4:7]
	v_mfma_f32_16x16x32_bf16 v[0:3], v[166:169], v[198:201], v[0:3]
	s_setprio 0
	s_barrier
	s_cbranch_scc0 .LBB13_2163
	s_and_b64 vcc, exec, s[8:9]
	s_cbranch_vccz .LBB13_2166
	s_barrier
